# mix loop waits relaxed, W2-4 transposes moved to G1 tail, G2+G3 epilogue residual/ss loads batched
# speedup vs baseline: 1.0028x; 1.0028x over previous
; #define LAS __attribute__((address_space(3)))
; __device__ __forceinline__ unsigned xb_add(unsigned* p, unsigned v) { return __hip_atomic_fetch_add(p, v, __ATOMIC_RELAXED, __HIP_MEMORY_SCOPE_AGENT); }
; __device__ __forceinline__ unsigned xb_xcc_id() { return (unsigned)__builtin_amdgcn_s_getreg((3 << 11) | 20) & 0xFu; }
; __device__ __forceinline__ XcdBarrier xcd_barrier_post(unsigned* bar, volatile LAS unsigned* st) {
;     XcdBarrier b; b.bar = bar; b.x = xb_xcc_id(); b.st = st;
;     if (threadIdx.x == 0) (void)xb_add(&bar[XB_XCNT(b.x)], 1u);
;     return b;
; __global__ void __launch_bounds__(512, 2) fwd_megakernel(Params p) {
;     extern __shared__ __attribute__((aligned(16))) unsigned char lds_raw[];
;     LAS unsigned char* lds = (LAS unsigned char*)lds_raw;
;     cg::grid_group grid = cg::this_grid();
;     const int G = gridDim.x;
;     bf16_t* RA = (bf16_t*)(p.ws + WS_RA); bf16_t* RB = (bf16_t*)(p.ws + WS_RB);
;     volatile LAS unsigned* xst = (volatile LAS unsigned*)(lds + 131072 + 2048);
;     if (threadIdx.x < 4) xst[threadIdx.x] = 0u;
;     __syncthreads();
;     const XcdBarrier xbar = xcd_barrier_post((unsigned*)(p.ws + WS_CTL) + 1024, xst);
_Z14fwd_megakernel6Params:
	s_mov_b32 s94, s2
	s_load_dwordx16 s[72:87], s[0:1], 0x40
	s_load_dword s2, s[0:1], 0x88
	v_and_b32_e32 v194, 0x3ff, v0
	v_cmp_gt_u32_e32 vcc, 4, v194
	s_waitcnt lgkmcnt(0)
	v_writelane_b32 v234, s2, 0
	s_mov_b32 s95, 0
	v_writelane_b32 v236, s78, 0
	s_nop 1
	v_writelane_b32 v236, s79, 1
	s_nop 1
	v_writelane_b32 v236, s80, 2
	s_nop 1
	v_writelane_b32 v236, s81, 3
	s_nop 1
	v_writelane_b32 v236, s82, 4
	s_nop 1
	v_writelane_b32 v236, s83, 5
	s_nop 1
	s_load_dwordx2 s[2:3], s[0:1], 0x80
	s_waitcnt lgkmcnt(0)
	v_writelane_b32 v234, s2, 1
	s_nop 1
	v_writelane_b32 v234, s3, 2
	s_add_u32 s2, s0, 0x80
	s_addc_u32 s3, s1, 0
	s_and_saveexec_b64 s[4:5], vcc
	v_lshl_add_u32 v1, v194, 2, 0
	v_add_u32_e32 v1, 0x20800, v1
	v_mov_b32_e32 v2, 0
	ds_write_b32 v1, v2
	s_or_b64 exec, exec, s[4:5]
	s_load_dwordx16 s[4:19], s[0:1], 0x0
	s_add_u32 s0, s86, 0x1000
	s_addc_u32 s1, s87, 0
	s_waitcnt lgkmcnt(0)
	s_barrier
	v_writelane_b32 v234, s4, 3
	s_nop 1
	v_writelane_b32 v234, s5, 4
	v_writelane_b32 v234, s6, 5
	v_writelane_b32 v234, s7, 6
	v_writelane_b32 v234, s8, 7
	v_writelane_b32 v234, s9, 8
	v_writelane_b32 v234, s10, 9
	v_writelane_b32 v234, s11, 10
	v_writelane_b32 v234, s12, 11
	v_writelane_b32 v234, s13, 12
	v_writelane_b32 v234, s14, 13
	v_writelane_b32 v234, s15, 14
	v_writelane_b32 v234, s16, 15
	v_writelane_b32 v234, s17, 16
	v_writelane_b32 v234, s18, 17
	v_writelane_b32 v234, s19, 18
	v_writelane_b32 v234, s0, 19
	v_cmp_eq_u32_e64 s[4:5], 0, v194
	s_nop 0
	v_writelane_b32 v234, s1, 20
	s_getreg_b32 s0, hwreg(HW_REG_XCC_ID, 0, 4)
	s_and_b32 s0, s0, 15
	v_writelane_b32 v234, s0, 21
	s_mov_b64 s[0:1], exec
	v_writelane_b32 v234, s4, 22
	s_nop 1
	v_writelane_b32 v234, s5, 23
	s_and_b64 s[4:5], s[0:1], s[4:5]
	s_mov_b64 exec, s[4:5]
	s_cbranch_execz .LBB0_5
	s_mov_b64 s[4:5], exec
	v_mbcnt_lo_u32_b32 v1, s4, 0
	v_mbcnt_hi_u32_b32 v1, s5, v1
	v_cmp_eq_u32_e32 vcc, 0, v1
	s_and_b64 s[6:7], exec, vcc
	s_mov_b64 exec, s[6:7]
	s_cbranch_execz .LBB0_5
	v_readlane_b32 s6, v234, 21
	s_bcnt1_i32_b64 s4, s[4:5]
	s_lshl_b32 s6, s6, 8
	v_mov_b32_e32 v2, s4
	v_readlane_b32 s4, v234, 19
	v_mov_b32_e32 v1, s6
	v_readlane_b32 s5, v234, 20
	s_nop 4
	global_atomic_add v1, v2, s[4:5] offset:1024

; #define LAS __attribute__((address_space(3)))
; __device__ __forceinline__ void p0_transpose_item(const float* W, int K, int N, bf16_t* WT, const float* gk, LAS float* scr, int item, int lane, bool w1map) {
;     const int nblk = N / 32, kb = item / nblk, nb = item % nblk, k0 = 64 * kb, n0 = 32 * nb;
;     int nd0 = n0;
;     if (w1map) { if (n0 < GW) nd0 = (n0 >> 7) * 256 + (n0 & 127); else if (n0 < 2 * GW) nd0 = 2 * GW + (n0 - GW); else { const int c = n0 - 2 * GW; nd0 = (c >> 7) * 256 + 128 + (c & 127); } }
;     float wv[32];
; #pragma unroll
;     for (int i = 0; i < 32; ++i) wv[i] = __builtin_nontemporal_load(W + (size_t)(k0 + 2 * i + (lane >> 5)) * N + n0 + (lane & 31));
; __device__ __forceinline__ void p0_prologue(const Params& p, LAS unsigned char* lds, int G) {
;     ...
;     for (int it = gw; it < I1 + I2 + I3 + I4; it += NGW) {
;         int r = it;
;         if (r < I1) { p0_transpose_item(p.w1, DM, N1, W1T, nullptr, scr, r, lane, true); continue; } r -= I1;
;         if (r < I2) { p0_transpose_item(p.w2, GW, DM, W2T, nullptr, scr, r, lane, false); continue; } r -= I2;
;         if (r < I3) { p0_transpose_item(p.w3, DM, N3, W3T, p.norm_g + DM, scr, r, lane, false); continue; } r -= I3;
;         p0_transpose_item(p.w4, DM, DM, W4T, nullptr, scr, r, lane, false);
;     }
.LBB0_10:
	s_or_b64 exec, exec, s[0:1]
	s_add_u32 s0, s86, 0x400000
	s_addc_u32 s1, s87, 0
	s_add_u32 s14, s86, 0x3400000
	s_addc_u32 s15, s87, 0
	s_add_u32 s22, s86, 0x4400000
	v_writelane_b32 v234, s0, 25
	s_addc_u32 s23, s87, 0
	s_nop 0
	v_writelane_b32 v234, s1, 26
	s_add_u32 s0, s86, 0x6400000
	s_addc_u32 s1, s87, 0
	v_writelane_b32 v234, s0, 27
	s_nop 1
	v_writelane_b32 v234, s1, 28
	s_movk_i32 s0, 0x3000
	v_cmp_gt_i32_e32 vcc, s0, v10
	s_and_saveexec_b64 s[0:1], vcc
	s_cbranch_execz .LBB0_33
.Ltr_entry:
	v_lshl_add_u32 v6, v1, 14, 0
	v_lshrrev_b32_e32 v1, 5, v36
	v_lshlrev_b32_e32 v2, 2, v37
	v_and_b32_e32 v20, 0x7c, v2
	v_mul_u32_u24_e32 v2, 0x84, v1
	v_add3_u32 v11, v6, v20, v2
	v_and_b32_e32 v2, 56, v12
	v_readlane_b32 s4, v234, 27
	v_mul_u32_u24_e32 v7, 0x84, v2
	v_lshlrev_b32_e32 v2, 1, v2
	v_mov_b32_e32 v3, 0
	v_readlane_b32 s5, v234, 28
	v_readlane_b32 s36, v234, 3
	v_lshrrev_b32_e32 v24, 3, v36
	v_lshl_add_u64 v[4:5], s[4:5], 0, v[2:3]
	v_readlane_b32 s4, v234, 25
	v_readlane_b32 s5, v234, 26
	v_readlane_b32 s44, v234, 11
	v_lshlrev_b32_e32 v8, 2, v24
	v_lshl_add_u64 v[12:13], s[4:5], 0, v[2:3]
	v_mov_b32_e32 v21, v3
	v_readlane_b32 s45, v234, 12
	v_readlane_b32 s48, v234, 15
	v_readlane_b32 s49, v234, 16
	s_add_u32 s4, s44, 0x2000
	v_add3_u32 v25, v6, v7, v8
	v_or_b32_e32 v26, 8, v24
	v_or_b32_e32 v27, 16, v24
	v_or_b32_e32 v28, 24, v24
	v_lshl_add_u64 v[6:7], s[22:23], 0, v[2:3]
	v_lshl_add_u64 v[8:9], s[14:15], 0, v[2:3]
	v_lshl_add_u64 v[14:15], s[82:83], 0, v[20:21]
	v_lshl_add_u64 v[16:17], s[80:81], 0, v[20:21]
	v_lshl_add_u64 v[18:19], s[78:79], 0, v[20:21]
	v_lshl_add_u64 v[20:21], s[48:49], 0, v[20:21]
	s_addc_u32 s5, s45, 0
	v_lshlrev_b32_e32 v29, 5, v10
	s_lshl_b32 s16, s96, 5
	v_lshlrev_b32_e32 v30, 6, v10
	s_lshl_b32 s17, s96, 6
	s_mov_b64 s[6:7], 0
	s_movk_i32 s18, 0x2fff
	s_movk_i32 s19, 0x3fff
	s_movk_i32 s24, 0x5fff
	s_mov_b32 s25, 0xc000
	s_mov_b32 s26, 0x2aaaaaab
	s_movk_i32 s27, 0x7f
	s_movk_i32 s28, 0xff
	s_movk_i32 s29, 0x80
	s_movk_i32 s30, 0xff00
	s_movk_i32 s31, 0x2fff
	s_cmp_lg_u32 s95, 0
	s_cmovk_i32 s31, 0x67ff
	v_add_u32_e32 v31, 0x400, v11
	v_add_u32_e32 v32, 0x800, v11
	v_add_u32_e32 v33, 0xc00, v11
	v_add_u32_e32 v34, 0x1000, v11
	v_add_u32_e32 v35, 0x1400, v11
	v_add_u32_e32 v36, 0x1800, v11
	v_add_u32_e32 v37, 0x1c00, v11
	v_readlane_b32 s37, v234, 4
	v_readlane_b32 s38, v234, 5
	v_readlane_b32 s39, v234, 6
	v_readlane_b32 s40, v234, 7
	v_readlane_b32 s41, v234, 8
	v_readlane_b32 s42, v234, 9
	v_readlane_b32 s43, v234, 10
	v_readlane_b32 s46, v234, 13
	v_readlane_b32 s47, v234, 14
	v_readlane_b32 s50, v234, 17
	v_readlane_b32 s51, v234, 18
	s_branch .LBB0_14

; __global__ void __launch_bounds__(512, 2) fwd_megakernel(Params p) {
;     ...
;     p0_prologue(p, lds, G);
;     if (DUP == 1) { __syncthreads(); p0_prologue(p, lds, G); }
;     if (p.ws == nullptr) grid.sync();
;     xcd_barrier(xbar);
.LBB0_33:
	s_or_b64 exec, exec, s[0:1]
	s_cmp_lg_u32 s95, 0
	s_cbranch_scc1 .Ltr_ret
	s_cmp_lg_u64 s[86:87], 0
	s_cbranch_scc1 .LBB0_45
	v_lshrrev_b32_e32 v1, 20, v0
	v_lshrrev_b32_e32 v0, 10, v0
	v_or_b32_e32 v0, v0, v1
	s_movk_i32 s0, 0x3ff
	v_and_or_b32 v0, v0, s0, v194
	v_cmp_eq_u32_e32 vcc, 0, v0
	s_barrier
	s_and_saveexec_b64 s[0:1], vcc
	s_cbranch_execz .LBB0_44
	buffer_wbl2 sc1
	s_waitcnt vmcnt(0)
	s_load_dwordx2 s[2:3], s[2:3], 0x58
	v_mov_b32_e32 v2, 0
	s_mov_b64 s[4:5], exec
	v_mbcnt_lo_u32_b32 v1, s4, 0
	v_mbcnt_hi_u32_b32 v1, s5, v1
	s_waitcnt lgkmcnt(0)
	global_load_dword v0, v2, s[2:3] offset:40
	v_cmp_eq_u32_e32 vcc, 0, v1
	s_and_saveexec_b64 s[6:7], vcc
	s_cbranch_execz .LBB0_37
	s_bcnt1_i32_b64 s4, s[4:5]
	v_mov_b32_e32 v3, s4
	global_atomic_add v3, v2, v3, s[2:3] offset:32 sc0

; #define PG8_STAGE(bufoff, gbase, voff) do { _Pragma("unroll") for (int _i = 0; _i < 2; ++_i) \
;         __builtin_amdgcn_global_load_lds((const unsigned*)((const char*)(gbase) + (voff)[_i]), (LAS unsigned*)(lds + (bufoff) + ldsw + _i * 8192), 16, 0, 0); } while (0)
; #define PG8_LDA(dst, b, h) do { _Pragma("unroll") for (int m = 0; m < 4; ++m) _Pragma("unroll") for (int k = 0; k < 2; ++k) dst[m][k] = *(const LAS bf16x8*)(lds + PG8_SA(b, h) + aoff + m * 2048 + k * 1024); } while (0)
; #define PG8_BAR __builtin_amdgcn_s_barrier()
; template <class Epi, class Sched, bool ALIGN_EPI = true>
; __device__ __forceinline__ void gemm_phase(LAS unsigned char* lds, const Gemm g, const Sched& S, const Epi& E) {
;     ...
;         for (int t = 0; t < nt; t += 2) {
;             const bool last = (t == nt - 2);
;             const char* a1 = cA + (size_t)(t + 1) * kstep;
;             const char* a2 = last ? nA : cA + (size_t)(t + 2) * kstep; const char* b2 = last ? nB : cB + (size_t)(t + 2) * kstep;
;             const char* a3 = a2 + kstep; const char* b3 = b2 + kstep;
;             if (last && has_next) S.a_ready(nxt);
;             if (Sched::PUBLISH && t == 4 && pend >= 0) {
;                 if (tid == 0) __hip_atomic_fetch_add(S.pub + 64 * pend, 1u, __ATOMIC_RELAXED, __HIP_MEMORY_SCOPE_AGENT);
;                 pend = -1;
;             }
;             PG8_LDB(B0, 0, 0); PG8_LDB(B1, 0, 1); PG8_SCHED; PG8_LDA(At, 0, 0); PG8_STAGE(PG8_SA(1, 1), a1 + hstep, voffA);
;             PG8_WAIT_V(8); PG8_WAIT_L(0); PG8_BAR; PG8_MMA(0, 0, At, B0); PG8_MMA(0, 1, At, B1); PG8_BAR; PG8_SCHED;
;             PG8_LDA(At, 0, 1); PG8_STAGE(PG8_SB(0, 0), b2, voffB); PG8_STAGE(PG8_SB(0, 1), b2 + hstep, voffB); PG8_STAGE(PG8_SA(0, 0), a2, voffA);
;             PG8_WAIT_V(8); PG8_WAIT_L(0); PG8_BAR; PG8_MMA(1, 0, At, B0); PG8_MMA(1, 1, At, B1); PG8_BAR; PG8_SCHED;
;             PG8_LDB(B0, 1, 0); PG8_LDB(B1, 1, 1); PG8_SCHED; PG8_LDA(At, 1, 0); PG8_STAGE(PG8_SA(0, 1), a2 + hstep, voffA);
;             PG8_WAIT_V(8); PG8_WAIT_L(0); PG8_BAR; PG8_MMA(0, 0, At, B0); PG8_MMA(0, 1, At, B1); PG8_BAR; PG8_SCHED;
;             PG8_LDA(At, 1, 1); PG8_STAGE(PG8_SB(1, 0), b3, voffB); PG8_STAGE(PG8_SB(1, 1), b3 + hstep, voffB); PG8_STAGE(PG8_SA(1, 0), a3, voffA);
;             PG8_WAIT_V(8); PG8_WAIT_L(0); PG8_BAR; PG8_MMA(1, 0, At, B0); PG8_MMA(1, 1, At, B1); PG8_BAR; PG8_SCHED;
.LBB0_115:
	s_or_b64 exec, exec, s[62:63]
	v_add_u32_e32 v156, s79, v162
	ds_read_b128 v[148:151], v156
	ds_read_b128 v[152:155], v156 offset:1024
	ds_read_b128 v[168:171], v156 offset:2048
	ds_read_b128 v[172:175], v156 offset:3072
	v_add_u32_e32 v156, s80, v162
	s_add_u32 s62, s58, s60
	ds_read_b128 v[176:179], v156
	ds_read_b128 v[180:183], v156 offset:1024
	ds_read_b128 v[184:187], v156 offset:2048
	ds_read_b128 v[188:191], v156 offset:3072
	s_addc_u32 s63, s59, s61
	s_add_u32 s62, s62, 0x100
	s_addc_u32 s63, s63, 0
	s_add_u32 s89, s82, s60
	s_addc_u32 s90, s83, s61
	s_cmpk_eq_i32 s60, 0xf00
	s_cselect_b32 s65, s3, s63
	s_cselect_b32 s64, s13, s62
	s_cselect_b32 s63, s18, s90
	s_cselect_b32 s62, s51, s89
	v_lshl_add_u64 v[156:157], v[144:145], 0, s[60:61]
	s_add_i32 m0, s39, 0xc000
	ds_read_b128 v[196:199], v165
	ds_read_b128 v[200:203], v165 offset:1024
	ds_read_b128 v[204:207], v165 offset:2048
	ds_read_b128 v[208:211], v165 offset:3072
	ds_read_b128 v[212:215], v165 offset:4096
	ds_read_b128 v[216:219], v165 offset:5120
	ds_read_b128 v[220:223], v165 offset:6144
	ds_read_b128 v[224:227], v165 offset:7168
	global_load_lds_dwordx4 v[156:157], off
	v_lshl_add_u64 v[156:157], v[146:147], 0, s[60:61]
	s_add_i32 m0, s39, 0xe000
	s_nop 0
	global_load_lds_dwordx4 v[156:157], off
	s_waitcnt vmcnt(8)
	s_waitcnt lgkmcnt(0)
	s_barrier
	s_setprio 1
	s_waitcnt lgkmcnt(0)
	v_mfma_f32_16x16x32_bf16 v[124:127], v[148:151], v[196:199], v[124:127]
	v_mfma_f32_16x16x32_bf16 v[116:119], v[168:171], v[196:199], v[116:119]
	v_mfma_f32_16x16x32_bf16 v[108:111], v[148:151], v[204:207], v[108:111]
	v_mfma_f32_16x16x32_bf16 v[100:103], v[168:171], v[204:207], v[100:103]
	v_mfma_f32_16x16x32_bf16 v[92:95], v[148:151], v[212:215], v[92:95]
	v_mfma_f32_16x16x32_bf16 v[84:87], v[168:171], v[212:215], v[84:87]
	v_mfma_f32_16x16x32_bf16 v[76:79], v[148:151], v[220:223], v[76:79]
	v_mfma_f32_16x16x32_bf16 v[68:71], v[168:171], v[220:223], v[68:71]
	v_mfma_f32_16x16x32_bf16 v[124:127], v[152:155], v[200:203], v[124:127]
	v_mfma_f32_16x16x32_bf16 v[116:119], v[172:175], v[200:203], v[116:119]
	v_mfma_f32_16x16x32_bf16 v[108:111], v[152:155], v[208:211], v[108:111]
	v_mfma_f32_16x16x32_bf16 v[100:103], v[172:175], v[208:211], v[100:103]
	v_mfma_f32_16x16x32_bf16 v[92:95], v[152:155], v[216:219], v[92:95]
	v_mfma_f32_16x16x32_bf16 v[84:87], v[172:175], v[216:219], v[84:87]
	v_mfma_f32_16x16x32_bf16 v[76:79], v[152:155], v[224:227], v[76:79]
	v_mfma_f32_16x16x32_bf16 v[68:71], v[172:175], v[224:227], v[68:71]
	s_setprio 0
	s_setprio 1
	v_mfma_f32_16x16x32_bf16 v[120:123], v[176:179], v[196:199], v[120:123]
	v_mfma_f32_16x16x32_bf16 v[112:115], v[184:187], v[196:199], v[112:115]
	v_mfma_f32_16x16x32_bf16 v[104:107], v[176:179], v[204:207], v[104:107]
	v_mfma_f32_16x16x32_bf16 v[96:99], v[184:187], v[204:207], v[96:99]
	v_mfma_f32_16x16x32_bf16 v[88:91], v[176:179], v[212:215], v[88:91]
	v_mfma_f32_16x16x32_bf16 v[80:83], v[184:187], v[212:215], v[80:83]
	v_mfma_f32_16x16x32_bf16 v[72:75], v[176:179], v[220:223], v[72:75]
	v_mfma_f32_16x16x32_bf16 v[64:67], v[184:187], v[220:223], v[64:67]
	v_mfma_f32_16x16x32_bf16 v[120:123], v[180:183], v[200:203], v[120:123]
	v_mfma_f32_16x16x32_bf16 v[112:115], v[188:191], v[200:203], v[112:115]
	v_mfma_f32_16x16x32_bf16 v[104:107], v[180:183], v[208:211], v[104:107]
	v_mfma_f32_16x16x32_bf16 v[96:99], v[188:191], v[208:211], v[96:99]
	v_mfma_f32_16x16x32_bf16 v[88:91], v[180:183], v[216:219], v[88:91]
	v_mfma_f32_16x16x32_bf16 v[80:83], v[188:191], v[216:219], v[80:83]
	v_mfma_f32_16x16x32_bf16 v[72:75], v[180:183], v[224:227], v[72:75]
	v_mfma_f32_16x16x32_bf16 v[64:67], v[188:191], v[224:227], v[64:67]
	s_setprio 0
	s_barrier
	s_add_i32 s89, s79, s37
	v_lshl_add_u64 v[156:157], s[62:63], 0, v[130:131]
	s_mov_b32 m0, s89
	ds_read_b128 v[196:199], v165 offset:16384
	ds_read_b128 v[200:203], v165 offset:17408
	ds_read_b128 v[204:207], v165 offset:18432
	ds_read_b128 v[208:211], v165 offset:19456
	ds_read_b128 v[212:215], v165 offset:20480
	ds_read_b128 v[216:219], v165 offset:21504
	ds_read_b128 v[220:223], v165 offset:22528
	ds_read_b128 v[224:227], v165 offset:23552
	global_load_lds_dwordx4 v[156:157], off
	s_add_i32 m0, s89, 0x2000
	s_add_u32 s90, s62, 0x80000
	v_lshl_add_u64 v[192:193], s[62:63], 0, v[134:135]
	s_addc_u32 s91, s63, 0
	s_add_i32 s89, s80, s37
	global_load_lds_dwordx4 v[192:193], off
	v_lshl_add_u64 v[228:229], s[90:91], 0, v[130:131]
	s_mov_b32 m0, s89
	v_lshl_add_u64 v[230:231], s[64:65], 0, v[132:133]
	global_load_lds_dwordx4 v[228:229], off
	v_lshl_add_u64 v[228:229], s[90:91], 0, v[134:135]
	s_add_i32 m0, s89, 0x2000
	s_nop 0
	global_load_lds_dwordx4 v[228:229], off
	v_lshl_add_u64 v[228:229], s[64:65], 0, v[128:129]
	s_mov_b32 m0, s39
	s_nop 0
	global_load_lds_dwordx4 v[228:229], off
	s_mov_b32 m0, s49
	s_nop 0
	global_load_lds_dwordx4 v[230:231], off
	s_waitcnt vmcnt(8)
	s_waitcnt lgkmcnt(0)
	s_barrier
; #define PG8_STAGE(bufoff, gbase, voff) do { _Pragma("unroll") for (int _i = 0; _i < 2; ++_i) \
;         __builtin_amdgcn_global_load_lds((const unsigned*)((const char*)(gbase) + (voff)[_i]), (LAS unsigned*)(lds + (bufoff) + ldsw + _i * 8192), 16, 0, 0); } while (0)
; #define PG8_LDA(dst, b, h) do { _Pragma("unroll") for (int m = 0; m < 4; ++m) _Pragma("unroll") for (int k = 0; k < 2; ++k) dst[m][k] = *(const LAS bf16x8*)(lds + PG8_SA(b, h) + aoff + m * 2048 + k * 1024); } while (0)
; #define PG8_LDB(dst, b, h) do { _Pragma("unroll") for (int n = 0; n < 2; ++n) _Pragma("unroll") for (int k = 0; k < 2; ++k) dst[n][k] = *(const LAS bf16x8*)(lds + PG8_SB(b, h) + boff + n * 2048 + k * 1024); } while (0)
; #define PG8_MMA(ai, bj, At, Bt) do { __builtin_amdgcn_s_setprio(1); _Pragma("unroll") for (int m = 0; m < 4; ++m) _Pragma("unroll") for (int n = 0; n < 2; ++n) _Pragma("unroll") for (int k = 0; k < 2; ++k) \
;         acc[ai][bj][m][n] = __builtin_amdgcn_mfma_f32_16x16x32_bf16(Bt[n][k], At[m][k], acc[ai][bj][m][n], 0, 0, 0); __builtin_amdgcn_s_setprio(0); } while (0)
; #define PG8_WAIT_V(n) asm volatile("s_waitcnt vmcnt(" #n ")" ::: "memory")
; template <class Epi, class Sched, bool ALIGN_EPI = true>
; __device__ __forceinline__ void gemm_phase(LAS unsigned char* lds, const Gemm g, const Sched& S, const Epi& E) {
;     ...
;             PG8_LDB(B0, 0, 0); PG8_LDB(B1, 0, 1); PG8_SCHED; PG8_LDA(At, 0, 0); PG8_STAGE(PG8_SA(1, 1), a1 + hstep, voffA);
;             PG8_WAIT_V(8); PG8_WAIT_L(0); PG8_BAR; PG8_MMA(0, 0, At, B0); PG8_MMA(0, 1, At, B1); PG8_BAR; PG8_SCHED;
;             PG8_LDA(At, 0, 1); PG8_STAGE(PG8_SB(0, 0), b2, voffB); PG8_STAGE(PG8_SB(0, 1), b2 + hstep, voffB); PG8_STAGE(PG8_SA(0, 0), a2, voffA);
;             PG8_WAIT_V(8); PG8_WAIT_L(0); PG8_BAR; PG8_MMA(1, 0, At, B0); PG8_MMA(1, 1, At, B1); PG8_BAR; PG8_SCHED;
;             PG8_LDB(B0, 1, 0); PG8_LDB(B1, 1, 1); PG8_SCHED; PG8_LDA(At, 1, 0); PG8_STAGE(PG8_SA(0, 1), a2 + hstep, voffA);
;             PG8_WAIT_V(8); PG8_WAIT_L(0); PG8_BAR; PG8_MMA(0, 0, At, B0); PG8_MMA(0, 1, At, B1); PG8_BAR; PG8_SCHED;
;             PG8_LDA(At, 1, 1); PG8_STAGE(PG8_SB(1, 0), b3, voffB); PG8_STAGE(PG8_SB(1, 1), b3 + hstep, voffB); PG8_STAGE(PG8_SA(1, 0), a3, voffA);
;             PG8_WAIT_V(8); PG8_WAIT_L(0); PG8_BAR; PG8_MMA(1, 0, At, B0); PG8_MMA(1, 1, At, B1); PG8_BAR; PG8_SCHED;
	s_setprio 1
	s_waitcnt lgkmcnt(0)
	v_mfma_f32_16x16x32_bf16 v[60:63], v[148:151], v[196:199], v[60:63]
	v_mfma_f32_16x16x32_bf16 v[52:55], v[168:171], v[196:199], v[52:55]
	v_mfma_f32_16x16x32_bf16 v[44:47], v[148:151], v[204:207], v[44:47]
	v_mfma_f32_16x16x32_bf16 v[36:39], v[168:171], v[204:207], v[36:39]
	v_mfma_f32_16x16x32_bf16 v[28:31], v[148:151], v[212:215], v[28:31]
	v_mfma_f32_16x16x32_bf16 v[20:23], v[168:171], v[212:215], v[20:23]
	v_mfma_f32_16x16x32_bf16 v[12:15], v[148:151], v[220:223], v[12:15]
	v_mfma_f32_16x16x32_bf16 v[4:7], v[168:171], v[220:223], v[4:7]
	v_mfma_f32_16x16x32_bf16 v[60:63], v[152:155], v[200:203], v[60:63]
	v_mfma_f32_16x16x32_bf16 v[52:55], v[172:175], v[200:203], v[52:55]
	v_mfma_f32_16x16x32_bf16 v[44:47], v[152:155], v[208:211], v[44:47]
	v_mfma_f32_16x16x32_bf16 v[36:39], v[172:175], v[208:211], v[36:39]
	v_mfma_f32_16x16x32_bf16 v[28:31], v[152:155], v[216:219], v[28:31]
	v_mfma_f32_16x16x32_bf16 v[20:23], v[172:175], v[216:219], v[20:23]
	v_mfma_f32_16x16x32_bf16 v[12:15], v[152:155], v[224:227], v[12:15]
	v_mfma_f32_16x16x32_bf16 v[4:7], v[172:175], v[224:227], v[4:7]
	s_setprio 0
	s_setprio 1
	v_mfma_f32_16x16x32_bf16 v[56:59], v[176:179], v[196:199], v[56:59]
	v_mfma_f32_16x16x32_bf16 v[48:51], v[184:187], v[196:199], v[48:51]
	v_mfma_f32_16x16x32_bf16 v[40:43], v[176:179], v[204:207], v[40:43]
	v_mfma_f32_16x16x32_bf16 v[32:35], v[184:187], v[204:207], v[32:35]
	v_mfma_f32_16x16x32_bf16 v[24:27], v[176:179], v[212:215], v[24:27]
	v_mfma_f32_16x16x32_bf16 v[16:19], v[184:187], v[212:215], v[16:19]
	v_mfma_f32_16x16x32_bf16 v[8:11], v[176:179], v[220:223], v[8:11]
	v_mfma_f32_16x16x32_bf16 v[0:3], v[184:187], v[220:223], v[0:3]
	v_mfma_f32_16x16x32_bf16 v[56:59], v[180:183], v[200:203], v[56:59]
	v_mfma_f32_16x16x32_bf16 v[48:51], v[188:191], v[200:203], v[48:51]
	v_mfma_f32_16x16x32_bf16 v[40:43], v[180:183], v[208:211], v[40:43]
	v_mfma_f32_16x16x32_bf16 v[32:35], v[188:191], v[208:211], v[32:35]
	v_mfma_f32_16x16x32_bf16 v[24:27], v[180:183], v[216:219], v[24:27]
	v_mfma_f32_16x16x32_bf16 v[16:19], v[188:191], v[216:219], v[16:19]
	v_mfma_f32_16x16x32_bf16 v[8:11], v[180:183], v[224:227], v[8:11]
	v_mfma_f32_16x16x32_bf16 v[0:3], v[188:191], v[224:227], v[0:3]
	s_setprio 0
	s_barrier
	s_add_i32 s89, 0, 0x18000
	s_add_i32 s90, 0, 0x1c000
	v_add_u32_e32 v172, s89, v162
	v_add_u32_e32 v188, s90, v162
	ds_read_b128 v[148:151], v172
	ds_read_b128 v[152:155], v172 offset:1024
	ds_read_b128 v[168:171], v172 offset:2048
	ds_read_b128 v[172:175], v172 offset:3072
	ds_read_b128 v[176:179], v188
	ds_read_b128 v[180:183], v188 offset:1024
	ds_read_b128 v[184:187], v188 offset:2048
	ds_read_b128 v[188:191], v188 offset:3072
	s_add_u32 s64, s64, 0x80000
	s_addc_u32 s65, s65, 0
	s_mov_b32 m0, s66
	v_lshl_add_u64 v[232:233], s[64:65], 0, v[128:129]
	ds_read_b128 v[196:199], v165 offset:32768
	ds_read_b128 v[200:203], v165 offset:33792
	ds_read_b128 v[204:207], v165 offset:34816
	ds_read_b128 v[208:211], v165 offset:35840
	ds_read_b128 v[212:215], v165 offset:36864
	ds_read_b128 v[216:219], v165 offset:37888
	ds_read_b128 v[220:223], v165 offset:38912
	ds_read_b128 v[224:227], v165 offset:39936
	global_load_lds_dwordx4 v[232:233], off
	v_lshl_add_u64 v[232:233], s[64:65], 0, v[132:133]
	s_mov_b32 m0, s67
	s_nop 0
	global_load_lds_dwordx4 v[232:233], off
	s_waitcnt vmcnt(8)
	s_waitcnt lgkmcnt(0)
	s_barrier
	s_setprio 1
	s_waitcnt lgkmcnt(0)
	v_mfma_f32_16x16x32_bf16 v[124:127], v[148:151], v[196:199], v[124:127]
	v_mfma_f32_16x16x32_bf16 v[116:119], v[168:171], v[196:199], v[116:119]
	v_mfma_f32_16x16x32_bf16 v[108:111], v[148:151], v[204:207], v[108:111]
	v_mfma_f32_16x16x32_bf16 v[100:103], v[168:171], v[204:207], v[100:103]
	v_mfma_f32_16x16x32_bf16 v[92:95], v[148:151], v[212:215], v[92:95]
	v_mfma_f32_16x16x32_bf16 v[84:87], v[168:171], v[212:215], v[84:87]
	v_mfma_f32_16x16x32_bf16 v[76:79], v[148:151], v[220:223], v[76:79]
	v_mfma_f32_16x16x32_bf16 v[68:71], v[168:171], v[220:223], v[68:71]
	v_mfma_f32_16x16x32_bf16 v[124:127], v[152:155], v[200:203], v[124:127]
	v_mfma_f32_16x16x32_bf16 v[116:119], v[172:175], v[200:203], v[116:119]
	v_mfma_f32_16x16x32_bf16 v[108:111], v[152:155], v[208:211], v[108:111]
	v_mfma_f32_16x16x32_bf16 v[100:103], v[172:175], v[208:211], v[100:103]
	v_mfma_f32_16x16x32_bf16 v[92:95], v[152:155], v[216:219], v[92:95]
	v_mfma_f32_16x16x32_bf16 v[84:87], v[172:175], v[216:219], v[84:87]
	v_mfma_f32_16x16x32_bf16 v[76:79], v[152:155], v[224:227], v[76:79]
	v_mfma_f32_16x16x32_bf16 v[68:71], v[172:175], v[224:227], v[68:71]
	s_setprio 0
	s_setprio 1
	v_mfma_f32_16x16x32_bf16 v[120:123], v[176:179], v[196:199], v[120:123]
	v_mfma_f32_16x16x32_bf16 v[112:115], v[184:187], v[196:199], v[112:115]
	v_mfma_f32_16x16x32_bf16 v[104:107], v[176:179], v[204:207], v[104:107]
	v_mfma_f32_16x16x32_bf16 v[96:99], v[184:187], v[204:207], v[96:99]
	v_mfma_f32_16x16x32_bf16 v[88:91], v[176:179], v[212:215], v[88:91]
	v_mfma_f32_16x16x32_bf16 v[80:83], v[184:187], v[212:215], v[80:83]
	v_mfma_f32_16x16x32_bf16 v[72:75], v[176:179], v[220:223], v[72:75]
	v_mfma_f32_16x16x32_bf16 v[64:67], v[184:187], v[220:223], v[64:67]
	v_mfma_f32_16x16x32_bf16 v[120:123], v[180:183], v[200:203], v[120:123]
	v_mfma_f32_16x16x32_bf16 v[112:115], v[188:191], v[200:203], v[112:115]
	v_mfma_f32_16x16x32_bf16 v[104:107], v[180:183], v[208:211], v[104:107]
	v_mfma_f32_16x16x32_bf16 v[96:99], v[188:191], v[208:211], v[96:99]
	v_mfma_f32_16x16x32_bf16 v[88:91], v[180:183], v[216:219], v[88:91]
	v_mfma_f32_16x16x32_bf16 v[80:83], v[188:191], v[216:219], v[80:83]
	v_mfma_f32_16x16x32_bf16 v[72:75], v[180:183], v[224:227], v[72:75]
	v_mfma_f32_16x16x32_bf16 v[64:67], v[188:191], v[224:227], v[64:67]
	s_setprio 0
	s_barrier
; #define PG8_STAGE(bufoff, gbase, voff) do { _Pragma("unroll") for (int _i = 0; _i < 2; ++_i) \
;         __builtin_amdgcn_global_load_lds((const unsigned*)((const char*)(gbase) + (voff)[_i]), (LAS unsigned*)(lds + (bufoff) + ldsw + _i * 8192), 16, 0, 0); } while (0)
; #define PG8_LDA(dst, b, h) do { _Pragma("unroll") for (int m = 0; m < 4; ++m) _Pragma("unroll") for (int k = 0; k < 2; ++k) dst[m][k] = *(const LAS bf16x8*)(lds + PG8_SA(b, h) + aoff + m * 2048 + k * 1024); } while (0)
; #define PG8_LDB(dst, b, h) do { _Pragma("unroll") for (int n = 0; n < 2; ++n) _Pragma("unroll") for (int k = 0; k < 2; ++k) dst[n][k] = *(const LAS bf16x8*)(lds + PG8_SB(b, h) + boff + n * 2048 + k * 1024); } while (0)
; #define PG8_MMA(ai, bj, At, Bt) do { __builtin_amdgcn_s_setprio(1); _Pragma("unroll") for (int m = 0; m < 4; ++m) _Pragma("unroll") for (int n = 0; n < 2; ++n) _Pragma("unroll") for (int k = 0; k < 2; ++k) \
;         acc[ai][bj][m][n] = __builtin_amdgcn_mfma_f32_16x16x32_bf16(Bt[n][k], At[m][k], acc[ai][bj][m][n], 0, 0, 0); __builtin_amdgcn_s_setprio(0); } while (0)
; #define PG8_WAIT_V(n) asm volatile("s_waitcnt vmcnt(" #n ")" ::: "memory")
; #define PG8_WAIT_L(n) asm volatile("s_waitcnt lgkmcnt(" #n ")" ::: "memory")
; #define PG8_BAR __builtin_amdgcn_s_barrier()
; #define PG8_SCHED __builtin_amdgcn_sched_barrier(0)
; template <class Epi, class Sched, bool ALIGN_EPI = true>
; __device__ __forceinline__ void gemm_phase(LAS unsigned char* lds, const Gemm g, const Sched& S, const Epi& E) {
;     ...
;             PG8_LDB(B0, 1, 0); PG8_LDB(B1, 1, 1); PG8_SCHED; PG8_LDA(At, 1, 0); PG8_STAGE(PG8_SA(0, 1), a2 + hstep, voffA);
;             PG8_WAIT_V(8); PG8_WAIT_L(0); PG8_BAR; PG8_MMA(0, 0, At, B0); PG8_MMA(0, 1, At, B1); PG8_BAR; PG8_SCHED;
;             PG8_LDA(At, 1, 1); PG8_STAGE(PG8_SB(1, 0), b3, voffB); PG8_STAGE(PG8_SB(1, 1), b3 + hstep, voffB); PG8_STAGE(PG8_SA(1, 0), a3, voffA);
;             PG8_WAIT_V(8); PG8_WAIT_L(0); PG8_BAR; PG8_MMA(1, 0, At, B0); PG8_MMA(1, 1, At, B1); PG8_BAR; PG8_SCHED;
;         }
	s_add_i32 s64, s89, s37
	v_lshl_add_u64 v[156:157], v[156:157], 0, s[26:27]
	s_mov_b32 m0, s64
	ds_read_b128 v[196:199], v165 offset:49152
	ds_read_b128 v[200:203], v165 offset:50176
	ds_read_b128 v[204:207], v165 offset:51200
	ds_read_b128 v[208:211], v165 offset:52224
	ds_read_b128 v[212:215], v165 offset:53248
	ds_read_b128 v[216:219], v165 offset:54272
	ds_read_b128 v[220:223], v165 offset:55296
	ds_read_b128 v[224:227], v165 offset:56320
	global_load_lds_dwordx4 v[156:157], off
	s_add_i32 m0, s64, 0x2000
	s_add_u32 s62, s62, 0x80080
	v_lshl_add_u64 v[156:157], v[192:193], 0, s[26:27]
	s_addc_u32 s63, s63, 0
	s_add_i32 s64, s90, s37
	global_load_lds_dwordx4 v[156:157], off
	v_lshl_add_u64 v[156:157], s[62:63], 0, v[130:131]
	s_mov_b32 m0, s64
	s_nop 0
	global_load_lds_dwordx4 v[156:157], off
	v_lshl_add_u64 v[156:157], s[62:63], 0, v[134:135]
	s_add_i32 m0, s64, 0x2000
	s_nop 0
	global_load_lds_dwordx4 v[156:157], off
	v_lshl_add_u64 v[156:157], v[228:229], 0, s[26:27]
	s_mov_b32 m0, s68
	s_nop 0
	global_load_lds_dwordx4 v[156:157], off
	v_lshl_add_u64 v[156:157], v[230:231], 0, s[26:27]
	s_mov_b32 m0, s69
	s_nop 0
	global_load_lds_dwordx4 v[156:157], off
	s_waitcnt vmcnt(8)
	s_waitcnt lgkmcnt(0)
	s_barrier
	s_setprio 1
	s_waitcnt lgkmcnt(0)
	v_mfma_f32_16x16x32_bf16 v[60:63], v[148:151], v[196:199], v[60:63]
	v_mfma_f32_16x16x32_bf16 v[52:55], v[168:171], v[196:199], v[52:55]
	v_mfma_f32_16x16x32_bf16 v[44:47], v[148:151], v[204:207], v[44:47]
	v_mfma_f32_16x16x32_bf16 v[36:39], v[168:171], v[204:207], v[36:39]
	v_mfma_f32_16x16x32_bf16 v[28:31], v[148:151], v[212:215], v[28:31]
	v_mfma_f32_16x16x32_bf16 v[20:23], v[168:171], v[212:215], v[20:23]
	v_mfma_f32_16x16x32_bf16 v[12:15], v[148:151], v[220:223], v[12:15]
	v_mfma_f32_16x16x32_bf16 v[4:7], v[168:171], v[220:223], v[4:7]
	v_mfma_f32_16x16x32_bf16 v[60:63], v[152:155], v[200:203], v[60:63]
	v_mfma_f32_16x16x32_bf16 v[52:55], v[172:175], v[200:203], v[52:55]
	v_mfma_f32_16x16x32_bf16 v[44:47], v[152:155], v[208:211], v[44:47]
	v_mfma_f32_16x16x32_bf16 v[36:39], v[172:175], v[208:211], v[36:39]
	v_mfma_f32_16x16x32_bf16 v[28:31], v[152:155], v[216:219], v[28:31]
	v_mfma_f32_16x16x32_bf16 v[20:23], v[172:175], v[216:219], v[20:23]
	v_mfma_f32_16x16x32_bf16 v[12:15], v[152:155], v[224:227], v[12:15]
	v_mfma_f32_16x16x32_bf16 v[4:7], v[172:175], v[224:227], v[4:7]
	s_setprio 0
	s_setprio 1
	v_mfma_f32_16x16x32_bf16 v[56:59], v[176:179], v[196:199], v[56:59]
	v_mfma_f32_16x16x32_bf16 v[48:51], v[184:187], v[196:199], v[48:51]
	v_mfma_f32_16x16x32_bf16 v[40:43], v[176:179], v[204:207], v[40:43]
	v_mfma_f32_16x16x32_bf16 v[32:35], v[184:187], v[204:207], v[32:35]
	v_mfma_f32_16x16x32_bf16 v[24:27], v[176:179], v[212:215], v[24:27]
	v_mfma_f32_16x16x32_bf16 v[16:19], v[184:187], v[212:215], v[16:19]
	v_mfma_f32_16x16x32_bf16 v[8:11], v[176:179], v[220:223], v[8:11]
	v_mfma_f32_16x16x32_bf16 v[0:3], v[184:187], v[220:223], v[0:3]
	v_mfma_f32_16x16x32_bf16 v[56:59], v[180:183], v[200:203], v[56:59]
	v_mfma_f32_16x16x32_bf16 v[48:51], v[188:191], v[200:203], v[48:51]
	v_mfma_f32_16x16x32_bf16 v[40:43], v[180:183], v[208:211], v[40:43]
	v_mfma_f32_16x16x32_bf16 v[32:35], v[188:191], v[208:211], v[32:35]
	v_mfma_f32_16x16x32_bf16 v[24:27], v[180:183], v[216:219], v[24:27]
	v_mfma_f32_16x16x32_bf16 v[16:19], v[188:191], v[216:219], v[16:19]
	v_mfma_f32_16x16x32_bf16 v[8:11], v[180:183], v[224:227], v[8:11]
	v_mfma_f32_16x16x32_bf16 v[0:3], v[188:191], v[224:227], v[0:3]
	s_setprio 0
	s_barrier
	s_add_i32 s88, s88, 2
	s_add_u32 s60, s60, 0x100
	s_addc_u32 s61, s61, 0
	s_cmp_gt_u32 s88, 29
	v_mov_b32_e32 v148, v136
	s_cbranch_scc1 .LBB0_118

; __device__ __forceinline__ void mix_phase(const Params& p, LAS unsigned char* lds, int G, bool dry) {
;     ...
;     for (;;) {
;         __syncthreads();
;         const int unit = misc[0];
;         if (unit >= 66 * 16) break;
;         const int nb = unit >> 4, g = unit & 15, row_base = nb * 128; const bool smp = nb >= 64;
;         if (!((seen >> (nb >> 1)) & 1ull)) {
;             if (tid < 64) pg8::panel_wait_wave0(pcnt, nb >> 1, 48u);
;             seen |= 1ull << (nb >> 1);
;         }
;         __syncthreads();
.LBB0_159:
	s_waitcnt lgkmcnt(0)
	s_barrier
	ds_read_b32 v0, v129
	s_mov_b64 s[10:11], -1
	s_waitcnt lgkmcnt(0)
	v_cmp_lt_i32_e32 vcc, s38, v0
	v_readfirstlane_b32 s18, v0
	s_cbranch_vccnz .LBB0_158
	s_ashr_i32 s34, s18, 5
	s_lshl_b64 s[10:11], 1, s34
	s_and_b64 s[30:31], s[10:11], s[28:29]
	s_cmp_lg_u64 s[30:31], 0
	s_cbranch_scc1 .LBB0_172
	s_and_saveexec_b64 s[30:31], s[4:5]
	s_cbranch_execz .LBB0_171
	s_lshl_b32 s34, s34, 6
	s_ashr_i32 s35, s34, 31
	s_lshl_b64 s[34:35], s[34:35], 2
	s_add_u32 s34, s16, s34
	s_addc_u32 s35, s17, s35
	s_mov_b32 s43, 0x400001
	s_branch .LBB0_164

; __device__ __forceinline__ void mix_phase(const Params& p, LAS unsigned char* lds, int G, bool dry) {
;     ...
;         int nticket = 0;
;         if (tid == 0) nticket = (int)atomicAdd(ctr, 1u);
;         u32x4 raw[8];
; #pragma unroll
;         for (int i = 0; i < 8; ++i) { const int cid = tid + 512 * i, s = cid >> 5, c = (cid & 31) * 8; raw[i] = __builtin_nontemporal_load((const u32x4*)(gv + (size_t)(row_base + s) * GW + g * 256 + c)); }
;         const int t = tid >> 2, s0 = (tid & 3) * 32; bool on; const float* src;
;         if (smp) { on = (t >> 5) == (tid & 3); src = p.wsp + ((size_t)g * 128 + (t & 31)) * 128; }
;         else { on = (s0 >> 6) <= (t >> 6); src = p.wsp + ((size_t)g * 128 + t) * 128 + s0; }
.LBB0_172:
	v_mov_b32_e32 v130, 0
	s_barrier
	s_and_saveexec_b64 s[10:11], s[12:13]
	s_cbranch_execz .LBB0_176
	s_mov_b64 s[34:35], exec
	v_mbcnt_lo_u32_b32 v0, s34, 0
	v_mbcnt_hi_u32_b32 v0, s35, v0
	v_cmp_eq_u32_e32 vcc, 0, v0
	s_and_saveexec_b64 s[30:31], vcc
	s_cbranch_execz .LBB0_175
	s_bcnt1_i32_b64 s34, s[34:35]
	v_mov_b32_e32 v1, s34
	global_atomic_add v235, v83, v1, s[86:87] offset:8 sc0
.LBB0_175:
	s_or_b64 exec, exec, s[30:31]
.LBB0_176:
	s_or_b64 exec, exec, s[10:11]
	s_ashr_i32 s10, s18, 4
	s_and_b32 s36, s18, 15
	s_lshl_b32 s37, s10, 7
	s_cmp_gt_i32 s10, 63
	v_add_u32_e32 v2, s37, v96
	v_add_u32_e32 v4, s37, v97
	s_cselect_b64 s[30:31], -1, 0
	s_lshl_b32 s18, s36, 9
	v_ashrrev_i32_e32 v3, 31, v2
	v_ashrrev_i32_e32 v5, 31, v4
	v_lshl_add_u64 v[0:1], v[84:85], 0, s[18:19]
	v_lshlrev_b64 v[2:3], 13, v[2:3]
	v_lshlrev_b64 v[4:5], 13, v[4:5]
	v_lshl_add_u64 v[2:3], v[0:1], 0, v[2:3]
	v_lshl_add_u64 v[4:5], v[0:1], 0, v[4:5]
	global_load_dwordx4 v[44:47], v[2:3], off nt
	global_load_dwordx4 v[40:43], v[4:5], off nt
	v_add_u32_e32 v2, s37, v98
	v_add_u32_e32 v4, s37, v99
	v_ashrrev_i32_e32 v3, 31, v2
	v_ashrrev_i32_e32 v5, 31, v4
	v_lshlrev_b64 v[2:3], 13, v[2:3]
	v_lshlrev_b64 v[4:5], 13, v[4:5]
	v_lshl_add_u64 v[2:3], v[0:1], 0, v[2:3]
	v_lshl_add_u64 v[4:5], v[0:1], 0, v[4:5]
	global_load_dwordx4 v[36:39], v[2:3], off nt
	global_load_dwordx4 v[32:35], v[4:5], off nt
	v_add_u32_e32 v2, s37, v100
	v_add_u32_e32 v4, s37, v101
	v_ashrrev_i32_e32 v3, 31, v2
	v_ashrrev_i32_e32 v5, 31, v4
	v_lshlrev_b64 v[2:3], 13, v[2:3]
	v_lshlrev_b64 v[4:5], 13, v[4:5]
	v_lshl_add_u64 v[2:3], v[0:1], 0, v[2:3]
	v_lshl_add_u64 v[4:5], v[0:1], 0, v[4:5]
	global_load_dwordx4 v[12:15], v[2:3], off nt
	global_load_dwordx4 v[8:11], v[4:5], off nt
	v_add_u32_e32 v2, s37, v102
	v_add_u32_e32 v4, s37, v103
	v_ashrrev_i32_e32 v3, 31, v2
	v_ashrrev_i32_e32 v5, 31, v4
	v_lshlrev_b64 v[2:3], 13, v[2:3]
	v_lshlrev_b64 v[4:5], 13, v[4:5]
	v_lshl_add_u64 v[2:3], v[0:1], 0, v[2:3]
	v_lshl_add_u64 v[0:1], v[0:1], 0, v[4:5]
	global_load_dwordx4 v[4:7], v[2:3], off nt
	s_nop 0
	global_load_dwordx4 v[0:3], v[0:1], off nt
	s_cmp_lt_i32 s10, 64
	s_mov_b64 s[10:11], -1
	s_cbranch_scc0 .LBB0_178
	s_lshl_b32 s18, s36, 7
	v_lshl_add_u64 v[16:17], s[18:19], 0, v[86:87]
	v_lshlrev_b64 v[16:17], 9, v[16:17]
	v_lshl_add_u64 v[16:17], v[90:91], 0, v[16:17]
	s_mov_b64 s[10:11], 0

; __device__ __forceinline__ void mix_phase(const Params& p, LAS unsigned char* lds, int G, bool dry) {
;     ...
;         for (int i = 0; i < 8; ++i) {
;             const int cid = tid + 512 * i, s = cid >> 5, c = (cid & 31) * 8;
;             const float mu = st[s], rs = st[128 + s];
;             f32x4 x0 = (f32x4){bf_lo(raw[i].x), bf_hi(raw[i].x), bf_lo(raw[i].y), bf_hi(raw[i].y)}, x1 = (f32x4){bf_lo(raw[i].z), bf_hi(raw[i].z), bf_lo(raw[i].w), bf_hi(raw[i].w)};
;             x0 = (x0 - mu) * rs * g0 + b0; x1 = (x1 - mu) * rs * g1 + b1;
;             if (smp) { float* o = p.out + O_GMV + (size_t)(row_base - MP + s) * GW + g * 256 + c; __builtin_nontemporal_store(x0, (f32x4*)o); __builtin_nontemporal_store(x1, (f32x4*)(o + 4)); }
;             u32x4 w; w.x = cvt_pk_bf16(x0[0], x0[1]); w.y = cvt_pk_bf16(x0[2], x0[3]); w.z = cvt_pk_bf16(x1[0], x1[1]); w.w = cvt_pk_bf16(x1[2], x1[3]);
;             *(LAS u32x4*)(Vl + s * MIX_VP + c) = w;
;         }
;         u32x2 ur[4][4]; float bias[4];
;         bf16_t* const gup = gu + (size_t)(row_base + 64 * wr + fr) * GW + g * 256 + 64 * wc + 4 * fq;
; #pragma unroll
;         for (int m = 0; m < 4; ++m) {
;             const int tt = 64 * wr + 16 * m + fr; bias[m] = p.bsp[g * 128 + (smp ? (tt & 31) : tt)];
; #pragma unroll
;             for (int n = 0; n < 4; ++n) ur[m][n] = __builtin_nontemporal_load((const u32x2*)(gup + (size_t)m * 16 * GW + 16 * n));
;         }
;         __syncthreads();
;         f32x4 acc[4][4];
; #pragma unroll
;         for (int m = 0; m < 4; ++m)
; #pragma unroll
;             for (int n = 0; n < 4; ++n) acc[m][n] = (f32x4){0.f, 0.f, 0.f, 0.f};
; #pragma unroll
;         for (int ks = 0; ks < 4; ++ks) {
;             bf16x8 af[4], bfr[4];
; #pragma unroll
;             for (int m = 0; m < 4; ++m) af[m] = *(const LAS bf16x8*)(Wl + (64 * wr + 16 * m + fr) * MIX_WP + 32 * ks + 8 * fq);
; #pragma unroll
;             for (int n = 0; n < 4; ++n) {
;                 const LAS bf16_t* a0 = Vl + (32 * ks + 8 * fq + (fr >> 2)) * MIX_VP + 64 * wc + 16 * n + 4 * (fr & 3);
;                 const s16x4 lo = __builtin_amdgcn_ds_read_tr16_b64_v4i16((LAS s16x4*)a0), hi = __builtin_amdgcn_ds_read_tr16_b64_v4i16((LAS s16x4*)(a0 + 4 * MIX_VP));
;                 bfr[n] = (bf16x8){lo[0], lo[1], lo[2], lo[3], hi[0], hi[1], hi[2], hi[3]};
;             }
; #pragma unroll
;             for (int m = 0; m < 4; ++m)
.LBB0_214:
	v_cvt_pk_bf16_f32 v0, v0, v1
	v_cvt_pk_bf16_f32 v1, v2, v3
	v_cvt_pk_bf16_f32 v2, v4, v5
	v_cvt_pk_bf16_f32 v3, v6, v7
	ds_write_b128 v127, v[0:3] offset:34816
	v_add_u32_e32 v0, s37, v95
	v_ashrrev_i32_e32 v1, 31, v0
	v_lshlrev_b64 v[0:1], 13, v[0:1]
	v_lshl_add_u64 v[0:1], s[0:1], 0, v[0:1]
	s_lshl_b32 s18, s34, 1
	v_lshl_add_u64 v[0:1], v[0:1], 0, s[18:19]
	v_lshl_add_u64 v[0:1], v[0:1], 0, v[82:83]
	v_mov_b32_e32 v93, v83
	s_lshl_b32 s10, s36, 7
	v_lshl_add_u64 v[34:35], v[0:1], 0, v[92:93]
	v_add_u32_e32 v0, s10, v11
	v_ashrrev_i32_e32 v1, 31, v0
	v_add_u32_e32 v2, s10, v10
	v_lshl_add_u64 v[0:1], v[0:1], 2, s[76:77]
	v_ashrrev_i32_e32 v3, 31, v2
	global_load_dwordx2 v[46:47], v[34:35], off nt
	global_load_dwordx2 v[44:45], v[34:35], off offset:32 nt
	global_load_dwordx2 v[42:43], v[34:35], off offset:64 nt
	global_load_dwordx2 v[38:39], v[34:35], off offset:96 nt
	v_lshl_add_u64 v[2:3], v[2:3], 2, s[76:77]
	global_load_dword v40, v[0:1], off
	global_load_dword v28, v[2:3], off
	v_add_co_u32_e32 v22, vcc, s40, v34
	v_add_u32_e32 v0, s10, v9
	s_nop 0
	v_addc_co_u32_e32 v23, vcc, 0, v35, vcc
	global_load_dwordx2 v[36:37], v[22:23], off nt
	global_load_dwordx2 v[32:33], v[22:23], off offset:32 nt
	global_load_dwordx2 v[30:31], v[22:23], off offset:64 nt
	global_load_dwordx2 v[26:27], v[22:23], off offset:96 nt
	v_ashrrev_i32_e32 v1, 31, v0
	v_lshl_add_u64 v[0:1], v[0:1], 2, s[76:77]
	global_load_dword v16, v[0:1], off
	v_add_co_u32_e32 v10, vcc, s41, v34
	v_add_u32_e32 v0, s10, v8
	s_nop 0
	v_addc_co_u32_e32 v11, vcc, 0, v35, vcc
	global_load_dwordx2 v[24:25], v[10:11], off nt
	global_load_dwordx2 v[20:21], v[10:11], off offset:32 nt
	global_load_dwordx2 v[18:19], v[10:11], off offset:64 nt
	global_load_dwordx2 v[14:15], v[10:11], off offset:96 nt
	v_ashrrev_i32_e32 v1, 31, v0
	v_lshl_add_u64 v[0:1], v[0:1], 2, s[76:77]
	global_load_dword v4, v[0:1], off
	v_add_co_u32_e32 v0, vcc, s42, v34
	s_waitcnt vmcnt(15)
	v_lshlrev_b32_e32 v5, 16, v46
	v_addc_co_u32_e32 v1, vcc, 0, v35, vcc
	global_load_dwordx2 v[12:13], v[0:1], off nt
	global_load_dwordx2 v[8:9], v[0:1], off offset:32 nt
	global_load_dwordx2 v[6:7], v[0:1], off offset:64 nt
	global_load_dwordx2 v[2:3], v[0:1], off offset:96 nt
	s_waitcnt lgkmcnt(0)
	s_barrier
	ds_read_b64_tr_b16 v[50:51], v116 offset:36928
	ds_read_b64_tr_b16 v[48:49], v116 offset:34816
	ds_read_b128 v[52:55], v128
	ds_read_b64_tr_b16 v[58:59], v116 offset:36960
	ds_read_b64_tr_b16 v[56:57], v116 offset:34848
	ds_read_b64_tr_b16 v[60:61], v116 offset:34880
	ds_read_b64_tr_b16 v[64:65], v116 offset:34912
	ds_read_b64_tr_b16 v[62:63], v116 offset:36992
	ds_read_b64_tr_b16 v[66:67], v116 offset:37024
	ds_read_b128 v[68:71], v128 offset:64
	ds_read_b128 v[136:139], v128 offset:4352
	ds_read_b128 v[140:143], v128 offset:4416
	ds_read_b128 v[156:159], v128 offset:8704
	ds_read_b128 v[160:163], v128 offset:8768
	ds_read_b128 v[176:179], v128 offset:13056
	ds_read_b128 v[180:183], v128 offset:13120
	s_waitcnt lgkmcnt(13)
	v_mfma_f32_16x16x32_bf16 v[72:75], v[48:51], v[52:55], 0
	ds_read_b64_tr_b16 v[184:185], v116 offset:51712
	ds_read_b64_tr_b16 v[186:187], v116 offset:53824
	v_and_b32_e32 v17, 0xffff0000, v46
	s_waitcnt lgkmcnt(13)
	v_mfma_f32_16x16x32_bf16 v[76:79], v[56:59], v[52:55], 0
	s_waitcnt lgkmcnt(10)
	v_mfma_f32_16x16x32_bf16 v[132:135], v[60:63], v[52:55], 0
	s_waitcnt lgkmcnt(9)
	v_mfma_f32_16x16x32_bf16 v[52:55], v[64:67], v[52:55], 0
	s_waitcnt lgkmcnt(7)
	v_mfma_f32_16x16x32_bf16 v[144:147], v[48:51], v[136:139], 0
	v_mfma_f32_16x16x32_bf16 v[148:151], v[56:59], v[136:139], 0
	v_mfma_f32_16x16x32_bf16 v[152:155], v[60:63], v[136:139], 0
	v_mfma_f32_16x16x32_bf16 v[136:139], v[64:67], v[136:139], 0
	s_waitcnt lgkmcnt(5)
	v_mfma_f32_16x16x32_bf16 v[164:167], v[48:51], v[156:159], 0
	v_mfma_f32_16x16x32_bf16 v[168:171], v[56:59], v[156:159], 0
	v_mfma_f32_16x16x32_bf16 v[172:175], v[60:63], v[156:159], 0
	v_mfma_f32_16x16x32_bf16 v[156:159], v[64:67], v[156:159], 0
	s_waitcnt lgkmcnt(3)
	v_mfma_f32_16x16x32_bf16 v[48:51], v[48:51], v[176:179], 0
	v_mfma_f32_16x16x32_bf16 v[56:59], v[56:59], v[176:179], 0
	v_mfma_f32_16x16x32_bf16 v[60:63], v[60:63], v[176:179], 0
	v_mfma_f32_16x16x32_bf16 v[64:67], v[64:67], v[176:179], 0
	ds_read_b64_tr_b16 v[178:179], v116 offset:53856
	ds_read_b64_tr_b16 v[176:177], v116 offset:51744
	ds_read_b64_tr_b16 v[188:189], v116 offset:51776
	ds_read_b64_tr_b16 v[196:197], v116 offset:51808
	ds_read_b64_tr_b16 v[190:191], v116 offset:53888
	ds_read_b64_tr_b16 v[198:199], v116 offset:53920
	s_waitcnt lgkmcnt(6)
	v_mfma_f32_16x16x32_bf16 v[72:75], v[184:187], v[68:71], v[72:75]
	s_waitcnt lgkmcnt(4)
	v_mfma_f32_16x16x32_bf16 v[76:79], v[176:179], v[68:71], v[76:79]
	s_waitcnt lgkmcnt(1)
	v_mfma_f32_16x16x32_bf16 v[132:135], v[188:191], v[68:71], v[132:135]
	s_waitcnt lgkmcnt(0)
; __device__ __forceinline__ unsigned cvt_pk_bf16(float lo, float hi) { unsigned r; asm volatile("v_cvt_pk_bf16_f32 %0, %1, %2" : "=v"(r) : "v"(lo), "v"(hi)); return r; }
; __device__ __forceinline__ float bf_lo(unsigned w) { return __uint_as_float(w << 16); }
; __device__ __forceinline__ float bf_hi(unsigned w) { return __uint_as_float(w & 0xffff0000u); }
; __device__ __forceinline__ void mix_phase(const Params& p, LAS unsigned char* lds, int G, bool dry) {
;     ...
; #pragma unroll
;             for (int m = 0; m < 4; ++m)
; #pragma unroll
;                 for (int n = 0; n < 4; ++n) acc[m][n] = __builtin_amdgcn_mfma_f32_16x16x32_bf16(bfr[n], af[m], acc[m][n], 0, 0, 0);
;         }
; #pragma unroll
;         for (int m = 0; m < 4; ++m) {
; #pragma unroll
;             for (int n = 0; n < 4; ++n) {
;                 const f32x4 a = acc[m][n] + bias[m]; const u32x2 u2 = ur[m][n];
;                 u32x2 w; w.x = cvt_pk_bf16(bf_lo(u2.x) * a[0], bf_hi(u2.x) * a[1]); w.y = cvt_pk_bf16(bf_lo(u2.y) * a[2], bf_hi(u2.y) * a[3]);
;                 if (!dry) *(u32x2*)(gup + (size_t)m * 16 * GW + 16 * n) = w;
;             }
	v_mfma_f32_16x16x32_bf16 v[52:55], v[196:199], v[68:71], v[52:55]
	v_mfma_f32_16x16x32_bf16 v[68:71], v[184:187], v[140:143], v[144:147]
	v_mfma_f32_16x16x32_bf16 v[144:147], v[176:179], v[140:143], v[148:151]
	v_mfma_f32_16x16x32_bf16 v[148:151], v[188:191], v[140:143], v[152:155]
	v_mfma_f32_16x16x32_bf16 v[136:139], v[196:199], v[140:143], v[136:139]
	v_mfma_f32_16x16x32_bf16 v[140:143], v[184:187], v[160:163], v[164:167]
	v_mfma_f32_16x16x32_bf16 v[152:155], v[176:179], v[160:163], v[168:171]
	v_mfma_f32_16x16x32_bf16 v[164:167], v[188:191], v[160:163], v[172:175]
	v_mfma_f32_16x16x32_bf16 v[156:159], v[196:199], v[160:163], v[156:159]
	ds_read_b128 v[160:163], v128 offset:128
	ds_read_b64_tr_b16 v[170:171], v117 offset:35904
	v_mfma_f32_16x16x32_bf16 v[48:51], v[184:187], v[180:183], v[48:51]
	v_mfma_f32_16x16x32_bf16 v[56:59], v[176:179], v[180:183], v[56:59]
	ds_read_b64_tr_b16 v[168:169], v117 offset:33792
	ds_read_b64_tr_b16 v[172:173], v117 offset:33824
	ds_read_b64_tr_b16 v[176:177], v117 offset:33856
	ds_read_b64_tr_b16 v[184:185], v117 offset:33888
	v_mfma_f32_16x16x32_bf16 v[60:63], v[188:191], v[180:183], v[60:63]
	v_mfma_f32_16x16x32_bf16 v[64:67], v[196:199], v[180:183], v[64:67]
	ds_read_b64_tr_b16 v[174:175], v117 offset:35936
	ds_read_b64_tr_b16 v[178:179], v117 offset:35968
	ds_read_b64_tr_b16 v[186:187], v117 offset:36000
	ds_read_b128 v[180:183], v128 offset:192
	ds_read_b128 v[188:191], v128 offset:4480
	ds_read_b128 v[196:199], v128 offset:4544
	ds_read_b128 v[200:203], v128 offset:8832
	ds_read_b128 v[204:207], v128 offset:8896
	ds_read_b128 v[208:211], v128 offset:13184
	ds_read_b128 v[212:215], v128 offset:13248
	ds_read_b64_tr_b16 v[216:217], v117 offset:50688
	ds_read_b64_tr_b16 v[218:219], v117 offset:52800
	s_waitcnt lgkmcnt(14)
	v_mfma_f32_16x16x32_bf16 v[72:75], v[168:171], v[160:163], v[72:75]
	ds_read_b64_tr_b16 v[220:221], v117 offset:50720
	ds_read_b64_tr_b16 v[224:225], v117 offset:50752
	ds_read_b64_tr_b16 v[228:229], v117 offset:50784
	ds_read_b64_tr_b16 v[222:223], v117 offset:52832
	ds_read_b64_tr_b16 v[226:227], v117 offset:52864
	ds_read_b64_tr_b16 v[230:231], v117 offset:52896
	s_waitcnt lgkmcnt(14)
	v_mfma_f32_16x16x32_bf16 v[76:79], v[172:175], v[160:163], v[76:79]
	s_waitcnt lgkmcnt(6)
	v_mfma_f32_16x16x32_bf16 v[72:75], v[216:219], v[180:183], v[72:75]
	s_waitcnt lgkmcnt(2)
	v_mfma_f32_16x16x32_bf16 v[76:79], v[220:223], v[180:183], v[76:79]
	v_mfma_f32_16x16x32_bf16 v[132:135], v[176:179], v[160:163], v[132:135]
	s_waitcnt vmcnt(15)
	s_nop 3
	v_pk_add_f32 v[72:73], v[40:41], v[72:73] op_sel_hi:[0,1]
	v_mul_f32_e32 v5, v72, v5
	v_mul_f32_e32 v17, v73, v17
	v_mfma_f32_16x16x32_bf16 v[52:55], v[184:187], v[160:163], v[52:55]
	v_add_f32_e64 v160, v40, v74
	v_add_f32_e64 v161, v40, v75
	v_cvt_pk_bf16_f32 v46, v5, v17
	v_lshlrev_b32_e32 v5, 16, v47
	v_and_b32_e32 v17, 0xffff0000, v47
	v_mul_f32_e32 v5, v160, v5
	v_mul_f32_e32 v17, v161, v17
	v_mfma_f32_16x16x32_bf16 v[72:75], v[172:175], v[188:191], v[144:147]
	v_cvt_pk_bf16_f32 v47, v5, v17
	v_lshlrev_b32_e32 v5, 16, v44
	v_and_b32_e32 v17, 0xffff0000, v44
	v_mfma_f32_16x16x32_bf16 v[144:147], v[176:179], v[188:191], v[148:151]
	global_store_dwordx2 v[34:35], v[46:47], off
	v_pk_add_f32 v[46:47], v[40:41], v[78:79] op_sel_hi:[0,1]
	s_nop 0
	v_pk_add_f32 v[148:149], v[40:41], v[76:77] op_sel_hi:[0,1]
	v_mul_f32_e32 v5, v148, v5
	v_mul_f32_e32 v17, v149, v17
	v_cvt_pk_bf16_f32 v148, v5, v17
	v_lshlrev_b32_e32 v5, 16, v45
	v_and_b32_e32 v17, 0xffff0000, v45
	v_mul_f32_e32 v5, v46, v5
	v_mul_f32_e32 v17, v47, v17
	s_waitcnt lgkmcnt(1)
	v_mfma_f32_16x16x32_bf16 v[44:47], v[224:227], v[180:183], v[132:135]
	v_cvt_pk_bf16_f32 v149, v5, v17
	v_lshlrev_b32_e32 v5, 16, v42
	v_and_b32_e32 v17, 0xffff0000, v42
	v_mfma_f32_16x16x32_bf16 v[68:71], v[168:171], v[188:191], v[68:71]
	global_store_dwordx2 v[34:35], v[148:149], off offset:32
	s_nop 3
	v_pk_add_f32 v[150:151], v[40:41], v[44:45] op_sel_hi:[0,1]
	v_mul_f32_e32 v5, v150, v5
	s_waitcnt lgkmcnt(0)
	v_mfma_f32_16x16x32_bf16 v[52:55], v[228:231], v[180:183], v[52:55]
	v_mul_f32_e32 v17, v151, v17
	v_pk_add_f32 v[148:149], v[40:41], v[46:47] op_sel_hi:[0,1]
	v_cvt_pk_bf16_f32 v42, v5, v17
	v_lshlrev_b32_e32 v5, 16, v43
	v_and_b32_e32 v17, 0xffff0000, v43
	v_mul_f32_e32 v5, v148, v5
	v_mul_f32_e32 v17, v149, v17
	v_cvt_pk_bf16_f32 v43, v5, v17
	global_store_dwordx2 v[34:35], v[42:43], off offset:64
	s_nop 0
	v_pk_add_f32 v[148:149], v[40:41], v[54:55] op_sel_hi:[0,1]
	v_pk_add_f32 v[52:53], v[40:41], v[52:53] op_sel_hi:[0,1]
	v_lshlrev_b32_e32 v5, 16, v38
	v_mfma_f32_16x16x32_bf16 v[40:43], v[176:179], v[208:211], v[60:63]
	v_and_b32_e32 v17, 0xffff0000, v38
	v_mul_f32_e32 v5, v52, v5
	v_mul_f32_e32 v17, v53, v17
	v_mfma_f32_16x16x32_bf16 v[60:63], v[216:219], v[196:199], v[68:71]
	v_cvt_pk_bf16_f32 v38, v5, v17
	v_lshlrev_b32_e32 v5, 16, v39
	v_and_b32_e32 v17, 0xffff0000, v39
	v_mul_f32_e32 v5, v148, v5
	v_mul_f32_e32 v17, v149, v17
	v_cvt_pk_bf16_f32 v39, v5, v17
	v_mfma_f32_16x16x32_bf16 v[52:55], v[184:187], v[208:211], v[64:67]
	global_store_dwordx2 v[34:35], v[38:39], off offset:96
	s_waitcnt vmcnt(18)
	s_nop 0
	v_pk_add_f32 v[38:39], v[28:29], v[60:61] op_sel_hi:[0,1]
	s_waitcnt vmcnt(17)
	v_lshlrev_b32_e32 v5, 16, v36
	v_mfma_f32_16x16x32_bf16 v[64:67], v[220:223], v[196:199], v[72:75]
	v_and_b32_e32 v17, 0xffff0000, v36
	v_mul_f32_e32 v5, v38, v5
	v_mul_f32_e32 v17, v39, v17
	v_pk_add_f32 v[34:35], v[28:29], v[62:63] op_sel_hi:[0,1]
	v_cvt_pk_bf16_f32 v38, v5, v17
	v_lshlrev_b32_e32 v5, 16, v37
	v_and_b32_e32 v17, 0xffff0000, v37
	v_mul_f32_e32 v5, v34, v5
	v_mul_f32_e32 v17, v35, v17
	v_mfma_f32_16x16x32_bf16 v[76:79], v[184:187], v[188:191], v[136:139]
	v_cvt_pk_bf16_f32 v39, v5, v17
	v_add_f32_e64 v64, v28, v64
	v_add_f32_e64 v65, v28, v65
	s_waitcnt vmcnt(16)
; __device__ __forceinline__ unsigned cvt_pk_bf16(float lo, float hi) { unsigned r; asm volatile("v_cvt_pk_bf16_f32 %0, %1, %2" : "=v"(r) : "v"(lo), "v"(hi)); return r; }
; __device__ __forceinline__ float bf_lo(unsigned w) { return __uint_as_float(w << 16); }
; __device__ __forceinline__ float bf_hi(unsigned w) { return __uint_as_float(w & 0xffff0000u); }
; __device__ __forceinline__ void mix_phase(const Params& p, LAS unsigned char* lds, int G, bool dry) {
;     ...
; #pragma unroll
;         for (int m = 0; m < 4; ++m) {
; #pragma unroll
;             for (int n = 0; n < 4; ++n) {
;                 const f32x4 a = acc[m][n] + bias[m]; const u32x2 u2 = ur[m][n];
;                 u32x2 w; w.x = cvt_pk_bf16(bf_lo(u2.x) * a[0], bf_hi(u2.x) * a[1]); w.y = cvt_pk_bf16(bf_lo(u2.y) * a[2], bf_hi(u2.y) * a[3]);
;                 if (!dry) *(u32x2*)(gup + (size_t)m * 16 * GW + 16 * n) = w;
;             }
;         }
;         if (tid == 0) misc[0] = nticket;
	v_lshlrev_b32_e32 v5, 16, v32
	v_mfma_f32_16x16x32_bf16 v[60:63], v[224:227], v[196:199], v[144:147]
	v_and_b32_e32 v17, 0xffff0000, v32
	v_mul_f32_e32 v5, v64, v5
	v_mul_f32_e32 v17, v65, v17
	global_store_dwordx2 v[22:23], v[38:39], off
	v_pk_add_f32 v[38:39], v[28:29], v[66:67] op_sel_hi:[0,1]
	v_cvt_pk_bf16_f32 v32, v5, v17
	v_lshlrev_b32_e32 v5, 16, v33
	v_and_b32_e32 v17, 0xffff0000, v33
	v_mul_f32_e32 v5, v38, v5
	v_mul_f32_e32 v17, v39, v17
	v_mfma_f32_16x16x32_bf16 v[136:139], v[168:171], v[200:203], v[140:143]
	v_cvt_pk_bf16_f32 v33, v5, v17
	s_waitcnt vmcnt(16)
	v_lshlrev_b32_e32 v5, 16, v30
	v_and_b32_e32 v17, 0xffff0000, v30
	v_mfma_f32_16x16x32_bf16 v[68:71], v[228:231], v[196:199], v[76:79]
	global_store_dwordx2 v[22:23], v[32:33], off offset:32
	v_pk_add_f32 v[32:33], v[28:29], v[62:63] op_sel_hi:[0,1]
	v_mfma_f32_16x16x32_bf16 v[38:41], v[224:227], v[212:215], v[40:43]
	s_nop 2
	v_add_f32_e64 v42, v28, v60
	v_add_f32_e64 v43, v28, v61
	v_mul_f32_e32 v5, v42, v5
	v_mul_f32_e32 v17, v43, v17
	v_cvt_pk_bf16_f32 v30, v5, v17
	v_lshlrev_b32_e32 v5, 16, v31
	v_and_b32_e32 v17, 0xffff0000, v31
	v_mul_f32_e32 v5, v32, v5
	v_mul_f32_e32 v17, v33, v17
	v_cvt_pk_bf16_f32 v31, v5, v17
	v_mfma_f32_16x16x32_bf16 v[140:143], v[172:175], v[200:203], v[152:155]
	global_store_dwordx2 v[22:23], v[30:31], off offset:64
	v_pk_add_f32 v[30:31], v[28:29], v[70:71] op_sel_hi:[0,1]
	v_pk_add_f32 v[28:29], v[28:29], v[68:69] op_sel_hi:[0,1]
	v_mfma_f32_16x16x32_bf16 v[72:75], v[216:219], v[204:207], v[136:139]
	s_waitcnt vmcnt(17)
	v_lshlrev_b32_e32 v5, 16, v26
	v_and_b32_e32 v17, 0xffff0000, v26
	v_mul_f32_e32 v5, v28, v5
	v_mul_f32_e32 v17, v29, v17
	v_cvt_pk_bf16_f32 v26, v5, v17
	v_lshlrev_b32_e32 v5, 16, v27
	v_and_b32_e32 v17, 0xffff0000, v27
	v_mul_f32_e32 v5, v30, v5
	v_mul_f32_e32 v17, v31, v17
	v_cvt_pk_bf16_f32 v27, v5, v17
	v_mfma_f32_16x16x32_bf16 v[132:135], v[176:179], v[200:203], v[164:167]
	global_store_dwordx2 v[22:23], v[26:27], off offset:96
	s_waitcnt vmcnt(17)
	v_pk_add_f32 v[22:23], v[16:17], v[74:75] op_sel_hi:[0,1]
	v_pk_add_f32 v[26:27], v[16:17], v[72:73] op_sel_hi:[0,1]
	v_mfma_f32_16x16x32_bf16 v[34:37], v[220:223], v[204:207], v[140:143]
	s_waitcnt vmcnt(16)
	v_lshlrev_b32_e32 v5, 16, v24
	v_and_b32_e32 v17, 0xffff0000, v24
	v_mul_f32_e32 v5, v26, v5
	v_mul_f32_e32 v17, v27, v17
	v_cvt_pk_bf16_f32 v24, v5, v17
	v_lshlrev_b32_e32 v5, 16, v25
	v_and_b32_e32 v17, 0xffff0000, v25
	v_mul_f32_e32 v5, v22, v5
	v_mul_f32_e32 v17, v23, v17
	v_cvt_pk_bf16_f32 v25, v5, v17
	v_mfma_f32_16x16x32_bf16 v[44:47], v[184:187], v[200:203], v[156:159]
	global_store_dwordx2 v[10:11], v[24:25], off
	v_pk_add_f32 v[22:23], v[16:17], v[36:37] op_sel_hi:[0,1]
	v_pk_add_f32 v[24:25], v[16:17], v[34:35] op_sel_hi:[0,1]
	v_mfma_f32_16x16x32_bf16 v[76:79], v[224:227], v[204:207], v[132:135]
	s_waitcnt vmcnt(16)
	v_lshlrev_b32_e32 v5, 16, v20
	v_and_b32_e32 v17, 0xffff0000, v20
	v_mul_f32_e32 v5, v24, v5
	v_mul_f32_e32 v17, v25, v17
	v_cvt_pk_bf16_f32 v20, v5, v17
	v_lshlrev_b32_e32 v5, 16, v21
	v_and_b32_e32 v17, 0xffff0000, v21
	v_mul_f32_e32 v5, v22, v5
	v_mul_f32_e32 v17, v23, v17
	v_cvt_pk_bf16_f32 v21, v5, v17
	v_mfma_f32_16x16x32_bf16 v[44:47], v[228:231], v[204:207], v[44:47]
	global_store_dwordx2 v[10:11], v[20:21], off offset:32
	v_pk_add_f32 v[20:21], v[16:17], v[78:79] op_sel_hi:[0,1]
	v_pk_add_f32 v[22:23], v[16:17], v[76:77] op_sel_hi:[0,1]
	s_waitcnt vmcnt(16)
	v_lshlrev_b32_e32 v5, 16, v18
	v_and_b32_e32 v17, 0xffff0000, v18
	v_mfma_f32_16x16x32_bf16 v[48:51], v[168:171], v[208:211], v[48:51]
	v_mul_f32_e32 v5, v22, v5
	v_mul_f32_e32 v17, v23, v17
	v_cvt_pk_bf16_f32 v18, v5, v17
	v_lshlrev_b32_e32 v5, 16, v19
	v_and_b32_e32 v17, 0xffff0000, v19
	v_mul_f32_e32 v5, v20, v5
	v_mul_f32_e32 v17, v21, v17
	v_cvt_pk_bf16_f32 v19, v5, v17
	global_store_dwordx2 v[10:11], v[18:19], off offset:64
	v_pk_add_f32 v[18:19], v[16:17], v[46:47] op_sel_hi:[0,1]
	v_pk_add_f32 v[16:17], v[16:17], v[44:45] op_sel_hi:[0,1]
	s_waitcnt vmcnt(16)
	v_lshlrev_b32_e32 v5, 16, v14
	v_and_b32_e32 v14, 0xffff0000, v14
	v_mfma_f32_16x16x32_bf16 v[48:51], v[216:219], v[212:215], v[48:51]
	v_mul_f32_e32 v5, v16, v5
	v_mul_f32_e32 v14, v17, v14
	v_cvt_pk_bf16_f32 v14, v5, v14
	v_mfma_f32_16x16x32_bf16 v[56:59], v[172:175], v[208:211], v[56:59]
	v_lshlrev_b32_e32 v5, 16, v15
	v_and_b32_e32 v15, 0xffff0000, v15
	v_mul_f32_e32 v15, v19, v15
	v_mul_f32_e32 v5, v18, v5
	v_cvt_pk_bf16_f32 v15, v5, v15
	global_store_dwordx2 v[10:11], v[14:15], off offset:96
	s_waitcnt vmcnt(16)
	v_pk_add_f32 v[10:11], v[4:5], v[50:51] op_sel_hi:[0,1]
	v_pk_add_f32 v[14:15], v[4:5], v[48:49] op_sel_hi:[0,1]
	s_waitcnt vmcnt(15)
	v_lshlrev_b32_e32 v5, 16, v12
	v_and_b32_e32 v12, 0xffff0000, v12
	v_mfma_f32_16x16x32_bf16 v[56:59], v[220:223], v[212:215], v[56:59]
	v_mul_f32_e32 v5, v14, v5
	v_mul_f32_e32 v12, v15, v12
	v_cvt_pk_bf16_f32 v12, v5, v12
	v_lshlrev_b32_e32 v5, 16, v13
	v_mul_f32_e32 v5, v10, v5
	v_and_b32_e32 v10, 0xffff0000, v13
	v_mul_f32_e32 v10, v11, v10
	v_cvt_pk_bf16_f32 v13, v5, v10
	global_store_dwordx2 v[0:1], v[12:13], off
	s_nop 0
	v_pk_add_f32 v[10:11], v[4:5], v[58:59] op_sel_hi:[0,1]
	v_pk_add_f32 v[12:13], v[4:5], v[56:57] op_sel_hi:[0,1]
	s_waitcnt vmcnt(15)
	v_lshlrev_b32_e32 v5, 16, v8
	v_and_b32_e32 v8, 0xffff0000, v8
	v_mul_f32_e32 v5, v12, v5
	v_mul_f32_e32 v8, v13, v8
	v_cvt_pk_bf16_f32 v8, v5, v8
	v_lshlrev_b32_e32 v5, 16, v9
	v_and_b32_e32 v9, 0xffff0000, v9
	v_mul_f32_e32 v9, v11, v9
	v_mul_f32_e32 v5, v10, v5
	v_cvt_pk_bf16_f32 v9, v5, v9
	global_store_dwordx2 v[0:1], v[8:9], off offset:32
	v_pk_add_f32 v[8:9], v[4:5], v[40:41] op_sel_hi:[0,1]
	v_pk_add_f32 v[10:11], v[4:5], v[38:39] op_sel_hi:[0,1]
	s_waitcnt vmcnt(15)
	v_lshlrev_b32_e32 v5, 16, v6
	v_and_b32_e32 v6, 0xffff0000, v6
	v_mfma_f32_16x16x32_bf16 v[52:55], v[228:231], v[212:215], v[52:55]
	v_mul_f32_e32 v5, v10, v5
	v_mul_f32_e32 v6, v11, v6
	v_cvt_pk_bf16_f32 v6, v5, v6
	v_lshlrev_b32_e32 v5, 16, v7
	v_and_b32_e32 v7, 0xffff0000, v7
	v_mul_f32_e32 v7, v9, v7
	v_mul_f32_e32 v5, v8, v5
	v_cvt_pk_bf16_f32 v7, v5, v7
	global_store_dwordx2 v[0:1], v[6:7], off offset:64
	s_nop 0
	v_pk_add_f32 v[6:7], v[4:5], v[54:55] op_sel_hi:[0,1]
	v_pk_add_f32 v[4:5], v[4:5], v[52:53] op_sel_hi:[0,1]
	s_waitcnt vmcnt(15)
	v_lshlrev_b32_e32 v8, 16, v2
	v_and_b32_e32 v2, 0xffff0000, v2
	v_mul_f32_e32 v4, v4, v8
	v_mul_f32_e32 v2, v5, v2
	v_cvt_pk_bf16_f32 v2, v4, v2
	v_lshlrev_b32_e32 v4, 16, v3
	v_and_b32_e32 v3, 0xffff0000, v3
	v_mul_f32_e32 v3, v7, v3
	v_mul_f32_e32 v4, v6, v4
	v_cvt_pk_bf16_f32 v3, v4, v3
	global_store_dwordx2 v[0:1], v[2:3], off offset:96
	s_and_saveexec_b64 s[10:11], s[12:13]
	s_xor_b64 s[10:11], exec, s[10:11]
	s_cbranch_execz .LBB0_157
	v_mov_b32_e32 v0, s33
	ds_write_b32 v0, v235
	s_branch .LBB0_157
; __device__ __forceinline__ void p0_prologue(const Params& p, LAS unsigned char* lds, int G) {
;     ...
;     for (int it = gw; it < I1 + I2 + I3 + I4; it += NGW) {
;         int r = it;
;         if (r < I1) { p0_transpose_item(p.w1, DM, N1, W1T, nullptr, scr, r, lane, true); continue; } r -= I1;
;         if (r < I2) { p0_transpose_item(p.w2, GW, DM, W2T, nullptr, scr, r, lane, false); continue; } r -= I2;
;         if (r < I3) { p0_transpose_item(p.w3, DM, N3, W3T, p.norm_g + DM, scr, r, lane, false); continue; } r -= I3;
;         p0_transpose_item(p.w4, DM, DM, W4T, nullptr, scr, r, lane, false);
;     }
.LBB0_216:
	s_cmp_lt_u32 s94, 48
	s_cbranch_scc1 .Ltr_skip
	s_waitcnt lgkmcnt(0)
	s_barrier
	v_writelane_b32 v236, s0, 8
	s_nop 1
	v_writelane_b32 v236, s1, 9
	s_nop 1
	v_writelane_b32 v236, s2, 10
	s_nop 1
	v_writelane_b32 v236, s3, 11
	s_nop 1
	v_writelane_b32 v236, s4, 12
	s_nop 1
	v_writelane_b32 v236, s5, 13
	s_nop 1
	v_writelane_b32 v236, s6, 14
	s_nop 1
	v_writelane_b32 v236, s7, 15
	s_nop 1
	v_writelane_b32 v236, s8, 16
	s_nop 1
	v_writelane_b32 v236, s9, 17
	s_nop 1
	v_writelane_b32 v236, s10, 18
	s_nop 1
	v_writelane_b32 v236, s11, 19
	s_nop 1
	v_writelane_b32 v236, s12, 20
	s_nop 1
	v_writelane_b32 v236, s13, 21
	s_nop 1
	v_writelane_b32 v236, s14, 22
	s_nop 1
	v_writelane_b32 v236, s15, 23
	s_nop 1
	v_writelane_b32 v236, s16, 24
	s_nop 1
	v_writelane_b32 v236, s17, 25
	s_nop 1
	v_writelane_b32 v236, s18, 26
	s_nop 1
	v_writelane_b32 v236, s19, 27
	s_nop 1
	v_writelane_b32 v236, s20, 28
	s_nop 1
	v_writelane_b32 v236, s21, 29
	s_nop 1
	v_writelane_b32 v236, s22, 30
	s_nop 1
	v_writelane_b32 v236, s23, 31
	s_nop 1
	v_writelane_b32 v236, s24, 32
	s_nop 1
	v_writelane_b32 v236, s25, 33
	s_nop 1
	v_writelane_b32 v236, s26, 34
	s_nop 1
	v_writelane_b32 v236, s27, 35
	s_nop 1
	v_writelane_b32 v236, s28, 36
	s_nop 1
	v_writelane_b32 v236, s29, 37
	s_nop 1
	v_writelane_b32 v236, s30, 38
	s_nop 1
	v_writelane_b32 v236, s31, 39
	s_nop 1
	v_writelane_b32 v236, s32, 40
	s_nop 1
	v_writelane_b32 v236, s33, 41
	s_nop 1
	v_writelane_b32 v236, s34, 42
	s_nop 1
	v_writelane_b32 v236, s35, 43
	s_nop 1
	v_writelane_b32 v236, s36, 44
	s_nop 1
	v_writelane_b32 v236, s37, 45
	s_nop 1
	v_writelane_b32 v236, s38, 46
	s_nop 1
	v_writelane_b32 v236, s39, 47
	s_nop 1
	v_writelane_b32 v236, s40, 48
	s_nop 1
	v_writelane_b32 v236, s41, 49
	s_nop 1
	v_writelane_b32 v236, s42, 50
	s_nop 1
	v_writelane_b32 v236, s43, 51
	s_nop 1
	v_writelane_b32 v236, s44, 52
	s_nop 1
	v_writelane_b32 v236, s45, 53
	s_nop 1
	v_writelane_b32 v236, s46, 54
	s_nop 1
	v_writelane_b32 v236, s47, 55
	s_nop 1
	v_writelane_b32 v236, s48, 56
	s_nop 1
	v_writelane_b32 v236, s49, 57
	s_nop 1
	v_writelane_b32 v236, s50, 58
	s_nop 1
	v_writelane_b32 v236, s51, 59
	s_nop 1
	v_writelane_b32 v236, s96, 60
	s_nop 1
	v_writelane_b32 v236, s97, 61
	s_nop 1
	v_mov_b32_e32 v237, v3
	v_mov_b32_e32 v238, v37
	v_mov_b32_e32 v37, v194
	v_ashrrev_i32_e32 v1, 6, v37
	v_and_b32_e32 v36, 63, v37
	v_lshlrev_b32_e32 v12, 3, v36
	s_sub_u32 s0, s94, 48
	s_lshl_b32 s0, s0, 3
	s_add_u32 s0, s0, 0x3000
	v_add_u32_e32 v10, s0, v1
	s_movk_i32 s96, 0x680
	s_mov_b32 s97, 0
	s_add_u32 s14, s86, 0x3400000
	s_addc_u32 s15, s87, 0
	s_add_u32 s22, s86, 0x4400000
	s_addc_u32 s23, s87, 0
	v_readlane_b32 s78, v236, 0
	v_readlane_b32 s79, v236, 1
	v_readlane_b32 s80, v236, 2
	v_readlane_b32 s81, v236, 3
	v_readlane_b32 s82, v236, 4
	v_readlane_b32 s83, v236, 5
	s_mov_b32 s95, 1
	s_mov_b64 s[0:1], exec
	s_nop 4
	s_branch .Ltr_entry
.Ltr_ret:
	s_mov_b32 s95, 0
	v_mov_b32_e32 v3, v237
	v_mov_b32_e32 v37, v238
	s_nop 1
	v_readlane_b32 s0, v236, 8
	v_readlane_b32 s1, v236, 9
	v_readlane_b32 s2, v236, 10
	v_readlane_b32 s3, v236, 11
	v_readlane_b32 s4, v236, 12
	v_readlane_b32 s5, v236, 13
	v_readlane_b32 s6, v236, 14
	v_readlane_b32 s7, v236, 15
	v_readlane_b32 s8, v236, 16
	v_readlane_b32 s9, v236, 17
	v_readlane_b32 s10, v236, 18
	v_readlane_b32 s11, v236, 19
	v_readlane_b32 s12, v236, 20
	v_readlane_b32 s13, v236, 21
	v_readlane_b32 s14, v236, 22
	v_readlane_b32 s15, v236, 23
	v_readlane_b32 s16, v236, 24
	v_readlane_b32 s17, v236, 25
	v_readlane_b32 s18, v236, 26
	v_readlane_b32 s19, v236, 27
	v_readlane_b32 s20, v236, 28
	v_readlane_b32 s21, v236, 29
	v_readlane_b32 s22, v236, 30
	v_readlane_b32 s23, v236, 31
	v_readlane_b32 s24, v236, 32
	v_readlane_b32 s25, v236, 33
	v_readlane_b32 s26, v236, 34
	v_readlane_b32 s27, v236, 35
	v_readlane_b32 s28, v236, 36
	v_readlane_b32 s29, v236, 37
	v_readlane_b32 s30, v236, 38
	v_readlane_b32 s31, v236, 39
	v_readlane_b32 s32, v236, 40
	v_readlane_b32 s33, v236, 41
	v_readlane_b32 s34, v236, 42
	v_readlane_b32 s35, v236, 43
	v_readlane_b32 s36, v236, 44
	v_readlane_b32 s37, v236, 45
	v_readlane_b32 s38, v236, 46
	v_readlane_b32 s39, v236, 47
	v_readlane_b32 s40, v236, 48
	v_readlane_b32 s41, v236, 49
	v_readlane_b32 s42, v236, 50
	v_readlane_b32 s43, v236, 51
	v_readlane_b32 s44, v236, 52
	v_readlane_b32 s45, v236, 53
	v_readlane_b32 s46, v236, 54
	v_readlane_b32 s47, v236, 55
	v_readlane_b32 s48, v236, 56
	v_readlane_b32 s49, v236, 57
	v_readlane_b32 s50, v236, 58
	v_readlane_b32 s51, v236, 59
	v_readlane_b32 s96, v236, 60
	v_readlane_b32 s97, v236, 61
	s_nop 4

; __device__ __forceinline__ unsigned cvt_pk_bf16(float lo, float hi) { unsigned r; asm volatile("v_cvt_pk_bf16_f32 %0, %1, %2" : "=v"(r) : "v"(lo), "v"(hi)); return r; }
; __device__ __forceinline__ void st_wt8(void* ptr, u32x2 v) { asm volatile("global_store_dwordx2 %0, %1, off sc1" :: "v"(ptr), "v"(v) : "memory"); }
; __device__ __forceinline__ void st_wt4(void* ptr, unsigned v) { asm volatile("global_store_dword %0, %1, off sc1" :: "v"(ptr), "v"(v) : "memory"); }
;     __device__ __forceinline__ void operator()(const f32x4 (&acc)[2][2][4][2], const pg8::Unit& u, int wr, int wc, int fr, int fq) const {
;         const int row0 = u.pm * 256 + wr * 64 + fr, col0 = u.pn * 256 + wc * 32 + 4 * fq;
; #pragma unroll
;         for (int ai = 0; ai < 2; ++ai)
; #pragma unroll
;             for (int m = 0; m < 4; ++m) {
;                 const int row = row0 + ai * 128 + m * 16;
;                 float* orow = oy + (size_t)row * DM + col0;
;                 const float* xr = FIRST ? ((row < MP ? xp + (size_t)row * DM : xs + (size_t)(row - MP) * DM) + col0) : orow;
;                 float q = 0.f;
; #pragma unroll
;                 for (int bj = 0; bj < 2; ++bj)
; #pragma unroll
;                     for (int n = 0; n < 2; ++n) {
;                         const f32x4 xv = *(const f32x4*)(xr + bj * 128 + n * 16);
;                         const f32x4 o = xv + acc[ai][bj][m][n];
;                         *(f32x4*)(orow + bj * 128 + n * 16) = o;
;                         q += (o[0] * o[0] + o[1] * o[1]) + (o[2] * o[2] + o[3] * o[3]);
;                         if (FIRST) { u32x2 w; w.x = cvt_pk_bf16(o[0], o[1]); w.y = cvt_pk_bf16(o[2], o[3]); st_wt8(xb + (size_t)row * DM + col0 + bj * 128 + n * 16, w); }
;                     }
;                 q += __shfl_xor(q, 16); q += __shfl_xor(q, 32);
;                 if (fq == 0) { if (FIRST) st_wt4(ss + (size_t)row * 32 + u.pn * 4 + wc, __float_as_uint(q)); else ss[(size_t)row * 32 + u.pn * 4 + wc] = q; }
;             }
.LBB0_299:
	v_lshl_add_u32 v144, s63, 8, v148
	v_ashrrev_i32_e32 v145, 31, v144
	v_readlane_b32 s68, v234, 3
	v_add_u32_e32 v132, 0xffffe000, v144
	v_lshl_or_b32 v140, s10, 8, v150
	v_lshlrev_b64 v[156:157], 13, v[144:145]
	v_readlane_b32 s69, v234, 4
	v_readlane_b32 s70, v234, 5
	v_readlane_b32 s71, v234, 6
	v_lshlrev_b64 v[154:155], 13, v[132:133]
	v_ashrrev_i32_e32 v141, 31, v140
	v_lshl_add_u64 v[152:153], s[68:69], 0, v[156:157]
	v_lshl_add_u64 v[154:155], s[70:71], 0, v[154:155]
	v_cmp_gt_i32_e32 vcc, s54, v144
	v_lshlrev_b64 v[142:143], 2, v[140:141]
	v_lshlrev_b64 v[160:161], 12, v[144:145]
	v_cndmask_b32_e32 v153, v155, v153, vcc
	v_cndmask_b32_e32 v152, v154, v152, vcc
	v_lshl_add_u64 v[158:159], v[152:153], 0, v[142:143]
	v_mov_b32_e32 v232, v158
	v_mov_b32_e32 v233, v159
	global_load_dwordx4 v[164:167], v[232:233], off
	global_load_dwordx4 v[168:171], v[232:233], off offset:64
	global_load_dwordx4 v[172:175], v[232:233], off offset:512
	global_load_dwordx4 v[176:179], v[232:233], off offset:576
	s_mov_b64 s[98:99], 0x20000
	v_lshl_add_u64 v[192:193], v[232:233], 0, s[98:99]
	global_load_dwordx4 v[180:183], v[192:193], off
	global_load_dwordx4 v[184:187], v[192:193], off offset:64
	global_load_dwordx4 v[188:191], v[192:193], off offset:512
	global_load_dwordx4 v[196:199], v[192:193], off offset:576
	s_mov_b64 s[98:99], 0x40000
	v_lshl_add_u64 v[192:193], v[232:233], 0, s[98:99]
	global_load_dwordx4 v[200:203], v[192:193], off
	global_load_dwordx4 v[204:207], v[192:193], off offset:64
	global_load_dwordx4 v[208:211], v[192:193], off offset:512
	global_load_dwordx4 v[212:215], v[192:193], off offset:576
	s_mov_b64 s[98:99], 0x60000
	v_lshl_add_u64 v[192:193], v[232:233], 0, s[98:99]
	global_load_dwordx4 v[216:219], v[192:193], off
	global_load_dwordx4 v[220:223], v[192:193], off offset:64
	global_load_dwordx4 v[224:227], v[192:193], off offset:512
	global_load_dwordx4 v[228:231], v[192:193], off offset:576
	s_waitcnt vmcnt(0)
	v_mov_b32_e32 v152, v164
	v_mov_b32_e32 v153, v165
	v_mov_b32_e32 v154, v166
	v_mov_b32_e32 v155, v167
	v_lshl_add_u64 v[156:157], s[84:85], 0, v[156:157]
	v_lshl_add_u64 v[160:161], s[20:21], 0, v[160:161]
	v_lshl_add_u64 v[162:163], v[156:157], 0, v[142:143]
	v_lshl_add_u64 v[160:161], v[140:141], 1, v[160:161]
	v_lshl_add_u64 v[156:157], v[160:161], 0, 32
	s_lshl_b32 s42, s10, 2
	s_ashr_i32 s43, s42, 31
	v_readlane_b32 s72, v234, 7
	v_readlane_b32 s73, v234, 8
	v_readlane_b32 s74, v234, 9
	v_readlane_b32 s75, v234, 10
	v_readlane_b32 s76, v234, 11
	v_readlane_b32 s77, v234, 12
	v_readlane_b32 s78, v234, 13
	v_readlane_b32 s79, v234, 14
	v_readlane_b32 s80, v234, 15
	v_readlane_b32 s81, v234, 16
	v_readlane_b32 s82, v234, 17
	v_readlane_b32 s83, v234, 18
	v_pk_add_f32 v[126:127], v[126:127], v[154:155]
	v_pk_add_f32 v[124:125], v[124:125], v[152:153]
	global_store_dwordx4 v[162:163], v[124:127], off
	v_cvt_pk_bf16_f32 v152, v124, v125
	v_cvt_pk_bf16_f32 v153, v126, v127
	s_nop 0
	global_store_dwordx2 v[160:161], v[152:153], off sc1
	v_mov_b32_e32 v152, v168
	v_mov_b32_e32 v153, v169
	v_mov_b32_e32 v154, v170
	v_mov_b32_e32 v155, v171
	v_pk_add_f32 v[122:123], v[122:123], v[154:155]
	v_pk_add_f32 v[120:121], v[120:121], v[152:153]
	global_store_dwordx4 v[162:163], v[120:123], off offset:64
	v_cvt_pk_bf16_f32 v152, v120, v121
	v_cvt_pk_bf16_f32 v153, v122, v123
	s_nop 0
	global_store_dwordx2 v[156:157], v[152:153], off sc1
	v_mov_b32_e32 v152, v172
	v_mov_b32_e32 v153, v173
	v_mov_b32_e32 v154, v174
	v_mov_b32_e32 v155, v175
	v_lshl_add_u64 v[156:157], v[160:161], 0, s[28:29]
	v_pk_add_f32 v[154:155], v[118:119], v[154:155]
	v_pk_add_f32 v[152:153], v[116:117], v[152:153]
	global_store_dwordx4 v[162:163], v[152:155], off offset:512
	v_cvt_pk_bf16_f32 v116, v152, v153
	v_cvt_pk_bf16_f32 v117, v154, v155
	v_xor_b32_e32 v118, 32, v195
	global_store_dwordx2 v[156:157], v[116:117], off sc1
	v_mov_b32_e32 v156, v176
	v_mov_b32_e32 v157, v177
	v_mov_b32_e32 v158, v178
	v_mov_b32_e32 v159, v179
	v_and_b32_e32 v117, 64, v195
	v_xor_b32_e32 v116, 16, v195
	v_add_u32_e32 v117, 64, v117
	v_cmp_lt_i32_e32 vcc, v116, v117
	v_mul_f32_e32 v119, v127, v127
	v_fmac_f32_e32 v119, v126, v126
	v_cndmask_b32_e32 v116, v195, v116, vcc
	v_cmp_lt_i32_e32 vcc, v118, v117
	v_lshlrev_b32_e32 v116, 2, v116
	v_pk_add_f32 v[114:115], v[114:115], v[158:159]
	v_cndmask_b32_e32 v117, v195, v118, vcc
	v_mul_f32_e32 v118, v125, v125
	v_fmac_f32_e32 v118, v124, v124
	v_add_f32_e32 v118, v118, v119
	v_mul_f32_e32 v119, v121, v121
	v_mul_f32_e32 v121, v123, v123
	v_fmac_f32_e32 v119, v120, v120
	v_fmac_f32_e32 v121, v122, v122
	v_add_f32_e32 v119, v119, v121
	v_add_f32_e32 v118, v118, v119
	v_mul_f32_e32 v119, v153, v153
	v_mul_f32_e32 v120, v155, v155
	v_fmac_f32_e32 v119, v152, v152
	v_fmac_f32_e32 v120, v154, v154
	v_add_f32_e32 v119, v119, v120
	v_pk_add_f32 v[112:113], v[112:113], v[156:157]
	v_add_f32_e32 v118, v118, v119
	v_mul_f32_e32 v119, v113, v113
	v_mul_f32_e32 v120, v115, v115
	v_fmac_f32_e32 v119, v112, v112
	v_fmac_f32_e32 v120, v114, v114
	v_add_f32_e32 v119, v119, v120
	v_add_f32_e32 v122, v118, v119
	ds_bpermute_b32 v123, v116, v122
	global_store_dwordx4 v[162:163], v[112:115], off offset:576
	v_cvt_pk_bf16_f32 v120, v112, v113
	v_cvt_pk_bf16_f32 v121, v114, v115
	v_lshl_add_u64 v[118:119], v[160:161], 0, s[30:31]
	global_store_dwordx2 v[118:119], v[120:121], off sc1
	s_waitcnt lgkmcnt(0)
	v_add_f32_e32 v112, v122, v123
	v_lshlrev_b32_e32 v114, 2, v117
	ds_bpermute_b32 v113, v114, v112
	s_and_saveexec_b64 s[44:45], s[4:5]
	s_cbranch_execz .LBB0_301
	s_waitcnt lgkmcnt(0)
	v_add_f32_e32 v115, v112, v113
	v_lshlrev_b64 v[112:113], 7, v[144:145]
	v_lshl_add_u64 v[112:113], s[2:3], 0, v[112:113]
	v_lshl_add_u64 v[112:113], s[42:43], 2, v[112:113]
	s_lshl_b32 s10, s55, 2
	v_lshl_add_u64 v[112:113], v[112:113], 0, s[10:11]
	global_store_dword v[112:113], v115, off sc1
; __device__ __forceinline__ unsigned cvt_pk_bf16(float lo, float hi) { unsigned r; asm volatile("v_cvt_pk_bf16_f32 %0, %1, %2" : "=v"(r) : "v"(lo), "v"(hi)); return r; }
; __device__ __forceinline__ void st_wt8(void* ptr, u32x2 v) { asm volatile("global_store_dwordx2 %0, %1, off sc1" :: "v"(ptr), "v"(v) : "memory"); }
; __device__ __forceinline__ void st_wt4(void* ptr, unsigned v) { asm volatile("global_store_dword %0, %1, off sc1" :: "v"(ptr), "v"(v) : "memory"); }
;     __device__ __forceinline__ void operator()(const f32x4 (&acc)[2][2][4][2], const pg8::Unit& u, int wr, int wc, int fr, int fq) const {
;     ...
;         for (int ai = 0; ai < 2; ++ai)
; #pragma unroll
;             for (int m = 0; m < 4; ++m) {
;                 const int row = row0 + ai * 128 + m * 16;
;                 float* orow = oy + (size_t)row * DM + col0;
;                 const float* xr = FIRST ? ((row < MP ? xp + (size_t)row * DM : xs + (size_t)(row - MP) * DM) + col0) : orow;
;                 float q = 0.f;
; #pragma unroll
;                 for (int bj = 0; bj < 2; ++bj)
; #pragma unroll
;                     for (int n = 0; n < 2; ++n) {
;                         const f32x4 xv = *(const f32x4*)(xr + bj * 128 + n * 16);
;                         const f32x4 o = xv + acc[ai][bj][m][n];
;                         *(f32x4*)(orow + bj * 128 + n * 16) = o;
;                         q += (o[0] * o[0] + o[1] * o[1]) + (o[2] * o[2] + o[3] * o[3]);
;                         if (FIRST) { u32x2 w; w.x = cvt_pk_bf16(o[0], o[1]); w.y = cvt_pk_bf16(o[2], o[3]); st_wt8(xb + (size_t)row * DM + col0 + bj * 128 + n * 16, w); }
;                     }
;                 q += __shfl_xor(q, 16); q += __shfl_xor(q, 32);
;                 if (fq == 0) { if (FIRST) st_wt4(ss + (size_t)row * 32 + u.pn * 4 + wc, __float_as_uint(q)); else ss[(size_t)row * 32 + u.pn * 4 + wc] = q; }
.LBB0_301:
	s_or_b64 exec, exec, s[44:45]
	v_or_b32_e32 v112, 16, v144
	s_waitcnt lgkmcnt(0)
	v_ashrrev_i32_e32 v113, 31, v112
	v_readlane_b32 s68, v234, 3
	v_add_u32_e32 v132, 0xffffe010, v144
	v_lshlrev_b64 v[122:123], 13, v[112:113]
	v_readlane_b32 s69, v234, 4
	v_readlane_b32 s70, v234, 5
	v_readlane_b32 s71, v234, 6
	v_lshlrev_b64 v[120:121], 13, v[132:133]
	v_lshl_add_u64 v[118:119], s[68:69], 0, v[122:123]
	v_lshl_add_u64 v[120:121], s[70:71], 0, v[120:121]
	v_cmp_gt_i32_e32 vcc, s54, v112
	v_lshlrev_b64 v[126:127], 12, v[112:113]
	v_lshl_add_u64 v[122:123], s[84:85], 0, v[122:123]
	v_cndmask_b32_e32 v119, v121, v119, vcc
	v_cndmask_b32_e32 v118, v120, v118, vcc
	v_lshl_add_u64 v[124:125], v[118:119], 0, v[142:143]
	v_mov_b32_e32 v118, v180
	v_mov_b32_e32 v119, v181
	v_mov_b32_e32 v120, v182
	v_mov_b32_e32 v121, v183
	v_lshl_add_u64 v[126:127], s[20:21], 0, v[126:127]
	v_lshl_add_u64 v[122:123], v[122:123], 0, v[142:143]
	v_lshl_add_u64 v[126:127], v[140:141], 1, v[126:127]
	v_lshl_add_u64 v[152:153], v[126:127], 0, 32
	v_readlane_b32 s72, v234, 7
	v_readlane_b32 s73, v234, 8
	v_readlane_b32 s74, v234, 9
	v_readlane_b32 s75, v234, 10
	v_readlane_b32 s76, v234, 11
	v_readlane_b32 s77, v234, 12
	v_readlane_b32 s78, v234, 13
	v_readlane_b32 s79, v234, 14
	v_readlane_b32 s80, v234, 15
	v_readlane_b32 s81, v234, 16
	v_readlane_b32 s82, v234, 17
	v_readlane_b32 s83, v234, 18
	v_pk_add_f32 v[110:111], v[110:111], v[120:121]
	v_pk_add_f32 v[108:109], v[108:109], v[118:119]
	global_store_dwordx4 v[122:123], v[108:111], off
	v_cvt_pk_bf16_f32 v118, v108, v109
	v_cvt_pk_bf16_f32 v119, v110, v111
	s_nop 0
	global_store_dwordx2 v[126:127], v[118:119], off sc1
	v_mov_b32_e32 v118, v184
	v_mov_b32_e32 v119, v185
	v_mov_b32_e32 v120, v186
	v_mov_b32_e32 v121, v187
	v_mul_f32_e32 v109, v109, v109
	v_mul_f32_e32 v111, v111, v111
	v_fmac_f32_e32 v109, v108, v108
	v_fmac_f32_e32 v111, v110, v110
	v_add_f32_e32 v108, v109, v111
	v_pk_add_f32 v[106:107], v[106:107], v[120:121]
	v_pk_add_f32 v[104:105], v[104:105], v[118:119]
	global_store_dwordx4 v[122:123], v[104:107], off offset:64
	v_cvt_pk_bf16_f32 v118, v104, v105
	v_cvt_pk_bf16_f32 v119, v106, v107
	s_nop 0
	global_store_dwordx2 v[152:153], v[118:119], off sc1
	v_mov_b32_e32 v118, v188
	v_mov_b32_e32 v119, v189
	v_mov_b32_e32 v120, v190
	v_mov_b32_e32 v121, v191
	v_lshl_add_u64 v[152:153], v[126:127], 0, s[28:29]
	v_mul_f32_e32 v105, v105, v105
	v_mul_f32_e32 v107, v107, v107
	v_fmac_f32_e32 v105, v104, v104
	v_fmac_f32_e32 v107, v106, v106
	v_add_f32_e32 v104, v105, v107
	v_add_f32_e32 v104, v108, v104
	v_pk_add_f32 v[102:103], v[102:103], v[120:121]
	v_pk_add_f32 v[100:101], v[100:101], v[118:119]
	global_store_dwordx4 v[122:123], v[100:103], off offset:512
	v_cvt_pk_bf16_f32 v118, v100, v101
	v_cvt_pk_bf16_f32 v119, v102, v103
	s_nop 0
	global_store_dwordx2 v[152:153], v[118:119], off sc1
	v_mov_b32_e32 v118, v196
	v_mov_b32_e32 v119, v197
	v_mov_b32_e32 v120, v198
	v_mov_b32_e32 v121, v199
	v_mul_f32_e32 v101, v101, v101
	v_mul_f32_e32 v103, v103, v103
	v_fmac_f32_e32 v101, v100, v100
	v_fmac_f32_e32 v103, v102, v102
	v_add_f32_e32 v100, v101, v103
	v_add_f32_e32 v100, v104, v100
	v_pk_add_f32 v[98:99], v[98:99], v[120:121]
	v_pk_add_f32 v[96:97], v[96:97], v[118:119]
	v_mul_f32_e32 v102, v99, v99
	v_mul_f32_e32 v101, v97, v97
	v_fmac_f32_e32 v101, v96, v96
	v_fmac_f32_e32 v102, v98, v98
	v_add_f32_e32 v101, v101, v102
	v_add_f32_e32 v102, v100, v101
	ds_bpermute_b32 v103, v116, v102
	global_store_dwordx4 v[122:123], v[96:99], off offset:576
	v_cvt_pk_bf16_f32 v100, v96, v97
	v_cvt_pk_bf16_f32 v101, v98, v99
	s_waitcnt lgkmcnt(0)
	s_nop 0
	v_add_f32_e32 v96, v102, v103
	ds_bpermute_b32 v97, v114, v96
	v_lshl_add_u64 v[98:99], v[126:127], 0, s[30:31]
	global_store_dwordx2 v[98:99], v[100:101], off sc1
	s_and_saveexec_b64 s[44:45], s[4:5]
	s_cbranch_execz .LBB0_303
	s_waitcnt lgkmcnt(0)
	v_add_f32_e32 v98, v96, v97
	v_lshlrev_b64 v[96:97], 7, v[112:113]
	v_lshl_add_u64 v[96:97], s[2:3], 0, v[96:97]
	v_lshl_add_u64 v[96:97], s[42:43], 2, v[96:97]
	s_lshl_b32 s10, s55, 2
	v_lshl_add_u64 v[96:97], v[96:97], 0, s[10:11]
	global_store_dword v[96:97], v98, off sc1
.LBB0_303:
	s_or_b64 exec, exec, s[44:45]
	v_or_b32_e32 v96, 32, v144
	s_waitcnt lgkmcnt(0)
; __device__ __forceinline__ unsigned cvt_pk_bf16(float lo, float hi) { unsigned r; asm volatile("v_cvt_pk_bf16_f32 %0, %1, %2" : "=v"(r) : "v"(lo), "v"(hi)); return r; }
; __device__ __forceinline__ void st_wt8(void* ptr, u32x2 v) { asm volatile("global_store_dwordx2 %0, %1, off sc1" :: "v"(ptr), "v"(v) : "memory"); }
; __device__ __forceinline__ void st_wt4(void* ptr, unsigned v) { asm volatile("global_store_dword %0, %1, off sc1" :: "v"(ptr), "v"(v) : "memory"); }
;     __device__ __forceinline__ void operator()(const f32x4 (&acc)[2][2][4][2], const pg8::Unit& u, int wr, int wc, int fr, int fq) const {
;     ...
;         for (int ai = 0; ai < 2; ++ai)
; #pragma unroll
;             for (int m = 0; m < 4; ++m) {
;                 const int row = row0 + ai * 128 + m * 16;
;                 float* orow = oy + (size_t)row * DM + col0;
;                 const float* xr = FIRST ? ((row < MP ? xp + (size_t)row * DM : xs + (size_t)(row - MP) * DM) + col0) : orow;
;                 float q = 0.f;
; #pragma unroll
;                 for (int bj = 0; bj < 2; ++bj)
; #pragma unroll
;                     for (int n = 0; n < 2; ++n) {
;                         const f32x4 xv = *(const f32x4*)(xr + bj * 128 + n * 16);
;                         const f32x4 o = xv + acc[ai][bj][m][n];
;                         *(f32x4*)(orow + bj * 128 + n * 16) = o;
;                         q += (o[0] * o[0] + o[1] * o[1]) + (o[2] * o[2] + o[3] * o[3]);
;                         if (FIRST) { u32x2 w; w.x = cvt_pk_bf16(o[0], o[1]); w.y = cvt_pk_bf16(o[2], o[3]); st_wt8(xb + (size_t)row * DM + col0 + bj * 128 + n * 16, w); }
;                     }
;                 q += __shfl_xor(q, 16); q += __shfl_xor(q, 32);
;                 if (fq == 0) { if (FIRST) st_wt4(ss + (size_t)row * 32 + u.pn * 4 + wc, __float_as_uint(q)); else ss[(size_t)row * 32 + u.pn * 4 + wc] = q; }
	v_ashrrev_i32_e32 v97, 31, v96
	v_readlane_b32 s68, v234, 3
	v_add_u32_e32 v132, 0xffffe020, v144
	v_lshlrev_b64 v[102:103], 13, v[96:97]
	v_readlane_b32 s69, v234, 4
	v_readlane_b32 s70, v234, 5
	v_readlane_b32 s71, v234, 6
	v_lshlrev_b64 v[100:101], 13, v[132:133]
	v_lshl_add_u64 v[98:99], s[68:69], 0, v[102:103]
	v_lshl_add_u64 v[100:101], s[70:71], 0, v[100:101]
	v_cmp_gt_i32_e32 vcc, s54, v96
	v_lshlrev_b64 v[106:107], 12, v[96:97]
	v_lshl_add_u64 v[102:103], s[84:85], 0, v[102:103]
	v_cndmask_b32_e32 v99, v101, v99, vcc
	v_cndmask_b32_e32 v98, v100, v98, vcc
	v_lshl_add_u64 v[104:105], v[98:99], 0, v[142:143]
	v_mov_b32_e32 v98, v200
	v_mov_b32_e32 v99, v201
	v_mov_b32_e32 v100, v202
	v_mov_b32_e32 v101, v203
	v_lshl_add_u64 v[106:107], s[20:21], 0, v[106:107]
	v_lshl_add_u64 v[102:103], v[102:103], 0, v[142:143]
	v_lshl_add_u64 v[106:107], v[140:141], 1, v[106:107]
	v_lshl_add_u64 v[108:109], v[106:107], 0, 32
	v_readlane_b32 s72, v234, 7
	v_readlane_b32 s73, v234, 8
	v_readlane_b32 s74, v234, 9
	v_readlane_b32 s75, v234, 10
	v_readlane_b32 s76, v234, 11
	v_readlane_b32 s77, v234, 12
	v_readlane_b32 s78, v234, 13
	v_readlane_b32 s79, v234, 14
	v_readlane_b32 s80, v234, 15
	v_readlane_b32 s81, v234, 16
	v_readlane_b32 s82, v234, 17
	v_readlane_b32 s83, v234, 18
	v_pk_add_f32 v[94:95], v[94:95], v[100:101]
	v_pk_add_f32 v[92:93], v[92:93], v[98:99]
	global_store_dwordx4 v[102:103], v[92:95], off
	v_cvt_pk_bf16_f32 v98, v92, v93
	v_cvt_pk_bf16_f32 v99, v94, v95
	s_nop 0
	global_store_dwordx2 v[106:107], v[98:99], off sc1
	v_mov_b32_e32 v98, v204
	v_mov_b32_e32 v99, v205
	v_mov_b32_e32 v100, v206
	v_mov_b32_e32 v101, v207
	v_mul_f32_e32 v93, v93, v93
	v_mul_f32_e32 v95, v95, v95
	v_fmac_f32_e32 v93, v92, v92
	v_fmac_f32_e32 v95, v94, v94
	v_add_f32_e32 v92, v93, v95
	v_pk_add_f32 v[90:91], v[90:91], v[100:101]
	v_pk_add_f32 v[88:89], v[88:89], v[98:99]
	global_store_dwordx4 v[102:103], v[88:91], off offset:64
	v_cvt_pk_bf16_f32 v98, v88, v89
	v_cvt_pk_bf16_f32 v99, v90, v91
	s_nop 0
	global_store_dwordx2 v[108:109], v[98:99], off sc1
	v_mov_b32_e32 v98, v208
	v_mov_b32_e32 v99, v209
	v_mov_b32_e32 v100, v210
	v_mov_b32_e32 v101, v211
	v_lshl_add_u64 v[108:109], v[106:107], 0, s[28:29]
	v_mul_f32_e32 v89, v89, v89
	v_mul_f32_e32 v91, v91, v91
	v_fmac_f32_e32 v89, v88, v88
	v_fmac_f32_e32 v91, v90, v90
	v_add_f32_e32 v88, v89, v91
	v_add_f32_e32 v88, v92, v88
	v_pk_add_f32 v[86:87], v[86:87], v[100:101]
	v_pk_add_f32 v[84:85], v[84:85], v[98:99]
	global_store_dwordx4 v[102:103], v[84:87], off offset:512
	v_cvt_pk_bf16_f32 v98, v84, v85
	v_cvt_pk_bf16_f32 v99, v86, v87
	s_nop 0
	global_store_dwordx2 v[108:109], v[98:99], off sc1
	v_mov_b32_e32 v98, v212
	v_mov_b32_e32 v99, v213
	v_mov_b32_e32 v100, v214
	v_mov_b32_e32 v101, v215
	v_mul_f32_e32 v85, v85, v85
	v_mul_f32_e32 v87, v87, v87
	v_fmac_f32_e32 v85, v84, v84
	v_fmac_f32_e32 v87, v86, v86
	v_add_f32_e32 v84, v85, v87
	v_add_f32_e32 v84, v88, v84
	v_pk_add_f32 v[82:83], v[82:83], v[100:101]
	v_pk_add_f32 v[80:81], v[80:81], v[98:99]
	v_mul_f32_e32 v86, v83, v83
	v_mul_f32_e32 v85, v81, v81
	v_fmac_f32_e32 v85, v80, v80
	v_fmac_f32_e32 v86, v82, v82
	v_add_f32_e32 v85, v85, v86
	v_add_f32_e32 v86, v84, v85
	ds_bpermute_b32 v87, v116, v86
	global_store_dwordx4 v[102:103], v[80:83], off offset:576
	v_cvt_pk_bf16_f32 v84, v80, v81
	v_cvt_pk_bf16_f32 v85, v82, v83
	s_waitcnt lgkmcnt(0)
	s_nop 0
	v_add_f32_e32 v80, v86, v87
	ds_bpermute_b32 v81, v114, v80
	v_lshl_add_u64 v[82:83], v[106:107], 0, s[30:31]
	global_store_dwordx2 v[82:83], v[84:85], off sc1
	s_and_saveexec_b64 s[44:45], s[4:5]
	s_cbranch_execz .LBB0_305
	s_waitcnt lgkmcnt(0)
	v_add_f32_e32 v82, v80, v81
	v_lshlrev_b64 v[80:81], 7, v[96:97]
	v_lshl_add_u64 v[80:81], s[2:3], 0, v[80:81]
	v_lshl_add_u64 v[80:81], s[42:43], 2, v[80:81]
	s_lshl_b32 s10, s55, 2
	v_lshl_add_u64 v[80:81], v[80:81], 0, s[10:11]
	global_store_dword v[80:81], v82, off sc1
.LBB0_305:
	s_or_b64 exec, exec, s[44:45]
	v_or_b32_e32 v80, 48, v144
	s_waitcnt lgkmcnt(0)
	v_ashrrev_i32_e32 v81, 31, v80
	v_readlane_b32 s68, v234, 3
	v_add_u32_e32 v132, 0xffffe030, v144
	v_lshlrev_b64 v[86:87], 13, v[80:81]
	v_readlane_b32 s69, v234, 4
	v_readlane_b32 s70, v234, 5
	v_readlane_b32 s71, v234, 6
	v_lshlrev_b64 v[84:85], 13, v[132:133]
	v_lshl_add_u64 v[82:83], s[68:69], 0, v[86:87]
	v_lshl_add_u64 v[84:85], s[70:71], 0, v[84:85]
	v_cmp_gt_i32_e32 vcc, s54, v80
	v_lshlrev_b64 v[90:91], 12, v[80:81]
	v_lshl_add_u64 v[86:87], s[84:85], 0, v[86:87]
	v_cndmask_b32_e32 v83, v85, v83, vcc
	v_cndmask_b32_e32 v82, v84, v82, vcc
	v_lshl_add_u64 v[88:89], v[82:83], 0, v[142:143]
	v_mov_b32_e32 v82, v216
	v_mov_b32_e32 v83, v217
	v_mov_b32_e32 v84, v218
	v_mov_b32_e32 v85, v219
	v_lshl_add_u64 v[90:91], s[20:21], 0, v[90:91]
	v_lshl_add_u64 v[86:87], v[86:87], 0, v[142:143]
	v_lshl_add_u64 v[90:91], v[140:141], 1, v[90:91]
	v_lshl_add_u64 v[92:93], v[90:91], 0, 32
	v_readlane_b32 s72, v234, 7
	v_readlane_b32 s73, v234, 8
	v_readlane_b32 s74, v234, 9
	v_readlane_b32 s75, v234, 10
	v_readlane_b32 s76, v234, 11
	v_readlane_b32 s77, v234, 12
	v_readlane_b32 s78, v234, 13
	v_readlane_b32 s79, v234, 14
	v_readlane_b32 s80, v234, 15
	v_readlane_b32 s81, v234, 16
	v_readlane_b32 s82, v234, 17
	v_readlane_b32 s83, v234, 18
	v_pk_add_f32 v[78:79], v[78:79], v[84:85]
	v_pk_add_f32 v[76:77], v[76:77], v[82:83]
	global_store_dwordx4 v[86:87], v[76:79], off
	v_cvt_pk_bf16_f32 v82, v76, v77
	v_cvt_pk_bf16_f32 v83, v78, v79
	s_nop 0
	global_store_dwordx2 v[90:91], v[82:83], off sc1
	v_mov_b32_e32 v82, v220
	v_mov_b32_e32 v83, v221
	v_mov_b32_e32 v84, v222
	v_mov_b32_e32 v85, v223
; __device__ __forceinline__ unsigned cvt_pk_bf16(float lo, float hi) { unsigned r; asm volatile("v_cvt_pk_bf16_f32 %0, %1, %2" : "=v"(r) : "v"(lo), "v"(hi)); return r; }
; __device__ __forceinline__ void st_wt8(void* ptr, u32x2 v) { asm volatile("global_store_dwordx2 %0, %1, off sc1" :: "v"(ptr), "v"(v) : "memory"); }
; __device__ __forceinline__ void st_wt4(void* ptr, unsigned v) { asm volatile("global_store_dword %0, %1, off sc1" :: "v"(ptr), "v"(v) : "memory"); }
;     __device__ __forceinline__ void operator()(const f32x4 (&acc)[2][2][4][2], const pg8::Unit& u, int wr, int wc, int fr, int fq) const {
;     ...
;         for (int ai = 0; ai < 2; ++ai)
; #pragma unroll
;             for (int m = 0; m < 4; ++m) {
;                 const int row = row0 + ai * 128 + m * 16;
;                 float* orow = oy + (size_t)row * DM + col0;
;                 const float* xr = FIRST ? ((row < MP ? xp + (size_t)row * DM : xs + (size_t)(row - MP) * DM) + col0) : orow;
;                 float q = 0.f;
; #pragma unroll
;                 for (int bj = 0; bj < 2; ++bj)
; #pragma unroll
;                     for (int n = 0; n < 2; ++n) {
;                         const f32x4 xv = *(const f32x4*)(xr + bj * 128 + n * 16);
;                         const f32x4 o = xv + acc[ai][bj][m][n];
;                         *(f32x4*)(orow + bj * 128 + n * 16) = o;
;                         q += (o[0] * o[0] + o[1] * o[1]) + (o[2] * o[2] + o[3] * o[3]);
;                         if (FIRST) { u32x2 w; w.x = cvt_pk_bf16(o[0], o[1]); w.y = cvt_pk_bf16(o[2], o[3]); st_wt8(xb + (size_t)row * DM + col0 + bj * 128 + n * 16, w); }
;                     }
;                 q += __shfl_xor(q, 16); q += __shfl_xor(q, 32);
;                 if (fq == 0) { if (FIRST) st_wt4(ss + (size_t)row * 32 + u.pn * 4 + wc, __float_as_uint(q)); else ss[(size_t)row * 32 + u.pn * 4 + wc] = q; }
	v_mul_f32_e32 v77, v77, v77
	v_mul_f32_e32 v79, v79, v79
	v_fmac_f32_e32 v77, v76, v76
	v_fmac_f32_e32 v79, v78, v78
	v_add_f32_e32 v76, v77, v79
	v_pk_add_f32 v[74:75], v[74:75], v[84:85]
	v_pk_add_f32 v[72:73], v[72:73], v[82:83]
	global_store_dwordx4 v[86:87], v[72:75], off offset:64
	v_cvt_pk_bf16_f32 v82, v72, v73
	v_cvt_pk_bf16_f32 v83, v74, v75
	s_nop 0
	global_store_dwordx2 v[92:93], v[82:83], off sc1
	v_mov_b32_e32 v82, v224
	v_mov_b32_e32 v83, v225
	v_mov_b32_e32 v84, v226
	v_mov_b32_e32 v85, v227
	v_lshl_add_u64 v[92:93], v[90:91], 0, s[28:29]
	v_mul_f32_e32 v73, v73, v73
	v_mul_f32_e32 v75, v75, v75
	v_fmac_f32_e32 v73, v72, v72
	v_fmac_f32_e32 v75, v74, v74
	v_add_f32_e32 v72, v73, v75
	v_add_f32_e32 v72, v76, v72
	v_pk_add_f32 v[70:71], v[70:71], v[84:85]
	v_pk_add_f32 v[68:69], v[68:69], v[82:83]
	global_store_dwordx4 v[86:87], v[68:71], off offset:512
	v_cvt_pk_bf16_f32 v82, v68, v69
	v_cvt_pk_bf16_f32 v83, v70, v71
	s_nop 0
	global_store_dwordx2 v[92:93], v[82:83], off sc1
	v_mov_b32_e32 v82, v228
	v_mov_b32_e32 v83, v229
	v_mov_b32_e32 v84, v230
	v_mov_b32_e32 v85, v231
	v_mul_f32_e32 v69, v69, v69
	v_mul_f32_e32 v71, v71, v71
	v_fmac_f32_e32 v69, v68, v68
	v_fmac_f32_e32 v71, v70, v70
	v_add_f32_e32 v68, v69, v71
	v_add_f32_e32 v68, v72, v68
	v_pk_add_f32 v[66:67], v[66:67], v[84:85]
	v_pk_add_f32 v[64:65], v[64:65], v[82:83]
	v_mul_f32_e32 v70, v67, v67
	v_mul_f32_e32 v69, v65, v65
	v_fmac_f32_e32 v69, v64, v64
	v_fmac_f32_e32 v70, v66, v66
	v_add_f32_e32 v69, v69, v70
	v_add_f32_e32 v70, v68, v69
	ds_bpermute_b32 v71, v116, v70
	global_store_dwordx4 v[86:87], v[64:67], off offset:576
	v_cvt_pk_bf16_f32 v68, v64, v65
	v_cvt_pk_bf16_f32 v69, v66, v67
	s_waitcnt lgkmcnt(0)
	s_nop 0
	v_add_f32_e32 v64, v70, v71
	ds_bpermute_b32 v65, v114, v64
	v_lshl_add_u64 v[66:67], v[90:91], 0, s[30:31]
	global_store_dwordx2 v[66:67], v[68:69], off sc1
	s_and_saveexec_b64 s[44:45], s[4:5]
	s_cbranch_execz .LBB0_307
	s_waitcnt lgkmcnt(0)
	v_add_f32_e32 v66, v64, v65
	v_lshlrev_b64 v[64:65], 7, v[80:81]
	v_lshl_add_u64 v[64:65], s[2:3], 0, v[64:65]
	v_lshl_add_u64 v[64:65], s[42:43], 2, v[64:65]
	s_lshl_b32 s10, s55, 2
	v_lshl_add_u64 v[64:65], v[64:65], 0, s[10:11]
	global_store_dword v[64:65], v66, off sc1
.LBB0_307:
	s_or_b64 exec, exec, s[44:45]
	v_add_u32_e32 v64, 0x80, v144
	s_waitcnt lgkmcnt(0)
	v_ashrrev_i32_e32 v65, 31, v64
	v_readlane_b32 s68, v234, 3
	v_add_u32_e32 v132, 0xffffe080, v144
	v_lshlrev_b64 v[70:71], 13, v[64:65]
	v_readlane_b32 s69, v234, 4
	v_readlane_b32 s70, v234, 5
	v_readlane_b32 s71, v234, 6
	v_lshlrev_b64 v[68:69], 13, v[132:133]
	s_movk_i32 s9, 0x1f80
	v_lshl_add_u64 v[66:67], s[68:69], 0, v[70:71]
	v_lshl_add_u64 v[68:69], s[70:71], 0, v[68:69]
	v_cmp_gt_i32_e32 vcc, s9, v144
	v_lshlrev_b64 v[74:75], 12, v[64:65]
	v_lshl_add_u64 v[70:71], s[84:85], 0, v[70:71]
	v_cndmask_b32_e32 v67, v69, v67, vcc
	v_cndmask_b32_e32 v66, v68, v66, vcc
	v_lshl_add_u64 v[72:73], v[66:67], 0, v[142:143]
	s_mov_b64 s[98:99], 0x100000
	v_lshl_add_u64 v[192:193], v[232:233], 0, s[98:99]
	global_load_dwordx4 v[164:167], v[192:193], off
	global_load_dwordx4 v[168:171], v[192:193], off offset:64
	global_load_dwordx4 v[172:175], v[192:193], off offset:512
	global_load_dwordx4 v[176:179], v[192:193], off offset:576
	s_mov_b64 s[98:99], 0x120000
	v_lshl_add_u64 v[192:193], v[232:233], 0, s[98:99]
	global_load_dwordx4 v[180:183], v[192:193], off
	global_load_dwordx4 v[184:187], v[192:193], off offset:64
	global_load_dwordx4 v[188:191], v[192:193], off offset:512
	global_load_dwordx4 v[196:199], v[192:193], off offset:576
	s_mov_b64 s[98:99], 0x140000
	v_lshl_add_u64 v[192:193], v[232:233], 0, s[98:99]
	global_load_dwordx4 v[200:203], v[192:193], off
	global_load_dwordx4 v[204:207], v[192:193], off offset:64
	global_load_dwordx4 v[208:211], v[192:193], off offset:512
	global_load_dwordx4 v[212:215], v[192:193], off offset:576
	s_mov_b64 s[98:99], 0x160000
	v_lshl_add_u64 v[192:193], v[232:233], 0, s[98:99]
	global_load_dwordx4 v[216:219], v[192:193], off
	global_load_dwordx4 v[220:223], v[192:193], off offset:64
	global_load_dwordx4 v[224:227], v[192:193], off offset:512
	global_load_dwordx4 v[228:231], v[192:193], off offset:576
	s_waitcnt vmcnt(0)
	v_mov_b32_e32 v66, v164
	v_mov_b32_e32 v67, v165
	v_mov_b32_e32 v68, v166
	v_mov_b32_e32 v69, v167
	v_lshl_add_u64 v[74:75], s[20:21], 0, v[74:75]
	v_lshl_add_u64 v[70:71], v[70:71], 0, v[142:143]
	v_lshl_add_u64 v[74:75], v[140:141], 1, v[74:75]
	v_lshl_add_u64 v[76:77], v[74:75], 0, 32
	v_readlane_b32 s72, v234, 7
	v_readlane_b32 s73, v234, 8
	v_readlane_b32 s74, v234, 9
	v_readlane_b32 s75, v234, 10
	v_readlane_b32 s76, v234, 11
	v_readlane_b32 s77, v234, 12
	v_readlane_b32 s78, v234, 13
	v_readlane_b32 s79, v234, 14
	v_readlane_b32 s80, v234, 15
	v_readlane_b32 s81, v234, 16
	v_readlane_b32 s82, v234, 17
	v_readlane_b32 s83, v234, 18
	v_pk_add_f32 v[62:63], v[62:63], v[68:69]
	v_pk_add_f32 v[60:61], v[60:61], v[66:67]
	global_store_dwordx4 v[70:71], v[60:63], off
	v_cvt_pk_bf16_f32 v66, v60, v61
	v_cvt_pk_bf16_f32 v67, v62, v63
	s_nop 0
	global_store_dwordx2 v[74:75], v[66:67], off sc1
	v_mov_b32_e32 v66, v168
	v_mov_b32_e32 v67, v169
	v_mov_b32_e32 v68, v170
	v_mov_b32_e32 v69, v171
	v_mul_f32_e32 v61, v61, v61
	v_mul_f32_e32 v63, v63, v63
	v_fmac_f32_e32 v61, v60, v60
	v_fmac_f32_e32 v63, v62, v62
	v_add_f32_e32 v60, v61, v63
	v_pk_add_f32 v[58:59], v[58:59], v[68:69]
	v_pk_add_f32 v[56:57], v[56:57], v[66:67]
	global_store_dwordx4 v[70:71], v[56:59], off offset:64
	v_cvt_pk_bf16_f32 v66, v56, v57
	v_cvt_pk_bf16_f32 v67, v58, v59
	s_nop 0
	global_store_dwordx2 v[76:77], v[66:67], off sc1
	v_mov_b32_e32 v66, v172
	v_mov_b32_e32 v67, v173
	v_mov_b32_e32 v68, v174
	v_mov_b32_e32 v69, v175
	v_lshl_add_u64 v[76:77], v[74:75], 0, s[28:29]
	v_mul_f32_e32 v57, v57, v57
	v_mul_f32_e32 v59, v59, v59
	v_fmac_f32_e32 v57, v56, v56
	v_fmac_f32_e32 v59, v58, v58
	v_add_f32_e32 v56, v57, v59
	v_add_f32_e32 v56, v60, v56
	v_pk_add_f32 v[54:55], v[54:55], v[68:69]
	v_pk_add_f32 v[52:53], v[52:53], v[66:67]
	global_store_dwordx4 v[70:71], v[52:55], off offset:512
	v_cvt_pk_bf16_f32 v66, v52, v53
	v_cvt_pk_bf16_f32 v67, v54, v55
	s_nop 0
	global_store_dwordx2 v[76:77], v[66:67], off sc1
	v_mov_b32_e32 v66, v176
	v_mov_b32_e32 v67, v177
	v_mov_b32_e32 v68, v178
	v_mov_b32_e32 v69, v179
	v_mul_f32_e32 v53, v53, v53
	v_mul_f32_e32 v55, v55, v55
	v_fmac_f32_e32 v53, v52, v52
	v_fmac_f32_e32 v55, v54, v54
	v_add_f32_e32 v52, v53, v55
	v_add_f32_e32 v52, v56, v52
	v_pk_add_f32 v[50:51], v[50:51], v[68:69]
	v_pk_add_f32 v[48:49], v[48:49], v[66:67]
	v_mul_f32_e32 v54, v51, v51
	v_mul_f32_e32 v53, v49, v49
	v_fmac_f32_e32 v53, v48, v48
	v_fmac_f32_e32 v54, v50, v50
	v_add_f32_e32 v53, v53, v54
	v_add_f32_e32 v54, v52, v53
	ds_bpermute_b32 v55, v116, v54
	global_store_dwordx4 v[70:71], v[48:51], off offset:576
	v_cvt_pk_bf16_f32 v52, v48, v49
	v_cvt_pk_bf16_f32 v53, v50, v51
	s_waitcnt lgkmcnt(0)
; __device__ __forceinline__ unsigned cvt_pk_bf16(float lo, float hi) { unsigned r; asm volatile("v_cvt_pk_bf16_f32 %0, %1, %2" : "=v"(r) : "v"(lo), "v"(hi)); return r; }
; __device__ __forceinline__ void st_wt8(void* ptr, u32x2 v) { asm volatile("global_store_dwordx2 %0, %1, off sc1" :: "v"(ptr), "v"(v) : "memory"); }
; __device__ __forceinline__ void st_wt4(void* ptr, unsigned v) { asm volatile("global_store_dword %0, %1, off sc1" :: "v"(ptr), "v"(v) : "memory"); }
;     __device__ __forceinline__ void operator()(const f32x4 (&acc)[2][2][4][2], const pg8::Unit& u, int wr, int wc, int fr, int fq) const {
;     ...
;         for (int ai = 0; ai < 2; ++ai)
; #pragma unroll
;             for (int m = 0; m < 4; ++m) {
;                 const int row = row0 + ai * 128 + m * 16;
;                 float* orow = oy + (size_t)row * DM + col0;
;                 const float* xr = FIRST ? ((row < MP ? xp + (size_t)row * DM : xs + (size_t)(row - MP) * DM) + col0) : orow;
;                 float q = 0.f;
; #pragma unroll
;                 for (int bj = 0; bj < 2; ++bj)
; #pragma unroll
;                     for (int n = 0; n < 2; ++n) {
;                         const f32x4 xv = *(const f32x4*)(xr + bj * 128 + n * 16);
;                         const f32x4 o = xv + acc[ai][bj][m][n];
;                         *(f32x4*)(orow + bj * 128 + n * 16) = o;
;                         q += (o[0] * o[0] + o[1] * o[1]) + (o[2] * o[2] + o[3] * o[3]);
;                         if (FIRST) { u32x2 w; w.x = cvt_pk_bf16(o[0], o[1]); w.y = cvt_pk_bf16(o[2], o[3]); st_wt8(xb + (size_t)row * DM + col0 + bj * 128 + n * 16, w); }
;                     }
;                 q += __shfl_xor(q, 16); q += __shfl_xor(q, 32);
;                 if (fq == 0) { if (FIRST) st_wt4(ss + (size_t)row * 32 + u.pn * 4 + wc, __float_as_uint(q)); else ss[(size_t)row * 32 + u.pn * 4 + wc] = q; }
	s_nop 0
	v_add_f32_e32 v48, v54, v55
	ds_bpermute_b32 v49, v114, v48
	v_lshl_add_u64 v[50:51], v[74:75], 0, s[30:31]
	global_store_dwordx2 v[50:51], v[52:53], off sc1
	s_and_saveexec_b64 s[44:45], s[4:5]
	s_cbranch_execz .LBB0_309
	s_waitcnt lgkmcnt(0)
	v_add_f32_e32 v50, v48, v49
	v_lshlrev_b64 v[48:49], 7, v[64:65]
	v_lshl_add_u64 v[48:49], s[2:3], 0, v[48:49]
	v_lshl_add_u64 v[48:49], s[42:43], 2, v[48:49]
	s_lshl_b32 s10, s55, 2
	v_lshl_add_u64 v[48:49], v[48:49], 0, s[10:11]
	global_store_dword v[48:49], v50, off sc1
.LBB0_309:
	s_or_b64 exec, exec, s[44:45]
	v_add_u32_e32 v48, 0x90, v144
	s_waitcnt lgkmcnt(0)
	v_ashrrev_i32_e32 v49, 31, v48
	v_readlane_b32 s68, v234, 3
	v_add_u32_e32 v132, 0xffffe090, v144
	v_lshlrev_b64 v[54:55], 13, v[48:49]
	v_readlane_b32 s69, v234, 4
	v_readlane_b32 s70, v234, 5
	v_readlane_b32 s71, v234, 6
	v_lshlrev_b64 v[52:53], 13, v[132:133]
	s_movk_i32 s9, 0x1f70
	v_lshl_add_u64 v[50:51], s[68:69], 0, v[54:55]
	v_lshl_add_u64 v[52:53], s[70:71], 0, v[52:53]
	v_cmp_gt_i32_e32 vcc, s9, v144
	v_lshlrev_b64 v[58:59], 12, v[48:49]
	v_lshl_add_u64 v[54:55], s[84:85], 0, v[54:55]
	v_cndmask_b32_e32 v51, v53, v51, vcc
	v_cndmask_b32_e32 v50, v52, v50, vcc
	v_lshl_add_u64 v[56:57], v[50:51], 0, v[142:143]
	v_mov_b32_e32 v50, v180
	v_mov_b32_e32 v51, v181
	v_mov_b32_e32 v52, v182
	v_mov_b32_e32 v53, v183
	v_lshl_add_u64 v[58:59], s[20:21], 0, v[58:59]
	v_lshl_add_u64 v[54:55], v[54:55], 0, v[142:143]
	v_lshl_add_u64 v[58:59], v[140:141], 1, v[58:59]
	v_lshl_add_u64 v[60:61], v[58:59], 0, 32
	v_readlane_b32 s72, v234, 7
	v_readlane_b32 s73, v234, 8
	v_readlane_b32 s74, v234, 9
	v_readlane_b32 s75, v234, 10
	v_readlane_b32 s76, v234, 11
	v_readlane_b32 s77, v234, 12
	v_readlane_b32 s78, v234, 13
	v_readlane_b32 s79, v234, 14
	v_readlane_b32 s80, v234, 15
	v_readlane_b32 s81, v234, 16
	v_readlane_b32 s82, v234, 17
	v_readlane_b32 s83, v234, 18
	v_pk_add_f32 v[46:47], v[46:47], v[52:53]
	v_pk_add_f32 v[44:45], v[44:45], v[50:51]
	global_store_dwordx4 v[54:55], v[44:47], off
	v_cvt_pk_bf16_f32 v50, v44, v45
	v_cvt_pk_bf16_f32 v51, v46, v47
	s_nop 0
	global_store_dwordx2 v[58:59], v[50:51], off sc1
	v_mov_b32_e32 v50, v184
	v_mov_b32_e32 v51, v185
	v_mov_b32_e32 v52, v186
	v_mov_b32_e32 v53, v187
	v_mul_f32_e32 v45, v45, v45
	v_mul_f32_e32 v47, v47, v47
	v_fmac_f32_e32 v45, v44, v44
	v_fmac_f32_e32 v47, v46, v46
	v_add_f32_e32 v44, v45, v47
	v_pk_add_f32 v[42:43], v[42:43], v[52:53]
	v_pk_add_f32 v[40:41], v[40:41], v[50:51]
	global_store_dwordx4 v[54:55], v[40:43], off offset:64
	v_cvt_pk_bf16_f32 v50, v40, v41
	v_cvt_pk_bf16_f32 v51, v42, v43
	s_nop 0
	global_store_dwordx2 v[60:61], v[50:51], off sc1
	v_mov_b32_e32 v50, v188
	v_mov_b32_e32 v51, v189
	v_mov_b32_e32 v52, v190
	v_mov_b32_e32 v53, v191
	v_lshl_add_u64 v[60:61], v[58:59], 0, s[28:29]
	v_mul_f32_e32 v41, v41, v41
	v_mul_f32_e32 v43, v43, v43
	v_fmac_f32_e32 v41, v40, v40
	v_fmac_f32_e32 v43, v42, v42
	v_add_f32_e32 v40, v41, v43
	v_add_f32_e32 v40, v44, v40
	v_pk_add_f32 v[38:39], v[38:39], v[52:53]
	v_pk_add_f32 v[36:37], v[36:37], v[50:51]
	global_store_dwordx4 v[54:55], v[36:39], off offset:512
	v_cvt_pk_bf16_f32 v50, v36, v37
	v_cvt_pk_bf16_f32 v51, v38, v39
	s_nop 0
	global_store_dwordx2 v[60:61], v[50:51], off sc1
	v_mov_b32_e32 v50, v196
	v_mov_b32_e32 v51, v197
	v_mov_b32_e32 v52, v198
	v_mov_b32_e32 v53, v199
	v_mul_f32_e32 v37, v37, v37
	v_mul_f32_e32 v39, v39, v39
	v_fmac_f32_e32 v37, v36, v36
	v_fmac_f32_e32 v39, v38, v38
	v_add_f32_e32 v36, v37, v39
	v_add_f32_e32 v36, v40, v36
	v_pk_add_f32 v[34:35], v[34:35], v[52:53]
	v_pk_add_f32 v[32:33], v[32:33], v[50:51]
	v_mul_f32_e32 v38, v35, v35
	v_mul_f32_e32 v37, v33, v33
	v_fmac_f32_e32 v37, v32, v32
	v_fmac_f32_e32 v38, v34, v34
	v_add_f32_e32 v37, v37, v38
	v_add_f32_e32 v38, v36, v37
	ds_bpermute_b32 v39, v116, v38
	global_store_dwordx4 v[54:55], v[32:35], off offset:576
	v_cvt_pk_bf16_f32 v36, v32, v33
	v_cvt_pk_bf16_f32 v37, v34, v35
	s_waitcnt lgkmcnt(0)
	s_nop 0
	v_add_f32_e32 v32, v38, v39
	ds_bpermute_b32 v33, v114, v32
	v_lshl_add_u64 v[34:35], v[58:59], 0, s[30:31]
	global_store_dwordx2 v[34:35], v[36:37], off sc1
	s_and_saveexec_b64 s[44:45], s[4:5]
	s_cbranch_execz .LBB0_311
	s_waitcnt lgkmcnt(0)
	v_add_f32_e32 v34, v32, v33
	v_lshlrev_b64 v[32:33], 7, v[48:49]
	v_lshl_add_u64 v[32:33], s[2:3], 0, v[32:33]
	v_lshl_add_u64 v[32:33], s[42:43], 2, v[32:33]
	s_lshl_b32 s10, s55, 2
	v_lshl_add_u64 v[32:33], v[32:33], 0, s[10:11]
	global_store_dword v[32:33], v34, off sc1
; __device__ __forceinline__ unsigned cvt_pk_bf16(float lo, float hi) { unsigned r; asm volatile("v_cvt_pk_bf16_f32 %0, %1, %2" : "=v"(r) : "v"(lo), "v"(hi)); return r; }
; __device__ __forceinline__ void st_wt8(void* ptr, u32x2 v) { asm volatile("global_store_dwordx2 %0, %1, off sc1" :: "v"(ptr), "v"(v) : "memory"); }
; __device__ __forceinline__ void st_wt4(void* ptr, unsigned v) { asm volatile("global_store_dword %0, %1, off sc1" :: "v"(ptr), "v"(v) : "memory"); }
;     __device__ __forceinline__ void operator()(const f32x4 (&acc)[2][2][4][2], const pg8::Unit& u, int wr, int wc, int fr, int fq) const {
;     ...
;         for (int ai = 0; ai < 2; ++ai)
; #pragma unroll
;             for (int m = 0; m < 4; ++m) {
;                 const int row = row0 + ai * 128 + m * 16;
;                 float* orow = oy + (size_t)row * DM + col0;
;                 const float* xr = FIRST ? ((row < MP ? xp + (size_t)row * DM : xs + (size_t)(row - MP) * DM) + col0) : orow;
;                 float q = 0.f;
; #pragma unroll
;                 for (int bj = 0; bj < 2; ++bj)
; #pragma unroll
;                     for (int n = 0; n < 2; ++n) {
;                         const f32x4 xv = *(const f32x4*)(xr + bj * 128 + n * 16);
;                         const f32x4 o = xv + acc[ai][bj][m][n];
;                         *(f32x4*)(orow + bj * 128 + n * 16) = o;
;                         q += (o[0] * o[0] + o[1] * o[1]) + (o[2] * o[2] + o[3] * o[3]);
;                         if (FIRST) { u32x2 w; w.x = cvt_pk_bf16(o[0], o[1]); w.y = cvt_pk_bf16(o[2], o[3]); st_wt8(xb + (size_t)row * DM + col0 + bj * 128 + n * 16, w); }
;                     }
;                 q += __shfl_xor(q, 16); q += __shfl_xor(q, 32);
;                 if (fq == 0) { if (FIRST) st_wt4(ss + (size_t)row * 32 + u.pn * 4 + wc, __float_as_uint(q)); else ss[(size_t)row * 32 + u.pn * 4 + wc] = q; }
.LBB0_311:
	s_or_b64 exec, exec, s[44:45]
	v_add_u32_e32 v32, 0xa0, v144
	s_waitcnt lgkmcnt(0)
	v_ashrrev_i32_e32 v33, 31, v32
	v_readlane_b32 s68, v234, 3
	v_add_u32_e32 v132, 0xffffe0a0, v144
	v_lshlrev_b64 v[38:39], 13, v[32:33]
	v_readlane_b32 s69, v234, 4
	v_readlane_b32 s70, v234, 5
	v_readlane_b32 s71, v234, 6
	v_lshlrev_b64 v[36:37], 13, v[132:133]
	s_movk_i32 s9, 0x1f60
	v_lshl_add_u64 v[34:35], s[68:69], 0, v[38:39]
	v_lshl_add_u64 v[36:37], s[70:71], 0, v[36:37]
	v_cmp_gt_i32_e32 vcc, s9, v144
	v_lshlrev_b64 v[42:43], 12, v[32:33]
	v_lshl_add_u64 v[38:39], s[84:85], 0, v[38:39]
	v_cndmask_b32_e32 v35, v37, v35, vcc
	v_cndmask_b32_e32 v34, v36, v34, vcc
	v_lshl_add_u64 v[40:41], v[34:35], 0, v[142:143]
	v_mov_b32_e32 v34, v200
	v_mov_b32_e32 v35, v201
	v_mov_b32_e32 v36, v202
	v_mov_b32_e32 v37, v203
	v_lshl_add_u64 v[42:43], s[20:21], 0, v[42:43]
	v_lshl_add_u64 v[38:39], v[38:39], 0, v[142:143]
	v_lshl_add_u64 v[42:43], v[140:141], 1, v[42:43]
	v_lshl_add_u64 v[44:45], v[42:43], 0, 32
	v_readlane_b32 s72, v234, 7
	v_readlane_b32 s73, v234, 8
	v_readlane_b32 s74, v234, 9
	v_readlane_b32 s75, v234, 10
	v_readlane_b32 s76, v234, 11
	v_readlane_b32 s77, v234, 12
	v_readlane_b32 s78, v234, 13
	v_readlane_b32 s79, v234, 14
	v_readlane_b32 s80, v234, 15
	v_readlane_b32 s81, v234, 16
	v_readlane_b32 s82, v234, 17
	v_readlane_b32 s83, v234, 18
	v_pk_add_f32 v[30:31], v[30:31], v[36:37]
	v_pk_add_f32 v[28:29], v[28:29], v[34:35]
	global_store_dwordx4 v[38:39], v[28:31], off
	v_cvt_pk_bf16_f32 v34, v28, v29
	v_cvt_pk_bf16_f32 v35, v30, v31
	s_nop 0
	global_store_dwordx2 v[42:43], v[34:35], off sc1
	v_mov_b32_e32 v34, v204
	v_mov_b32_e32 v35, v205
	v_mov_b32_e32 v36, v206
	v_mov_b32_e32 v37, v207
	v_mul_f32_e32 v29, v29, v29
	v_mul_f32_e32 v31, v31, v31
	v_fmac_f32_e32 v29, v28, v28
	v_fmac_f32_e32 v31, v30, v30
	v_add_f32_e32 v28, v29, v31
	v_pk_add_f32 v[26:27], v[26:27], v[36:37]
	v_pk_add_f32 v[24:25], v[24:25], v[34:35]
	global_store_dwordx4 v[38:39], v[24:27], off offset:64
	v_cvt_pk_bf16_f32 v34, v24, v25
	v_cvt_pk_bf16_f32 v35, v26, v27
	s_nop 0
	global_store_dwordx2 v[44:45], v[34:35], off sc1
	v_mov_b32_e32 v34, v208
	v_mov_b32_e32 v35, v209
	v_mov_b32_e32 v36, v210
	v_mov_b32_e32 v37, v211
	v_lshl_add_u64 v[44:45], v[42:43], 0, s[28:29]
	v_mul_f32_e32 v25, v25, v25
	v_mul_f32_e32 v27, v27, v27
	v_fmac_f32_e32 v25, v24, v24
	v_fmac_f32_e32 v27, v26, v26
	v_add_f32_e32 v24, v25, v27
	v_add_f32_e32 v24, v28, v24
	v_pk_add_f32 v[22:23], v[22:23], v[36:37]
	v_pk_add_f32 v[20:21], v[20:21], v[34:35]
	global_store_dwordx4 v[38:39], v[20:23], off offset:512
	v_cvt_pk_bf16_f32 v34, v20, v21
	v_cvt_pk_bf16_f32 v35, v22, v23
	s_nop 0
	global_store_dwordx2 v[44:45], v[34:35], off sc1
	v_mov_b32_e32 v34, v212
	v_mov_b32_e32 v35, v213
	v_mov_b32_e32 v36, v214
	v_mov_b32_e32 v37, v215
	v_mul_f32_e32 v21, v21, v21
	v_mul_f32_e32 v23, v23, v23
	v_fmac_f32_e32 v21, v20, v20
	v_fmac_f32_e32 v23, v22, v22
	v_add_f32_e32 v20, v21, v23
	v_add_f32_e32 v20, v24, v20
	v_pk_add_f32 v[18:19], v[18:19], v[36:37]
	v_pk_add_f32 v[16:17], v[16:17], v[34:35]
	v_mul_f32_e32 v22, v19, v19
	v_mul_f32_e32 v21, v17, v17
	v_fmac_f32_e32 v21, v16, v16
	v_fmac_f32_e32 v22, v18, v18
	v_add_f32_e32 v21, v21, v22
	v_add_f32_e32 v22, v20, v21
	ds_bpermute_b32 v23, v116, v22
	global_store_dwordx4 v[38:39], v[16:19], off offset:576
	v_cvt_pk_bf16_f32 v20, v16, v17
	v_cvt_pk_bf16_f32 v21, v18, v19
	s_waitcnt lgkmcnt(0)
	s_nop 0
	v_add_f32_e32 v16, v22, v23
	ds_bpermute_b32 v17, v114, v16
	v_lshl_add_u64 v[18:19], v[42:43], 0, s[30:31]
	global_store_dwordx2 v[18:19], v[20:21], off sc1
	s_and_saveexec_b64 s[44:45], s[4:5]
	s_cbranch_execz .LBB0_313
	s_waitcnt lgkmcnt(0)
	v_add_f32_e32 v18, v16, v17
	v_lshlrev_b64 v[16:17], 7, v[32:33]
	v_lshl_add_u64 v[16:17], s[2:3], 0, v[16:17]
	v_lshl_add_u64 v[16:17], s[42:43], 2, v[16:17]
	s_lshl_b32 s10, s55, 2
	v_lshl_add_u64 v[16:17], v[16:17], 0, s[10:11]
	global_store_dword v[16:17], v18, off sc1
; __device__ __forceinline__ unsigned cvt_pk_bf16(float lo, float hi) { unsigned r; asm volatile("v_cvt_pk_bf16_f32 %0, %1, %2" : "=v"(r) : "v"(lo), "v"(hi)); return r; }
; __device__ __forceinline__ void st_wt8(void* ptr, u32x2 v) { asm volatile("global_store_dwordx2 %0, %1, off sc1" :: "v"(ptr), "v"(v) : "memory"); }
; __device__ __forceinline__ void st_wt4(void* ptr, unsigned v) { asm volatile("global_store_dword %0, %1, off sc1" :: "v"(ptr), "v"(v) : "memory"); }
;     __device__ __forceinline__ void operator()(const f32x4 (&acc)[2][2][4][2], const pg8::Unit& u, int wr, int wc, int fr, int fq) const {
;     ...
;         for (int ai = 0; ai < 2; ++ai)
; #pragma unroll
;             for (int m = 0; m < 4; ++m) {
;                 const int row = row0 + ai * 128 + m * 16;
;                 float* orow = oy + (size_t)row * DM + col0;
;                 const float* xr = FIRST ? ((row < MP ? xp + (size_t)row * DM : xs + (size_t)(row - MP) * DM) + col0) : orow;
;                 float q = 0.f;
; #pragma unroll
;                 for (int bj = 0; bj < 2; ++bj)
; #pragma unroll
;                     for (int n = 0; n < 2; ++n) {
;                         const f32x4 xv = *(const f32x4*)(xr + bj * 128 + n * 16);
;                         const f32x4 o = xv + acc[ai][bj][m][n];
;                         *(f32x4*)(orow + bj * 128 + n * 16) = o;
;                         q += (o[0] * o[0] + o[1] * o[1]) + (o[2] * o[2] + o[3] * o[3]);
;                         if (FIRST) { u32x2 w; w.x = cvt_pk_bf16(o[0], o[1]); w.y = cvt_pk_bf16(o[2], o[3]); st_wt8(xb + (size_t)row * DM + col0 + bj * 128 + n * 16, w); }
;                     }
;                 q += __shfl_xor(q, 16); q += __shfl_xor(q, 32);
;                 if (fq == 0) { if (FIRST) st_wt4(ss + (size_t)row * 32 + u.pn * 4 + wc, __float_as_uint(q)); else ss[(size_t)row * 32 + u.pn * 4 + wc] = q; }
.LBB0_313:
	s_or_b64 exec, exec, s[44:45]
	v_add_u32_e32 v16, 0xb0, v144
	s_waitcnt lgkmcnt(0)
	v_ashrrev_i32_e32 v17, 31, v16
	v_readlane_b32 s68, v234, 3
	v_add_u32_e32 v132, 0xffffe0b0, v144
	v_lshlrev_b64 v[22:23], 13, v[16:17]
	v_readlane_b32 s69, v234, 4
	v_readlane_b32 s70, v234, 5
	v_readlane_b32 s71, v234, 6
	v_lshlrev_b64 v[20:21], 13, v[132:133]
	s_movk_i32 s9, 0x1f50
	v_lshl_add_u64 v[18:19], s[68:69], 0, v[22:23]
	v_lshl_add_u64 v[20:21], s[70:71], 0, v[20:21]
	v_cmp_gt_i32_e32 vcc, s9, v144
	v_lshlrev_b64 v[26:27], 12, v[16:17]
	v_lshl_add_u64 v[22:23], s[84:85], 0, v[22:23]
	v_cndmask_b32_e32 v19, v21, v19, vcc
	v_cndmask_b32_e32 v18, v20, v18, vcc
	v_lshl_add_u64 v[24:25], v[18:19], 0, v[142:143]
	v_mov_b32_e32 v18, v216
	v_mov_b32_e32 v19, v217
	v_mov_b32_e32 v20, v218
	v_mov_b32_e32 v21, v219
	v_lshl_add_u64 v[26:27], s[20:21], 0, v[26:27]
	v_lshl_add_u64 v[22:23], v[22:23], 0, v[142:143]
	v_lshl_add_u64 v[26:27], v[140:141], 1, v[26:27]
	v_lshl_add_u64 v[28:29], v[26:27], 0, 32
	v_readlane_b32 s72, v234, 7
	v_readlane_b32 s73, v234, 8
	v_readlane_b32 s74, v234, 9
	v_readlane_b32 s75, v234, 10
	v_readlane_b32 s76, v234, 11
	v_readlane_b32 s77, v234, 12
	v_readlane_b32 s78, v234, 13
	v_readlane_b32 s79, v234, 14
	v_readlane_b32 s80, v234, 15
	v_readlane_b32 s81, v234, 16
	v_readlane_b32 s82, v234, 17
	v_readlane_b32 s83, v234, 18
	v_pk_add_f32 v[14:15], v[14:15], v[20:21]
	v_pk_add_f32 v[12:13], v[12:13], v[18:19]
	global_store_dwordx4 v[22:23], v[12:15], off
	v_cvt_pk_bf16_f32 v18, v12, v13
	v_cvt_pk_bf16_f32 v19, v14, v15
	s_nop 0
	global_store_dwordx2 v[26:27], v[18:19], off sc1
	v_mov_b32_e32 v18, v220
	v_mov_b32_e32 v19, v221
	v_mov_b32_e32 v20, v222
	v_mov_b32_e32 v21, v223
	v_mul_f32_e32 v13, v13, v13
	v_mul_f32_e32 v15, v15, v15
	v_fmac_f32_e32 v13, v12, v12
	v_fmac_f32_e32 v15, v14, v14
	v_add_f32_e32 v12, v13, v15
	v_pk_add_f32 v[10:11], v[10:11], v[20:21]
	v_pk_add_f32 v[8:9], v[8:9], v[18:19]
	global_store_dwordx4 v[22:23], v[8:11], off offset:64
	v_cvt_pk_bf16_f32 v18, v8, v9
	v_cvt_pk_bf16_f32 v19, v10, v11
	s_nop 0
	global_store_dwordx2 v[28:29], v[18:19], off sc1
	v_mov_b32_e32 v18, v224
	v_mov_b32_e32 v19, v225
	v_mov_b32_e32 v20, v226
	v_mov_b32_e32 v21, v227
	v_lshl_add_u64 v[28:29], v[26:27], 0, s[28:29]
	v_mul_f32_e32 v9, v9, v9
	v_mul_f32_e32 v11, v11, v11
	v_fmac_f32_e32 v9, v8, v8
	v_fmac_f32_e32 v11, v10, v10
	v_add_f32_e32 v8, v9, v11
	v_add_f32_e32 v8, v12, v8
	v_pk_add_f32 v[6:7], v[6:7], v[20:21]
	v_pk_add_f32 v[4:5], v[4:5], v[18:19]
	global_store_dwordx4 v[22:23], v[4:7], off offset:512
	v_cvt_pk_bf16_f32 v18, v4, v5
	v_cvt_pk_bf16_f32 v19, v6, v7
	s_nop 0
	global_store_dwordx2 v[28:29], v[18:19], off sc1
	v_mov_b32_e32 v18, v228
	v_mov_b32_e32 v19, v229
	v_mov_b32_e32 v20, v230
	v_mov_b32_e32 v21, v231
	v_mul_f32_e32 v5, v5, v5
	v_mul_f32_e32 v7, v7, v7
	v_fmac_f32_e32 v5, v4, v4
	v_fmac_f32_e32 v7, v6, v6
	v_add_f32_e32 v4, v5, v7
	v_add_f32_e32 v4, v8, v4
	v_pk_add_f32 v[2:3], v[2:3], v[20:21]
	v_pk_add_f32 v[0:1], v[0:1], v[18:19]
	v_mul_f32_e32 v6, v3, v3
	v_mul_f32_e32 v5, v1, v1
	v_fmac_f32_e32 v5, v0, v0
	v_fmac_f32_e32 v6, v2, v2
	v_add_f32_e32 v5, v5, v6
	v_add_f32_e32 v6, v4, v5
	ds_bpermute_b32 v7, v116, v6
	global_store_dwordx4 v[22:23], v[0:3], off offset:576
	v_cvt_pk_bf16_f32 v4, v0, v1
	v_cvt_pk_bf16_f32 v5, v2, v3
	s_waitcnt lgkmcnt(0)
	s_nop 0
	v_add_f32_e32 v0, v6, v7
	ds_bpermute_b32 v1, v114, v0
	v_lshl_add_u64 v[2:3], v[26:27], 0, s[30:31]
	global_store_dwordx2 v[2:3], v[4:5], off sc1
	s_and_saveexec_b64 s[44:45], s[4:5]
	s_cbranch_execnz .LBB0_316
	s_or_b64 exec, exec, s[44:45]
	s_andn2_b64 vcc, exec, s[36:37]
	s_mov_b64 s[36:37], -1
	s_cbranch_vccz .LBB0_317

;     __device__ __forceinline__ void operator()(const f32x4 (&acc)[2][2][4][2], const pg8::Unit& u, int wr, int wc, int fr, int fq) const {
;         const int t = u.pn >> 3;
;         bf16_t* base = rb + (size_t)t * SZ_D;
;         const int row0 = u.pm * 256 + wr * 64 + fr, col0 = (u.pn & 7) * 256 + wc * 32 + 8 * fq;
; #pragma unroll
;         for (int ai = 0; ai < 2; ++ai)
; #pragma unroll
;             for (int m = 0; m < 4; ++m) {
;                 const int row = row0 + ai * 128 + m * 16;
;                 const f32x4 pa = *(const f32x4*)(ss1 + (size_t)row * 32 + 8 * fq), pb = *(const f32x4*)(ss1 + (size_t)row * 32 + 8 * fq + 4);
;                 float s = ((pa[0] + pa[1]) + (pa[2] + pa[3])) + ((pb[0] + pb[1]) + (pb[2] + pb[3]));
;                 s += __shfl_xor(s, 16); s += __shfl_xor(s, 32);
;                 float rinv = __builtin_amdgcn_rsqf(s * (1.0f / DM) + 1e-6f);
;                 if (t == 0) rinv *= 0.08838834764831845f * 1.4426950408889634f;
;                 bf16_t* rowp = base + (size_t)row * DM + col0;
;                 float* fo = nullptr;
;                 if (t == 1) fo = out + (row < MP ? O_KP + (size_t)row * DM : O_KS + (size_t)(row - MP) * DM) + col0;
.LBB0_431:
	v_lshl_add_u32 v150, s92, 8, v162
	v_ashrrev_i32_e32 v151, 31, v150
	v_lshlrev_b64 v[128:129], 7, v[150:151]
	v_lshl_add_u64 v[132:133], v[146:147], 0, v[128:129]
	global_load_dwordx4 v[178:181], v[132:133], off offset:2048
	global_load_dwordx4 v[182:185], v[132:133], off offset:2064
	s_mov_b64 s[6:7], 0x1000
	v_lshl_add_u64 v[248:249], v[132:133], 0, s[6:7]
	global_load_dwordx4 v[186:189], v[248:249], off
	global_load_dwordx4 v[190:193], v[248:249], off offset:16
	global_load_dwordx4 v[196:199], v[248:249], off offset:2048
	global_load_dwordx4 v[200:203], v[248:249], off offset:2064
	s_mov_b64 s[6:7], 0x4000
	v_lshl_add_u64 v[248:249], v[132:133], 0, s[6:7]
	global_load_dwordx4 v[204:207], v[248:249], off
	global_load_dwordx4 v[208:211], v[248:249], off offset:16
	global_load_dwordx4 v[212:215], v[248:249], off offset:2048
	global_load_dwordx4 v[216:219], v[248:249], off offset:2064
	s_mov_b64 s[6:7], 0x5000
	v_lshl_add_u64 v[250:251], v[132:133], 0, s[6:7]
	global_load_dwordx4 v[220:223], v[250:251], off
	global_load_dwordx4 v[224:227], v[250:251], off offset:16
	global_load_dwordx4 v[228:231], v[250:251], off offset:2048
	global_load_dwordx4 v[240:243], v[250:251], off offset:2064
	global_load_dwordx4 v[128:131], v[132:133], off
	s_nop 0
	global_load_dwordx4 v[132:135], v[132:133], off offset:16
	v_and_b32_e32 v152, 64, v195
	v_xor_b32_e32 v144, 16, v195
	v_add_u32_e32 v152, 64, v152
	v_cmp_lt_i32_e32 vcc, v144, v152
	v_xor_b32_e32 v153, 32, v195
	s_lshl_b32 s2, s30, 8
	v_cndmask_b32_e32 v144, v195, v144, vcc
	v_lshlrev_b32_e32 v168, 2, v144
	v_cmp_lt_i32_e32 vcc, v153, v152
	s_ashr_i32 s8, s30, 3
	s_and_b32 s2, s2, 0x700
	s_cmp_eq_u32 s8, 1
	v_or_b32_e32 v167, s2, v164
	s_cselect_b64 s[2:3], -1, 0
	s_cmp_lg_u32 s8, 1
	v_lshlrev_b64 v[156:157], 11, v[150:151]
	v_mov_b64_e32 v[154:155], 0
	s_waitcnt vmcnt(0)
	v_add_f32_e32 v128, v128, v129
	v_add_f32_e32 v129, v130, v131
	v_add_f32_e32 v130, v132, v133
	v_add_f32_e32 v131, v134, v135
	v_add_f32_e32 v128, v128, v129
	v_add_f32_e32 v129, v130, v131
	v_add_f32_e32 v128, v128, v129
	ds_bpermute_b32 v129, v168, v128
	v_cndmask_b32_e32 v130, v195, v153, vcc
	v_lshlrev_b32_e32 v169, 2, v130
	v_cmp_lt_i32_e32 vcc, s83, v150
	s_waitcnt lgkmcnt(0)
	v_add_f32_e32 v130, v128, v129
	ds_bpermute_b32 v131, v169, v130
	s_cbranch_scc1 .LBB0_437
	s_and_saveexec_b64 s[6:7], vcc
	s_xor_b64 s[6:7], exec, s[6:7]
	v_add_u32_e32 v144, 0xffffe000, v150
	v_lshlrev_b64 v[128:129], 11, v[144:145]
	v_lshl_add_u64 v[128:129], v[128:129], 0, s[50:51]
	s_andn2_saveexec_b64 s[6:7], s[6:7]
	v_lshl_add_u64 v[128:129], v[156:157], 0, s[52:53]
	s_or_b64 exec, exec, s[6:7]
	v_lshl_add_u64 v[128:129], v[128:129], 2, s[84:85]
	v_lshlrev_b32_e32 v144, 2, v167
	v_lshl_add_u64 v[154:155], v[128:129], 0, v[144:145]

;     __device__ __forceinline__ void operator()(const f32x4 (&acc)[2][2][4][2], const pg8::Unit& u, int wr, int wc, int fr, int fq) const {
;     ...
;             for (int m = 0; m < 4; ++m) {
;                 const int row = row0 + ai * 128 + m * 16;
;                 const f32x4 pa = *(const f32x4*)(ss1 + (size_t)row * 32 + 8 * fq), pb = *(const f32x4*)(ss1 + (size_t)row * 32 + 8 * fq + 4);
;                 float s = ((pa[0] + pa[1]) + (pa[2] + pa[3])) + ((pb[0] + pb[1]) + (pb[2] + pb[3]));
;                 s += __shfl_xor(s, 16); s += __shfl_xor(s, 32);
;                 float rinv = __builtin_amdgcn_rsqf(s * (1.0f / DM) + 1e-6f);
;                 if (t == 0) rinv *= 0.08838834764831845f * 1.4426950408889634f;
;                 bf16_t* rowp = base + (size_t)row * DM + col0;
;                 float* fo = nullptr;
;                 if (t == 1) fo = out + (row < MP ? O_KP + (size_t)row * DM : O_KS + (size_t)(row - MP) * DM) + col0;
;                 if (t == 2) fo = out + (row < MP ? O_VP + (size_t)row * DM : O_VS + (size_t)(row - MP) * DM) + col0;
.LBB0_451:
	s_nop 0
	v_cvt_pk_bf16_f32 v128, v128, v129
	v_cvt_pk_bf16_f32 v129, v130, v131
	v_cvt_pk_bf16_f32 v130, v132, v133
	v_cvt_pk_bf16_f32 v131, v134, v135
	s_nop 0
	v_lshl_add_u64 v[132:133], v[156:157], 0, s[48:49]
	global_store_dwordx4 v[132:133], v[128:131], off sc1
	s_nop 1
	v_or_b32_e32 v128, 16, v150
	v_ashrrev_i32_e32 v129, 31, v128
	v_lshlrev_b64 v[130:131], 7, v[128:129]
	v_lshl_add_u64 v[134:135], v[146:147], 0, v[130:131]
	v_mov_b32_e32 v130, v178
	v_mov_b32_e32 v131, v179
	v_mov_b32_e32 v132, v180
	v_mov_b32_e32 v133, v181
	v_mov_b32_e32 v154, v182
	v_mov_b32_e32 v155, v183
	v_mov_b32_e32 v156, v184
	v_mov_b32_e32 v157, v185
	s_andn2_b64 vcc, exec, s[2:3]
	v_cmp_lt_i32_e64 s[14:15], s83, v128
	v_add_f32_e32 v130, v130, v131
	v_add_f32_e32 v131, v132, v133
	v_add_f32_e32 v132, v154, v155
	v_add_f32_e32 v133, v156, v157
	v_add_f32_e32 v130, v130, v131
	v_add_f32_e32 v131, v132, v133
	v_add_f32_e32 v130, v130, v131
	ds_bpermute_b32 v131, v168, v130
	v_lshlrev_b64 v[156:157], 11, v[128:129]
	v_cndmask_b32_e64 v129, 0, 1, s[2:3]
	v_mov_b64_e32 v[154:155], 0
	v_cmp_ne_u32_e64 s[12:13], 1, v129
	s_waitcnt lgkmcnt(0)
	v_add_f32_e32 v132, v130, v131
	ds_bpermute_b32 v133, v169, v132
	s_cbranch_vccnz .LBB0_457
	s_and_saveexec_b64 s[2:3], s[14:15]
	s_xor_b64 s[2:3], exec, s[2:3]
	v_add_u32_e32 v144, 0xffffe010, v150
	v_lshlrev_b64 v[130:131], 11, v[144:145]
	v_lshl_add_u64 v[130:131], v[130:131], 0, s[50:51]
	s_andn2_saveexec_b64 s[2:3], s[2:3]
	v_lshl_add_u64 v[130:131], v[156:157], 0, s[52:53]
	s_or_b64 exec, exec, s[2:3]
	v_lshl_add_u64 v[130:131], v[130:131], 2, s[84:85]
	v_lshlrev_b32_e32 v144, 2, v167
	v_lshl_add_u64 v[154:155], v[130:131], 0, v[144:145]

;     __device__ __forceinline__ void operator()(const f32x4 (&acc)[2][2][4][2], const pg8::Unit& u, int wr, int wc, int fr, int fq) const {
;     ...
;             for (int m = 0; m < 4; ++m) {
;                 const int row = row0 + ai * 128 + m * 16;
;                 const f32x4 pa = *(const f32x4*)(ss1 + (size_t)row * 32 + 8 * fq), pb = *(const f32x4*)(ss1 + (size_t)row * 32 + 8 * fq + 4);
;                 float s = ((pa[0] + pa[1]) + (pa[2] + pa[3])) + ((pb[0] + pb[1]) + (pb[2] + pb[3]));
;                 s += __shfl_xor(s, 16); s += __shfl_xor(s, 32);
;                 float rinv = __builtin_amdgcn_rsqf(s * (1.0f / DM) + 1e-6f);
;                 if (t == 0) rinv *= 0.08838834764831845f * 1.4426950408889634f;
;                 bf16_t* rowp = base + (size_t)row * DM + col0;
;                 float* fo = nullptr;
;                 if (t == 1) fo = out + (row < MP ? O_KP + (size_t)row * DM : O_KS + (size_t)(row - MP) * DM) + col0;
;                 if (t == 2) fo = out + (row < MP ? O_VP + (size_t)row * DM : O_VS + (size_t)(row - MP) * DM) + col0;
.LBB0_471:
	s_nop 0
	v_cvt_pk_bf16_f32 v128, v128, v129
	v_cvt_pk_bf16_f32 v129, v130, v131
	v_cvt_pk_bf16_f32 v130, v132, v133
	v_cvt_pk_bf16_f32 v131, v134, v135
	s_nop 0
	v_lshl_add_u64 v[132:133], v[156:157], 0, s[48:49]
	global_store_dwordx4 v[132:133], v[128:131], off sc1
	s_nop 1
	v_or_b32_e32 v128, 32, v150
	v_ashrrev_i32_e32 v129, 31, v128
	v_lshlrev_b64 v[130:131], 7, v[128:129]
	v_lshl_add_u64 v[134:135], v[146:147], 0, v[130:131]
	v_mov_b32_e32 v130, v186
	v_mov_b32_e32 v131, v187
	v_mov_b32_e32 v132, v188
	v_mov_b32_e32 v133, v189
	v_mov_b32_e32 v154, v190
	v_mov_b32_e32 v155, v191
	v_mov_b32_e32 v156, v192
	v_mov_b32_e32 v157, v193
	s_and_b64 vcc, exec, s[12:13]
	v_cmp_lt_i32_e64 s[16:17], s83, v128
	v_add_f32_e32 v130, v130, v131
	v_add_f32_e32 v131, v132, v133
	v_add_f32_e32 v132, v154, v155
	v_add_f32_e32 v133, v156, v157
	v_add_f32_e32 v130, v130, v131
	v_add_f32_e32 v131, v132, v133
	v_add_f32_e32 v130, v130, v131
	ds_bpermute_b32 v131, v168, v130
	v_lshlrev_b64 v[156:157], 11, v[128:129]
	v_mov_b64_e32 v[154:155], 0
	s_waitcnt lgkmcnt(0)
	v_add_f32_e32 v132, v130, v131
	ds_bpermute_b32 v133, v169, v132
	s_cbranch_vccnz .LBB0_477
	s_and_saveexec_b64 s[2:3], s[16:17]
	s_xor_b64 s[2:3], exec, s[2:3]
	v_add_u32_e32 v144, 0xffffe020, v150
	v_lshlrev_b64 v[130:131], 11, v[144:145]
	v_lshl_add_u64 v[130:131], v[130:131], 0, s[50:51]
	s_andn2_saveexec_b64 s[2:3], s[2:3]
	v_lshl_add_u64 v[130:131], v[156:157], 0, s[52:53]
	s_or_b64 exec, exec, s[2:3]
	v_lshl_add_u64 v[130:131], v[130:131], 2, s[84:85]
	v_lshlrev_b32_e32 v144, 2, v167
	v_lshl_add_u64 v[154:155], v[130:131], 0, v[144:145]

;     __device__ __forceinline__ void operator()(const f32x4 (&acc)[2][2][4][2], const pg8::Unit& u, int wr, int wc, int fr, int fq) const {
;     ...
;             for (int m = 0; m < 4; ++m) {
;                 const int row = row0 + ai * 128 + m * 16;
;                 const f32x4 pa = *(const f32x4*)(ss1 + (size_t)row * 32 + 8 * fq), pb = *(const f32x4*)(ss1 + (size_t)row * 32 + 8 * fq + 4);
;                 float s = ((pa[0] + pa[1]) + (pa[2] + pa[3])) + ((pb[0] + pb[1]) + (pb[2] + pb[3]));
;                 s += __shfl_xor(s, 16); s += __shfl_xor(s, 32);
;                 float rinv = __builtin_amdgcn_rsqf(s * (1.0f / DM) + 1e-6f);
;                 if (t == 0) rinv *= 0.08838834764831845f * 1.4426950408889634f;
;                 bf16_t* rowp = base + (size_t)row * DM + col0;
;                 float* fo = nullptr;
;                 if (t == 1) fo = out + (row < MP ? O_KP + (size_t)row * DM : O_KS + (size_t)(row - MP) * DM) + col0;
;                 if (t == 2) fo = out + (row < MP ? O_VP + (size_t)row * DM : O_VS + (size_t)(row - MP) * DM) + col0;
.LBB0_491:
	s_nop 0
	v_cvt_pk_bf16_f32 v128, v128, v129
	v_cvt_pk_bf16_f32 v129, v130, v131
	v_cvt_pk_bf16_f32 v130, v132, v133
	v_cvt_pk_bf16_f32 v131, v134, v135
	s_nop 0
	v_lshl_add_u64 v[132:133], v[156:157], 0, s[48:49]
	global_store_dwordx4 v[132:133], v[128:131], off sc1
	s_nop 1
	v_or_b32_e32 v128, 48, v150
	v_ashrrev_i32_e32 v129, 31, v128
	v_lshlrev_b64 v[130:131], 7, v[128:129]
	v_lshl_add_u64 v[134:135], v[146:147], 0, v[130:131]
	v_mov_b32_e32 v130, v196
	v_mov_b32_e32 v131, v197
	v_mov_b32_e32 v132, v198
	v_mov_b32_e32 v133, v199
	v_mov_b32_e32 v154, v200
	v_mov_b32_e32 v155, v201
	v_mov_b32_e32 v156, v202
	v_mov_b32_e32 v157, v203
	s_and_b64 vcc, exec, s[12:13]
	v_cmp_lt_i32_e64 s[16:17], s83, v128
	v_add_f32_e32 v130, v130, v131
	v_add_f32_e32 v131, v132, v133
	v_add_f32_e32 v132, v154, v155
	v_add_f32_e32 v133, v156, v157
	v_add_f32_e32 v130, v130, v131
	v_add_f32_e32 v131, v132, v133
	v_add_f32_e32 v130, v130, v131
	ds_bpermute_b32 v131, v168, v130
	v_lshlrev_b64 v[156:157], 11, v[128:129]
	v_mov_b64_e32 v[154:155], 0
	s_waitcnt lgkmcnt(0)
	v_add_f32_e32 v132, v130, v131
	ds_bpermute_b32 v133, v169, v132
	s_cbranch_vccnz .LBB0_497
	s_and_saveexec_b64 s[2:3], s[16:17]
	s_xor_b64 s[2:3], exec, s[2:3]
	v_add_u32_e32 v144, 0xffffe030, v150
	v_lshlrev_b64 v[130:131], 11, v[144:145]
	v_lshl_add_u64 v[130:131], v[130:131], 0, s[50:51]
	s_andn2_saveexec_b64 s[2:3], s[2:3]
	v_lshl_add_u64 v[130:131], v[156:157], 0, s[52:53]
	s_or_b64 exec, exec, s[2:3]
	v_lshl_add_u64 v[130:131], v[130:131], 2, s[84:85]
	v_lshlrev_b32_e32 v144, 2, v167
	v_lshl_add_u64 v[154:155], v[130:131], 0, v[144:145]

;     __device__ __forceinline__ void operator()(const f32x4 (&acc)[2][2][4][2], const pg8::Unit& u, int wr, int wc, int fr, int fq) const {
;     ...
;             for (int m = 0; m < 4; ++m) {
;                 const int row = row0 + ai * 128 + m * 16;
;                 const f32x4 pa = *(const f32x4*)(ss1 + (size_t)row * 32 + 8 * fq), pb = *(const f32x4*)(ss1 + (size_t)row * 32 + 8 * fq + 4);
;                 float s = ((pa[0] + pa[1]) + (pa[2] + pa[3])) + ((pb[0] + pb[1]) + (pb[2] + pb[3]));
;                 s += __shfl_xor(s, 16); s += __shfl_xor(s, 32);
;                 float rinv = __builtin_amdgcn_rsqf(s * (1.0f / DM) + 1e-6f);
;                 if (t == 0) rinv *= 0.08838834764831845f * 1.4426950408889634f;
;                 bf16_t* rowp = base + (size_t)row * DM + col0;
;                 float* fo = nullptr;
;                 if (t == 1) fo = out + (row < MP ? O_KP + (size_t)row * DM : O_KS + (size_t)(row - MP) * DM) + col0;
;                 if (t == 2) fo = out + (row < MP ? O_VP + (size_t)row * DM : O_VS + (size_t)(row - MP) * DM) + col0;
.LBB0_511:
	v_add_u32_e32 v154, 0x80, v150
	v_cvt_pk_bf16_f32 v128, v128, v129
	v_cvt_pk_bf16_f32 v129, v130, v131
	v_ashrrev_i32_e32 v155, 31, v154
	v_cvt_pk_bf16_f32 v130, v132, v133
	v_cvt_pk_bf16_f32 v131, v134, v135
	v_lshl_add_u64 v[132:133], v[156:157], 0, s[48:49]
	global_store_dwordx4 v[132:133], v[128:131], off sc1
	s_nop 1
	v_lshlrev_b64 v[128:129], 7, v[154:155]
	v_lshl_add_u64 v[132:133], v[146:147], 0, v[128:129]
	v_mov_b32_e32 v128, v204
	v_mov_b32_e32 v129, v205
	v_mov_b32_e32 v130, v206
	v_mov_b32_e32 v131, v207
	s_nop 0
	v_mov_b32_e32 v132, v208
	v_mov_b32_e32 v133, v209
	v_mov_b32_e32 v134, v210
	v_mov_b32_e32 v135, v211
	v_lshlrev_b64 v[156:157], 11, v[154:155]
	v_mov_b64_e32 v[154:155], 0
	s_and_b64 vcc, exec, s[12:13]
	v_cmp_lt_i32_e64 s[16:17], s88, v150
	v_add_f32_e32 v128, v128, v129
	v_add_f32_e32 v129, v130, v131
	v_add_f32_e32 v130, v132, v133
	v_add_f32_e32 v131, v134, v135
	v_add_f32_e32 v128, v128, v129
	v_add_f32_e32 v129, v130, v131
	v_add_f32_e32 v128, v128, v129
	ds_bpermute_b32 v129, v168, v128
	s_waitcnt lgkmcnt(0)
	v_add_f32_e32 v130, v128, v129
	ds_bpermute_b32 v131, v169, v130
	s_cbranch_vccnz .LBB0_517
	s_and_saveexec_b64 s[2:3], s[16:17]
	s_xor_b64 s[2:3], exec, s[2:3]
	v_add_u32_e32 v144, 0xffffe080, v150
	v_lshlrev_b64 v[128:129], 11, v[144:145]
	v_lshl_add_u64 v[128:129], v[128:129], 0, s[50:51]
	s_andn2_saveexec_b64 s[2:3], s[2:3]
	v_lshl_add_u64 v[128:129], v[156:157], 0, s[52:53]
	s_or_b64 exec, exec, s[2:3]
	v_lshl_add_u64 v[128:129], v[128:129], 2, s[84:85]
	v_lshlrev_b32_e32 v144, 2, v167
	v_lshl_add_u64 v[154:155], v[128:129], 0, v[144:145]

;     __device__ __forceinline__ void operator()(const f32x4 (&acc)[2][2][4][2], const pg8::Unit& u, int wr, int wc, int fr, int fq) const {
;     ...
;             for (int m = 0; m < 4; ++m) {
;                 const int row = row0 + ai * 128 + m * 16;
;                 const f32x4 pa = *(const f32x4*)(ss1 + (size_t)row * 32 + 8 * fq), pb = *(const f32x4*)(ss1 + (size_t)row * 32 + 8 * fq + 4);
;                 float s = ((pa[0] + pa[1]) + (pa[2] + pa[3])) + ((pb[0] + pb[1]) + (pb[2] + pb[3]));
;                 s += __shfl_xor(s, 16); s += __shfl_xor(s, 32);
;                 float rinv = __builtin_amdgcn_rsqf(s * (1.0f / DM) + 1e-6f);
;                 if (t == 0) rinv *= 0.08838834764831845f * 1.4426950408889634f;
;                 bf16_t* rowp = base + (size_t)row * DM + col0;
;                 float* fo = nullptr;
;                 if (t == 1) fo = out + (row < MP ? O_KP + (size_t)row * DM : O_KS + (size_t)(row - MP) * DM) + col0;
;                 if (t == 2) fo = out + (row < MP ? O_VP + (size_t)row * DM : O_VS + (size_t)(row - MP) * DM) + col0;
.LBB0_531:
	v_add_u32_e32 v154, 0x90, v150
	v_cvt_pk_bf16_f32 v128, v128, v129
	v_cvt_pk_bf16_f32 v129, v130, v131
	v_ashrrev_i32_e32 v155, 31, v154
	v_cvt_pk_bf16_f32 v130, v132, v133
	v_cvt_pk_bf16_f32 v131, v134, v135
	v_lshl_add_u64 v[132:133], v[156:157], 0, s[48:49]
	global_store_dwordx4 v[132:133], v[128:131], off sc1
	s_nop 1
	v_lshlrev_b64 v[128:129], 7, v[154:155]
	v_lshl_add_u64 v[132:133], v[146:147], 0, v[128:129]
	v_mov_b32_e32 v128, v212
	v_mov_b32_e32 v129, v213
	v_mov_b32_e32 v130, v214
	v_mov_b32_e32 v131, v215
	s_nop 0
	v_mov_b32_e32 v132, v216
	v_mov_b32_e32 v133, v217
	v_mov_b32_e32 v134, v218
	v_mov_b32_e32 v135, v219
	v_lshlrev_b64 v[156:157], 11, v[154:155]
	v_mov_b64_e32 v[154:155], 0
	s_and_b64 vcc, exec, s[12:13]
	v_cmp_lt_i32_e64 s[16:17], s89, v150
	v_add_f32_e32 v128, v128, v129
	v_add_f32_e32 v129, v130, v131
	v_add_f32_e32 v130, v132, v133
	v_add_f32_e32 v131, v134, v135
	v_add_f32_e32 v128, v128, v129
	v_add_f32_e32 v129, v130, v131
	v_add_f32_e32 v128, v128, v129
	ds_bpermute_b32 v129, v168, v128
	s_waitcnt lgkmcnt(0)
	v_add_f32_e32 v130, v128, v129
	ds_bpermute_b32 v131, v169, v130
	s_cbranch_vccnz .LBB0_537
	s_and_saveexec_b64 s[2:3], s[16:17]
	s_xor_b64 s[2:3], exec, s[2:3]
	v_add_u32_e32 v144, 0xffffe090, v150
	v_lshlrev_b64 v[128:129], 11, v[144:145]
	v_lshl_add_u64 v[128:129], v[128:129], 0, s[50:51]
	s_andn2_saveexec_b64 s[2:3], s[2:3]
	v_lshl_add_u64 v[128:129], v[156:157], 0, s[52:53]
	s_or_b64 exec, exec, s[2:3]
	v_lshl_add_u64 v[128:129], v[128:129], 2, s[84:85]
	v_lshlrev_b32_e32 v144, 2, v167
	v_lshl_add_u64 v[154:155], v[128:129], 0, v[144:145]

;     __device__ __forceinline__ void operator()(const f32x4 (&acc)[2][2][4][2], const pg8::Unit& u, int wr, int wc, int fr, int fq) const {
;     ...
;             for (int m = 0; m < 4; ++m) {
;                 const int row = row0 + ai * 128 + m * 16;
;                 const f32x4 pa = *(const f32x4*)(ss1 + (size_t)row * 32 + 8 * fq), pb = *(const f32x4*)(ss1 + (size_t)row * 32 + 8 * fq + 4);
;                 float s = ((pa[0] + pa[1]) + (pa[2] + pa[3])) + ((pb[0] + pb[1]) + (pb[2] + pb[3]));
;                 s += __shfl_xor(s, 16); s += __shfl_xor(s, 32);
;                 float rinv = __builtin_amdgcn_rsqf(s * (1.0f / DM) + 1e-6f);
;                 if (t == 0) rinv *= 0.08838834764831845f * 1.4426950408889634f;
;                 bf16_t* rowp = base + (size_t)row * DM + col0;
;                 float* fo = nullptr;
;                 if (t == 1) fo = out + (row < MP ? O_KP + (size_t)row * DM : O_KS + (size_t)(row - MP) * DM) + col0;
;                 if (t == 2) fo = out + (row < MP ? O_VP + (size_t)row * DM : O_VS + (size_t)(row - MP) * DM) + col0;
.LBB0_551:
	v_add_u32_e32 v154, 0xa0, v150
	v_cvt_pk_bf16_f32 v128, v128, v129
	v_cvt_pk_bf16_f32 v129, v130, v131
	v_ashrrev_i32_e32 v155, 31, v154
	v_cvt_pk_bf16_f32 v130, v132, v133
	v_cvt_pk_bf16_f32 v131, v134, v135
	v_lshl_add_u64 v[132:133], v[156:157], 0, s[48:49]
	global_store_dwordx4 v[132:133], v[128:131], off sc1
	s_nop 1
	v_lshlrev_b64 v[128:129], 7, v[154:155]
	v_lshl_add_u64 v[132:133], v[146:147], 0, v[128:129]
	v_mov_b32_e32 v128, v220
	v_mov_b32_e32 v129, v221
	v_mov_b32_e32 v130, v222
	v_mov_b32_e32 v131, v223
	s_nop 0
	v_mov_b32_e32 v132, v224
	v_mov_b32_e32 v133, v225
	v_mov_b32_e32 v134, v226
	v_mov_b32_e32 v135, v227
	v_lshlrev_b64 v[156:157], 11, v[154:155]
	v_mov_b64_e32 v[154:155], 0
	s_and_b64 vcc, exec, s[12:13]
	v_cmp_lt_i32_e64 s[16:17], s90, v150
	v_add_f32_e32 v128, v128, v129
	v_add_f32_e32 v129, v130, v131
	v_add_f32_e32 v130, v132, v133
	v_add_f32_e32 v131, v134, v135
	v_add_f32_e32 v128, v128, v129
	v_add_f32_e32 v129, v130, v131
	v_add_f32_e32 v128, v128, v129
	ds_bpermute_b32 v129, v168, v128
	s_waitcnt lgkmcnt(0)
	v_add_f32_e32 v130, v128, v129
	ds_bpermute_b32 v131, v169, v130
	s_cbranch_vccnz .LBB0_557
	s_and_saveexec_b64 s[2:3], s[16:17]
	s_xor_b64 s[2:3], exec, s[2:3]
	v_add_u32_e32 v144, 0xffffe0a0, v150
	v_lshlrev_b64 v[128:129], 11, v[144:145]
	v_lshl_add_u64 v[128:129], v[128:129], 0, s[50:51]
	s_andn2_saveexec_b64 s[2:3], s[2:3]
	v_lshl_add_u64 v[128:129], v[156:157], 0, s[52:53]
	s_or_b64 exec, exec, s[2:3]
	v_lshl_add_u64 v[128:129], v[128:129], 2, s[84:85]
	v_lshlrev_b32_e32 v144, 2, v167
	v_lshl_add_u64 v[154:155], v[128:129], 0, v[144:145]

;     __device__ __forceinline__ void operator()(const f32x4 (&acc)[2][2][4][2], const pg8::Unit& u, int wr, int wc, int fr, int fq) const {
;     ...
;             for (int m = 0; m < 4; ++m) {
;                 const int row = row0 + ai * 128 + m * 16;
;                 const f32x4 pa = *(const f32x4*)(ss1 + (size_t)row * 32 + 8 * fq), pb = *(const f32x4*)(ss1 + (size_t)row * 32 + 8 * fq + 4);
;                 float s = ((pa[0] + pa[1]) + (pa[2] + pa[3])) + ((pb[0] + pb[1]) + (pb[2] + pb[3]));
;                 s += __shfl_xor(s, 16); s += __shfl_xor(s, 32);
;                 float rinv = __builtin_amdgcn_rsqf(s * (1.0f / DM) + 1e-6f);
;                 if (t == 0) rinv *= 0.08838834764831845f * 1.4426950408889634f;
;                 bf16_t* rowp = base + (size_t)row * DM + col0;
;                 float* fo = nullptr;
;                 if (t == 1) fo = out + (row < MP ? O_KP + (size_t)row * DM : O_KS + (size_t)(row - MP) * DM) + col0;
;                 if (t == 2) fo = out + (row < MP ? O_VP + (size_t)row * DM : O_VS + (size_t)(row - MP) * DM) + col0;
.LBB0_571:
	v_add_u32_e32 v154, 0xb0, v150
	v_cvt_pk_bf16_f32 v128, v128, v129
	v_cvt_pk_bf16_f32 v129, v130, v131
	v_ashrrev_i32_e32 v155, 31, v154
	v_cvt_pk_bf16_f32 v130, v132, v133
	v_cvt_pk_bf16_f32 v131, v134, v135
	v_lshl_add_u64 v[132:133], v[156:157], 0, s[48:49]
	global_store_dwordx4 v[132:133], v[128:131], off sc1
	s_nop 1
	v_lshlrev_b64 v[128:129], 7, v[154:155]
	v_lshl_add_u64 v[132:133], v[146:147], 0, v[128:129]
	v_mov_b32_e32 v128, v228
	v_mov_b32_e32 v129, v229
	v_mov_b32_e32 v130, v230
	v_mov_b32_e32 v131, v231
	s_nop 0
	v_mov_b32_e32 v132, v240
	v_mov_b32_e32 v133, v241
	v_mov_b32_e32 v134, v242
	v_mov_b32_e32 v135, v243
	v_lshlrev_b64 v[156:157], 11, v[154:155]
	v_mov_b64_e32 v[154:155], 0
	s_and_b64 vcc, exec, s[12:13]
	v_cmp_lt_i32_e64 s[12:13], s91, v150
	v_add_f32_e32 v128, v128, v129
	v_add_f32_e32 v129, v130, v131
	v_add_f32_e32 v130, v132, v133
	v_add_f32_e32 v131, v134, v135
	v_add_f32_e32 v128, v128, v129
	v_add_f32_e32 v129, v130, v131
	v_add_f32_e32 v128, v128, v129
	ds_bpermute_b32 v129, v168, v128
	s_waitcnt lgkmcnt(0)
	v_add_f32_e32 v130, v128, v129
	ds_bpermute_b32 v131, v169, v130
	s_cbranch_vccnz .LBB0_577
	s_and_saveexec_b64 s[2:3], s[12:13]
	s_xor_b64 s[2:3], exec, s[2:3]
	v_add_u32_e32 v144, 0xffffe0b0, v150
	v_lshlrev_b64 v[128:129], 11, v[144:145]
	v_lshl_add_u64 v[128:129], v[128:129], 0, s[50:51]
	s_andn2_saveexec_b64 s[2:3], s[2:3]
	v_lshl_add_u64 v[128:129], v[156:157], 0, s[52:53]
	s_or_b64 exec, exec, s[2:3]
	v_lshl_add_u64 v[128:129], v[128:129], 2, s[84:85]
	v_lshlrev_b32_e32 v144, 2, v167
	v_lshl_add_u64 v[154:155], v[128:129], 0, v[144:145]

; __global__ void __launch_bounds__(512, 2) fwd_megakernel(Params p) {
	.amdhsa_kernel _Z14fwd_megakernel6Params
		.amdhsa_group_segment_fixed_size 0
		.amdhsa_private_segment_fixed_size 0
		.amdhsa_kernarg_size 384
		.amdhsa_user_sgpr_count 2
		.amdhsa_user_sgpr_dispatch_ptr 0
		.amdhsa_user_sgpr_queue_ptr 0
		.amdhsa_user_sgpr_kernarg_segment_ptr 1
		.amdhsa_user_sgpr_dispatch_id 0
		.amdhsa_user_sgpr_kernarg_preload_length 0
		.amdhsa_user_sgpr_kernarg_preload_offset 0
		.amdhsa_user_sgpr_private_segment_size 0
		.amdhsa_uses_dynamic_stack 0
		.amdhsa_enable_private_segment 0
		.amdhsa_system_sgpr_workgroup_id_x 1
		.amdhsa_system_sgpr_workgroup_id_y 0
		.amdhsa_system_sgpr_workgroup_id_z 0
		.amdhsa_system_sgpr_workgroup_info 0
		.amdhsa_system_vgpr_workitem_id 2
		.amdhsa_next_free_vgpr 252
		.amdhsa_next_free_sgpr 100
		.amdhsa_accum_offset 252
		.amdhsa_reserve_vcc 1
		.amdhsa_float_round_mode_32 0
		.amdhsa_float_round_mode_16_64 0
		.amdhsa_float_denorm_mode_32 3
		.amdhsa_float_denorm_mode_16_64 3
		.amdhsa_dx10_clamp 1
		.amdhsa_ieee_mode 1
		.amdhsa_fp16_overflow 0
		.amdhsa_tg_split 0
		.amdhsa_exception_fp_ieee_invalid_op 0
		.amdhsa_exception_fp_denorm_src 0
		.amdhsa_exception_fp_ieee_div_zero 0
		.amdhsa_exception_fp_ieee_overflow 0
		.amdhsa_exception_fp_ieee_underflow 0
		.amdhsa_exception_fp_ieee_inexact 0
		.amdhsa_exception_int_div_zero 0
	.end_amdhsa_kernel

; __global__ void __launch_bounds__(512, 2) fwd_megakernel(Params p) {
amdhsa.kernels:
  - .agpr_count:     0
    .args:
      - .offset:         0
        .size:           128
        .value_kind:     by_value
      - .offset:         128
        .size:           4
        .value_kind:     hidden_block_count_x
      - .offset:         132
        .size:           4
        .value_kind:     hidden_block_count_y
      - .offset:         136
        .size:           4
        .value_kind:     hidden_block_count_z
      - .offset:         140
        .size:           2
        .value_kind:     hidden_group_size_x
      - .offset:         142
        .size:           2
        .value_kind:     hidden_group_size_y
      - .offset:         144
        .size:           2
        .value_kind:     hidden_group_size_z
      - .offset:         146
        .size:           2
        .value_kind:     hidden_remainder_x
      - .offset:         148
        .size:           2
        .value_kind:     hidden_remainder_y
      - .offset:         150
        .size:           2
        .value_kind:     hidden_remainder_z
      - .offset:         168
        .size:           8
        .value_kind:     hidden_global_offset_x
      - .offset:         176
        .size:           8
        .value_kind:     hidden_global_offset_y
      - .offset:         184
        .size:           8
        .value_kind:     hidden_global_offset_z
      - .offset:         192
        .size:           2
        .value_kind:     hidden_grid_dims
      - .offset:         216
        .size:           8
        .value_kind:     hidden_multigrid_sync_arg
      - .offset:         248
        .size:           4
        .value_kind:     hidden_dynamic_lds_size
    .group_segment_fixed_size: 0
    .kernarg_segment_align: 8
    .kernarg_segment_size: 384
    .language:       OpenCL C
    .language_version:
      - 2
      - 0
    .max_flat_workgroup_size: 512
    .name:           _Z14fwd_megakernel6Params
    .private_segment_fixed_size: 0
    .sgpr_count:     106
    .sgpr_spill_count: 61
    .symbol:         _Z14fwd_megakernel6Params.kd
    .uniform_work_group_size: 1
    .uses_dynamic_stack: false
    .vgpr_count:     252
    .vgpr_spill_count: 0
    .wavefront_size: 64
